# plus: MMA segment setprio and first-iteration branch moved in front of the opening barrier
# baseline (speedup 1.0000x reference)
.LBB0_120:
	ds_read_b128 v[128:131], v178
	ds_read_b128 v[132:135], v178 offset:1024
	ds_read_b128 v[154:157], v178 offset:2048
	ds_read_b128 v[158:161], v178 offset:3072
	ds_read_b128 v[162:165], v179
	ds_read_b128 v[166:169], v179 offset:1024
	ds_read_b128 v[182:185], v179 offset:2048
	ds_read_b128 v[186:189], v179 offset:3072
	s_add_u32 s67, s88, 0xfffc0080
	s_addc_u32 s68, s89, -1
	s_cmp_eq_u32 s66, 12
	s_cselect_b32 s93, s52, s68
	s_cselect_b32 s92, s53, s67
	s_cselect_b32 s91, s56, s59
	s_cselect_b32 s90, s57, s58
	v_lshl_add_u64 v[170:171], s[88:89], 0, v[144:145]
	s_add_i32 m0, s17, 0xc000
	ds_read_b128 v[190:193], v180
	ds_read_b128 v[194:197], v180 offset:1024
	ds_read_b128 v[198:201], v180 offset:2048
	ds_read_b128 v[202:205], v180 offset:3072
	ds_read_b128 v[206:209], v180 offset:4096
	ds_read_b128 v[210:213], v180 offset:5120
	ds_read_b128 v[214:217], v180 offset:6144
	ds_read_b128 v[218:221], v180 offset:7168
	global_load_lds_dwordx4 v[170:171], off
	s_add_i32 m0, s17, 0xe000
	v_lshl_add_u64 v[170:171], s[88:89], 0, v[148:149]
	global_load_lds_dwordx4 v[170:171], off
	s_cmp_eq_u32 s66, -2
	s_waitcnt vmcnt(8) lgkmcnt(0)
	s_setprio 1
	s_cbranch_scc1 .Lzv_0_0
	s_barrier
	v_mfma_f32_16x16x32_bf16 v[124:127], v[128:131], v[190:193], v[124:127]
	v_mfma_f32_16x16x32_bf16 v[124:127], v[132:135], v[194:197], v[124:127]
	v_mfma_f32_16x16x32_bf16 v[116:119], v[154:157], v[190:193], v[116:119]
	v_mfma_f32_16x16x32_bf16 v[116:119], v[158:161], v[194:197], v[116:119]
	v_mfma_f32_16x16x32_bf16 v[108:111], v[128:131], v[198:201], v[108:111]
	v_mfma_f32_16x16x32_bf16 v[108:111], v[132:135], v[202:205], v[108:111]
	v_mfma_f32_16x16x32_bf16 v[100:103], v[154:157], v[198:201], v[100:103]
	v_mfma_f32_16x16x32_bf16 v[100:103], v[158:161], v[202:205], v[100:103]
	v_mfma_f32_16x16x32_bf16 v[92:95], v[128:131], v[206:209], v[92:95]
	v_mfma_f32_16x16x32_bf16 v[92:95], v[132:135], v[210:213], v[92:95]
	v_mfma_f32_16x16x32_bf16 v[84:87], v[154:157], v[206:209], v[84:87]
	v_mfma_f32_16x16x32_bf16 v[84:87], v[158:161], v[210:213], v[84:87]
	v_mfma_f32_16x16x32_bf16 v[76:79], v[128:131], v[214:217], v[76:79]
	v_mfma_f32_16x16x32_bf16 v[76:79], v[132:135], v[218:221], v[76:79]
	v_mfma_f32_16x16x32_bf16 v[68:71], v[154:157], v[214:217], v[68:71]
	v_mfma_f32_16x16x32_bf16 v[68:71], v[158:161], v[218:221], v[68:71]
	v_mfma_f32_16x16x32_bf16 v[120:123], v[162:165], v[190:193], v[120:123]
	v_mfma_f32_16x16x32_bf16 v[120:123], v[166:169], v[194:197], v[120:123]
	v_mfma_f32_16x16x32_bf16 v[112:115], v[182:185], v[190:193], v[112:115]
	v_mfma_f32_16x16x32_bf16 v[112:115], v[186:189], v[194:197], v[112:115]
	v_mfma_f32_16x16x32_bf16 v[104:107], v[162:165], v[198:201], v[104:107]
	v_mfma_f32_16x16x32_bf16 v[104:107], v[166:169], v[202:205], v[104:107]
	v_mfma_f32_16x16x32_bf16 v[96:99], v[182:185], v[198:201], v[96:99]
	v_mfma_f32_16x16x32_bf16 v[96:99], v[186:189], v[202:205], v[96:99]
	v_mfma_f32_16x16x32_bf16 v[88:91], v[162:165], v[206:209], v[88:91]
	v_mfma_f32_16x16x32_bf16 v[88:91], v[166:169], v[210:213], v[88:91]
	v_mfma_f32_16x16x32_bf16 v[80:83], v[182:185], v[206:209], v[80:83]
	v_mfma_f32_16x16x32_bf16 v[80:83], v[186:189], v[210:213], v[80:83]
	v_mfma_f32_16x16x32_bf16 v[72:75], v[162:165], v[214:217], v[72:75]
	v_mfma_f32_16x16x32_bf16 v[72:75], v[166:169], v[218:221], v[72:75]
	s_setprio 3
	s_barrier
	v_mfma_f32_16x16x32_bf16 v[64:67], v[182:185], v[214:217], v[64:67]
	v_mfma_f32_16x16x32_bf16 v[64:67], v[186:189], v[218:221], v[64:67]
	s_setprio 0
.Lzj_0_0:
	s_add_i32 s67, s25, s16
	v_lshl_add_u64 v[170:171], s[90:91], 0, v[140:141]
	s_mov_b32 m0, s67
	ds_read_b128 v[190:193], v180 offset:16384
	ds_read_b128 v[194:197], v180 offset:17408
	ds_read_b128 v[198:201], v180 offset:18432
	ds_read_b128 v[202:205], v180 offset:19456
	ds_read_b128 v[206:209], v180 offset:20480
	ds_read_b128 v[210:213], v180 offset:21504
	ds_read_b128 v[214:217], v180 offset:22528
	ds_read_b128 v[218:221], v180 offset:23552
	global_load_lds_dwordx4 v[170:171], off
	s_add_i32 m0, s67, 0x2000
	s_add_u32 s68, s90, 0x40000
	v_lshl_add_u64 v[222:223], s[90:91], 0, v[136:137]
	s_addc_u32 s69, s91, 0
	s_add_i32 s67, s26, s16
	global_load_lds_dwordx4 v[222:223], off
	v_lshl_add_u64 v[224:225], s[68:69], 0, v[140:141]
	s_mov_b32 m0, s67
	global_load_lds_dwordx4 v[224:225], off
	s_add_i32 m0, s67, 0x2000
	v_lshl_add_u64 v[224:225], s[68:69], 0, v[136:137]
	global_load_lds_dwordx4 v[224:225], off
	s_mov_b32 m0, s17
	v_lshl_add_u64 v[224:225], s[92:93], 0, v[142:143]
	global_load_lds_dwordx4 v[224:225], off
	s_mov_b32 m0, s18
	v_lshl_add_u64 v[226:227], s[92:93], 0, v[138:139]
	global_load_lds_dwordx4 v[226:227], off
	s_cmp_eq_u32 s66, -2
	s_waitcnt vmcnt(8) lgkmcnt(0)
	s_setprio 1
	s_cbranch_scc1 .Lzv_0_1
	s_barrier
	v_mfma_f32_16x16x32_bf16 v[60:63], v[128:131], v[190:193], v[60:63]
	v_mfma_f32_16x16x32_bf16 v[60:63], v[132:135], v[194:197], v[60:63]
	v_mfma_f32_16x16x32_bf16 v[52:55], v[154:157], v[190:193], v[52:55]
	v_mfma_f32_16x16x32_bf16 v[52:55], v[158:161], v[194:197], v[52:55]
	v_mfma_f32_16x16x32_bf16 v[44:47], v[128:131], v[198:201], v[44:47]
	v_mfma_f32_16x16x32_bf16 v[44:47], v[132:135], v[202:205], v[44:47]
	v_mfma_f32_16x16x32_bf16 v[36:39], v[154:157], v[198:201], v[36:39]
	v_mfma_f32_16x16x32_bf16 v[36:39], v[158:161], v[202:205], v[36:39]
	v_mfma_f32_16x16x32_bf16 v[28:31], v[128:131], v[206:209], v[28:31]
	v_mfma_f32_16x16x32_bf16 v[28:31], v[132:135], v[210:213], v[28:31]
	v_mfma_f32_16x16x32_bf16 v[20:23], v[154:157], v[206:209], v[20:23]
	v_mfma_f32_16x16x32_bf16 v[20:23], v[158:161], v[210:213], v[20:23]
	v_mfma_f32_16x16x32_bf16 v[12:15], v[128:131], v[214:217], v[12:15]
	v_mfma_f32_16x16x32_bf16 v[12:15], v[132:135], v[218:221], v[12:15]
	v_mfma_f32_16x16x32_bf16 v[4:7], v[154:157], v[214:217], v[4:7]
	v_mfma_f32_16x16x32_bf16 v[4:7], v[158:161], v[218:221], v[4:7]
	v_mfma_f32_16x16x32_bf16 v[56:59], v[162:165], v[190:193], v[56:59]
	v_mfma_f32_16x16x32_bf16 v[56:59], v[166:169], v[194:197], v[56:59]
	v_mfma_f32_16x16x32_bf16 v[48:51], v[182:185], v[190:193], v[48:51]
	v_mfma_f32_16x16x32_bf16 v[48:51], v[186:189], v[194:197], v[48:51]
	v_mfma_f32_16x16x32_bf16 v[40:43], v[162:165], v[198:201], v[40:43]
	v_mfma_f32_16x16x32_bf16 v[40:43], v[166:169], v[202:205], v[40:43]
	v_mfma_f32_16x16x32_bf16 v[32:35], v[182:185], v[198:201], v[32:35]
	v_mfma_f32_16x16x32_bf16 v[32:35], v[186:189], v[202:205], v[32:35]
	v_mfma_f32_16x16x32_bf16 v[24:27], v[162:165], v[206:209], v[24:27]
	v_mfma_f32_16x16x32_bf16 v[24:27], v[166:169], v[210:213], v[24:27]
	v_mfma_f32_16x16x32_bf16 v[16:19], v[182:185], v[206:209], v[16:19]
	v_mfma_f32_16x16x32_bf16 v[16:19], v[186:189], v[210:213], v[16:19]
	v_mfma_f32_16x16x32_bf16 v[8:11], v[162:165], v[214:217], v[8:11]
	v_mfma_f32_16x16x32_bf16 v[8:11], v[166:169], v[218:221], v[8:11]
	s_setprio 3
	s_barrier
	v_mfma_f32_16x16x32_bf16 v[0:3], v[182:185], v[214:217], v[0:3]
	v_mfma_f32_16x16x32_bf16 v[0:3], v[186:189], v[218:221], v[0:3]
	s_setprio 0
.Lzj_0_1:
	s_add_i32 s67, 0, 0x18000
	s_add_i32 s73, 0, 0x1c000
	v_add_u32_e32 v158, s67, v175
	v_add_u32_e32 v186, s73, v175
	ds_read_b128 v[128:131], v158
	ds_read_b128 v[132:135], v158 offset:1024
	ds_read_b128 v[154:157], v158 offset:2048
	ds_read_b128 v[158:161], v158 offset:3072
	ds_read_b128 v[162:165], v186
	ds_read_b128 v[166:169], v186 offset:1024
	ds_read_b128 v[182:185], v186 offset:2048
	ds_read_b128 v[186:189], v186 offset:3072
	s_add_u32 s68, s92, 0x40000
	s_addc_u32 s69, s93, 0
	s_mov_b32 m0, s19
	v_lshl_add_u64 v[228:229], s[68:69], 0, v[142:143]
	ds_read_b128 v[190:193], v180 offset:32768
	ds_read_b128 v[194:197], v180 offset:33792
	ds_read_b128 v[198:201], v180 offset:34816
	ds_read_b128 v[202:205], v180 offset:35840
	ds_read_b128 v[206:209], v180 offset:36864
	ds_read_b128 v[210:213], v180 offset:37888
	ds_read_b128 v[214:217], v180 offset:38912
	ds_read_b128 v[218:221], v180 offset:39936
	global_load_lds_dwordx4 v[228:229], off
	s_mov_b32 m0, s20
	v_lshl_add_u64 v[228:229], s[68:69], 0, v[138:139]
	global_load_lds_dwordx4 v[228:229], off
	s_waitcnt vmcnt(8) lgkmcnt(0)
	s_setprio 1
	s_barrier
	v_mfma_f32_16x16x32_bf16 v[124:127], v[128:131], v[190:193], v[124:127]
	v_mfma_f32_16x16x32_bf16 v[124:127], v[132:135], v[194:197], v[124:127]
	v_mfma_f32_16x16x32_bf16 v[116:119], v[154:157], v[190:193], v[116:119]
	v_mfma_f32_16x16x32_bf16 v[116:119], v[158:161], v[194:197], v[116:119]
	v_mfma_f32_16x16x32_bf16 v[108:111], v[128:131], v[198:201], v[108:111]
	v_mfma_f32_16x16x32_bf16 v[108:111], v[132:135], v[202:205], v[108:111]
	v_mfma_f32_16x16x32_bf16 v[100:103], v[154:157], v[198:201], v[100:103]
	v_mfma_f32_16x16x32_bf16 v[100:103], v[158:161], v[202:205], v[100:103]
	v_mfma_f32_16x16x32_bf16 v[92:95], v[128:131], v[206:209], v[92:95]
	v_mfma_f32_16x16x32_bf16 v[92:95], v[132:135], v[210:213], v[92:95]
	v_mfma_f32_16x16x32_bf16 v[84:87], v[154:157], v[206:209], v[84:87]
	v_mfma_f32_16x16x32_bf16 v[84:87], v[158:161], v[210:213], v[84:87]
	v_mfma_f32_16x16x32_bf16 v[76:79], v[128:131], v[214:217], v[76:79]
	v_mfma_f32_16x16x32_bf16 v[76:79], v[132:135], v[218:221], v[76:79]
	v_mfma_f32_16x16x32_bf16 v[68:71], v[154:157], v[214:217], v[68:71]
	v_mfma_f32_16x16x32_bf16 v[68:71], v[158:161], v[218:221], v[68:71]
	v_mfma_f32_16x16x32_bf16 v[120:123], v[162:165], v[190:193], v[120:123]
	v_mfma_f32_16x16x32_bf16 v[120:123], v[166:169], v[194:197], v[120:123]
	v_mfma_f32_16x16x32_bf16 v[112:115], v[182:185], v[190:193], v[112:115]
	v_mfma_f32_16x16x32_bf16 v[112:115], v[186:189], v[194:197], v[112:115]
	v_mfma_f32_16x16x32_bf16 v[104:107], v[162:165], v[198:201], v[104:107]
	v_mfma_f32_16x16x32_bf16 v[104:107], v[166:169], v[202:205], v[104:107]
	v_mfma_f32_16x16x32_bf16 v[96:99], v[182:185], v[198:201], v[96:99]
	v_mfma_f32_16x16x32_bf16 v[96:99], v[186:189], v[202:205], v[96:99]
	v_mfma_f32_16x16x32_bf16 v[88:91], v[162:165], v[206:209], v[88:91]
	v_mfma_f32_16x16x32_bf16 v[88:91], v[166:169], v[210:213], v[88:91]
	v_mfma_f32_16x16x32_bf16 v[80:83], v[182:185], v[206:209], v[80:83]
	v_mfma_f32_16x16x32_bf16 v[80:83], v[186:189], v[210:213], v[80:83]
	v_mfma_f32_16x16x32_bf16 v[72:75], v[162:165], v[214:217], v[72:75]
	v_mfma_f32_16x16x32_bf16 v[72:75], v[166:169], v[218:221], v[72:75]
	s_setprio 3
	s_barrier
	v_mfma_f32_16x16x32_bf16 v[64:67], v[182:185], v[214:217], v[64:67]
	v_mfma_f32_16x16x32_bf16 v[64:67], v[186:189], v[218:221], v[64:67]
	s_setprio 0
	s_add_i32 s67, s67, s16
	v_lshl_add_u64 v[170:171], v[170:171], 0, s[74:75]
	s_mov_b32 m0, s67
	ds_read_b128 v[190:193], v180 offset:49152
	ds_read_b128 v[194:197], v180 offset:50176
	ds_read_b128 v[198:201], v180 offset:51200
	ds_read_b128 v[202:205], v180 offset:52224
	ds_read_b128 v[206:209], v180 offset:53248
	ds_read_b128 v[210:213], v180 offset:54272
	ds_read_b128 v[214:217], v180 offset:55296
	ds_read_b128 v[218:221], v180 offset:56320
	global_load_lds_dwordx4 v[170:171], off
	s_add_i32 m0, s67, 0x2000
	s_add_u32 s68, s90, 0x40080
	v_lshl_add_u64 v[170:171], v[222:223], 0, s[74:75]
	s_addc_u32 s69, s91, 0
	s_add_i32 s67, s73, s16
	global_load_lds_dwordx4 v[170:171], off
	s_mov_b32 m0, s67
	v_lshl_add_u64 v[170:171], s[68:69], 0, v[140:141]
	global_load_lds_dwordx4 v[170:171], off
	s_add_i32 m0, s67, 0x2000
	v_lshl_add_u64 v[170:171], s[68:69], 0, v[136:137]
	global_load_lds_dwordx4 v[170:171], off
	s_mov_b32 m0, s23
	v_lshl_add_u64 v[170:171], v[224:225], 0, s[74:75]
	global_load_lds_dwordx4 v[170:171], off
	s_mov_b32 m0, s24
	v_lshl_add_u64 v[170:171], v[226:227], 0, s[74:75]
	global_load_lds_dwordx4 v[170:171], off
	s_waitcnt vmcnt(8) lgkmcnt(0)
	s_setprio 1
	s_barrier
	v_mfma_f32_16x16x32_bf16 v[60:63], v[128:131], v[190:193], v[60:63]
	v_mfma_f32_16x16x32_bf16 v[60:63], v[132:135], v[194:197], v[60:63]
	v_mfma_f32_16x16x32_bf16 v[52:55], v[154:157], v[190:193], v[52:55]
	v_mfma_f32_16x16x32_bf16 v[52:55], v[158:161], v[194:197], v[52:55]
	v_mfma_f32_16x16x32_bf16 v[44:47], v[128:131], v[198:201], v[44:47]
	v_mfma_f32_16x16x32_bf16 v[44:47], v[132:135], v[202:205], v[44:47]
	v_mfma_f32_16x16x32_bf16 v[36:39], v[154:157], v[198:201], v[36:39]
	v_mfma_f32_16x16x32_bf16 v[36:39], v[158:161], v[202:205], v[36:39]
	v_mfma_f32_16x16x32_bf16 v[28:31], v[128:131], v[206:209], v[28:31]
	v_mfma_f32_16x16x32_bf16 v[28:31], v[132:135], v[210:213], v[28:31]
	v_mfma_f32_16x16x32_bf16 v[20:23], v[154:157], v[206:209], v[20:23]
	v_mfma_f32_16x16x32_bf16 v[20:23], v[158:161], v[210:213], v[20:23]
	v_mfma_f32_16x16x32_bf16 v[12:15], v[128:131], v[214:217], v[12:15]
	v_mfma_f32_16x16x32_bf16 v[12:15], v[132:135], v[218:221], v[12:15]
	v_mfma_f32_16x16x32_bf16 v[4:7], v[154:157], v[214:217], v[4:7]
	v_mfma_f32_16x16x32_bf16 v[4:7], v[158:161], v[218:221], v[4:7]
	v_mfma_f32_16x16x32_bf16 v[56:59], v[162:165], v[190:193], v[56:59]
	v_mfma_f32_16x16x32_bf16 v[56:59], v[166:169], v[194:197], v[56:59]
	v_mfma_f32_16x16x32_bf16 v[48:51], v[182:185], v[190:193], v[48:51]
	v_mfma_f32_16x16x32_bf16 v[48:51], v[186:189], v[194:197], v[48:51]
	v_mfma_f32_16x16x32_bf16 v[40:43], v[162:165], v[198:201], v[40:43]
	v_mfma_f32_16x16x32_bf16 v[40:43], v[166:169], v[202:205], v[40:43]
	v_mfma_f32_16x16x32_bf16 v[32:35], v[182:185], v[198:201], v[32:35]
	v_mfma_f32_16x16x32_bf16 v[32:35], v[186:189], v[202:205], v[32:35]
	v_mfma_f32_16x16x32_bf16 v[24:27], v[162:165], v[206:209], v[24:27]
	v_mfma_f32_16x16x32_bf16 v[24:27], v[166:169], v[210:213], v[24:27]
	v_mfma_f32_16x16x32_bf16 v[16:19], v[182:185], v[206:209], v[16:19]
	v_mfma_f32_16x16x32_bf16 v[16:19], v[186:189], v[210:213], v[16:19]
	v_mfma_f32_16x16x32_bf16 v[8:11], v[162:165], v[214:217], v[8:11]
	v_mfma_f32_16x16x32_bf16 v[8:11], v[166:169], v[218:221], v[8:11]
	s_setprio 3
	s_barrier
	v_mfma_f32_16x16x32_bf16 v[0:3], v[182:185], v[214:217], v[0:3]
	v_mfma_f32_16x16x32_bf16 v[0:3], v[186:189], v[218:221], v[0:3]
	s_setprio 0
	s_add_i32 s66, s66, 2
	s_add_u32 s88, s88, 0x100
	s_addc_u32 s89, s89, 0
	s_add_u32 s58, s58, 0x100
	s_addc_u32 s59, s59, 0
	s_cmp_gt_u32 s66, 13
	s_cbranch_scc0 .LBB0_120
	s_branch .Lzskip_0
.Lzv_0_0:
	s_barrier
	v_mfma_f32_16x16x32_bf16 v[124:127], v[128:131], v[190:193], 0
	v_mfma_f32_16x16x32_bf16 v[124:127], v[132:135], v[194:197], v[124:127]
	v_mfma_f32_16x16x32_bf16 v[116:119], v[154:157], v[190:193], 0
	v_mfma_f32_16x16x32_bf16 v[116:119], v[158:161], v[194:197], v[116:119]
	v_mfma_f32_16x16x32_bf16 v[108:111], v[128:131], v[198:201], 0
	v_mfma_f32_16x16x32_bf16 v[108:111], v[132:135], v[202:205], v[108:111]
	v_mfma_f32_16x16x32_bf16 v[100:103], v[154:157], v[198:201], 0
	v_mfma_f32_16x16x32_bf16 v[100:103], v[158:161], v[202:205], v[100:103]
	v_mfma_f32_16x16x32_bf16 v[92:95], v[128:131], v[206:209], 0
	v_mfma_f32_16x16x32_bf16 v[92:95], v[132:135], v[210:213], v[92:95]
	v_mfma_f32_16x16x32_bf16 v[84:87], v[154:157], v[206:209], 0
	v_mfma_f32_16x16x32_bf16 v[84:87], v[158:161], v[210:213], v[84:87]
	v_mfma_f32_16x16x32_bf16 v[76:79], v[128:131], v[214:217], 0
	v_mfma_f32_16x16x32_bf16 v[76:79], v[132:135], v[218:221], v[76:79]
	v_mfma_f32_16x16x32_bf16 v[68:71], v[154:157], v[214:217], 0
	v_mfma_f32_16x16x32_bf16 v[68:71], v[158:161], v[218:221], v[68:71]
	v_mfma_f32_16x16x32_bf16 v[120:123], v[162:165], v[190:193], 0
	v_mfma_f32_16x16x32_bf16 v[120:123], v[166:169], v[194:197], v[120:123]
	v_mfma_f32_16x16x32_bf16 v[112:115], v[182:185], v[190:193], 0
	v_mfma_f32_16x16x32_bf16 v[112:115], v[186:189], v[194:197], v[112:115]
	v_mfma_f32_16x16x32_bf16 v[104:107], v[162:165], v[198:201], 0
	v_mfma_f32_16x16x32_bf16 v[104:107], v[166:169], v[202:205], v[104:107]
	v_mfma_f32_16x16x32_bf16 v[96:99], v[182:185], v[198:201], 0
	v_mfma_f32_16x16x32_bf16 v[96:99], v[186:189], v[202:205], v[96:99]
	v_mfma_f32_16x16x32_bf16 v[88:91], v[162:165], v[206:209], 0
	v_mfma_f32_16x16x32_bf16 v[88:91], v[166:169], v[210:213], v[88:91]
	v_mfma_f32_16x16x32_bf16 v[80:83], v[182:185], v[206:209], 0
	v_mfma_f32_16x16x32_bf16 v[80:83], v[186:189], v[210:213], v[80:83]
	v_mfma_f32_16x16x32_bf16 v[72:75], v[162:165], v[214:217], 0
	v_mfma_f32_16x16x32_bf16 v[72:75], v[166:169], v[218:221], v[72:75]
	s_setprio 3
	s_barrier
	v_mfma_f32_16x16x32_bf16 v[64:67], v[182:185], v[214:217], 0
	v_mfma_f32_16x16x32_bf16 v[64:67], v[186:189], v[218:221], v[64:67]
	s_setprio 0
	s_branch .Lzj_0_0
.Lzv_0_1:
	s_barrier
	v_mfma_f32_16x16x32_bf16 v[60:63], v[128:131], v[190:193], 0
	v_mfma_f32_16x16x32_bf16 v[60:63], v[132:135], v[194:197], v[60:63]
	v_mfma_f32_16x16x32_bf16 v[52:55], v[154:157], v[190:193], 0
	v_mfma_f32_16x16x32_bf16 v[52:55], v[158:161], v[194:197], v[52:55]
	v_mfma_f32_16x16x32_bf16 v[44:47], v[128:131], v[198:201], 0
	v_mfma_f32_16x16x32_bf16 v[44:47], v[132:135], v[202:205], v[44:47]
	v_mfma_f32_16x16x32_bf16 v[36:39], v[154:157], v[198:201], 0
	v_mfma_f32_16x16x32_bf16 v[36:39], v[158:161], v[202:205], v[36:39]
	v_mfma_f32_16x16x32_bf16 v[28:31], v[128:131], v[206:209], 0
	v_mfma_f32_16x16x32_bf16 v[28:31], v[132:135], v[210:213], v[28:31]
	v_mfma_f32_16x16x32_bf16 v[20:23], v[154:157], v[206:209], 0
	v_mfma_f32_16x16x32_bf16 v[20:23], v[158:161], v[210:213], v[20:23]
	v_mfma_f32_16x16x32_bf16 v[12:15], v[128:131], v[214:217], 0
	v_mfma_f32_16x16x32_bf16 v[12:15], v[132:135], v[218:221], v[12:15]
	v_mfma_f32_16x16x32_bf16 v[4:7], v[154:157], v[214:217], 0
	v_mfma_f32_16x16x32_bf16 v[4:7], v[158:161], v[218:221], v[4:7]
	v_mfma_f32_16x16x32_bf16 v[56:59], v[162:165], v[190:193], 0
	v_mfma_f32_16x16x32_bf16 v[56:59], v[166:169], v[194:197], v[56:59]
	v_mfma_f32_16x16x32_bf16 v[48:51], v[182:185], v[190:193], 0
	v_mfma_f32_16x16x32_bf16 v[48:51], v[186:189], v[194:197], v[48:51]
	v_mfma_f32_16x16x32_bf16 v[40:43], v[162:165], v[198:201], 0
	v_mfma_f32_16x16x32_bf16 v[40:43], v[166:169], v[202:205], v[40:43]
	v_mfma_f32_16x16x32_bf16 v[32:35], v[182:185], v[198:201], 0
	v_mfma_f32_16x16x32_bf16 v[32:35], v[186:189], v[202:205], v[32:35]
	v_mfma_f32_16x16x32_bf16 v[24:27], v[162:165], v[206:209], 0
	v_mfma_f32_16x16x32_bf16 v[24:27], v[166:169], v[210:213], v[24:27]
	v_mfma_f32_16x16x32_bf16 v[16:19], v[182:185], v[206:209], 0
	v_mfma_f32_16x16x32_bf16 v[16:19], v[186:189], v[210:213], v[16:19]
	v_mfma_f32_16x16x32_bf16 v[8:11], v[162:165], v[214:217], 0
	v_mfma_f32_16x16x32_bf16 v[8:11], v[166:169], v[218:221], v[8:11]
	s_setprio 3
	s_barrier
	v_mfma_f32_16x16x32_bf16 v[0:3], v[182:185], v[214:217], 0
	v_mfma_f32_16x16x32_bf16 v[0:3], v[186:189], v[218:221], v[0:3]
	s_setprio 0
	s_branch .Lzj_0_1

.LBB0_272:
	ds_read_b128 v[120:123], v245
	ds_read_b128 v[124:127], v245 offset:1024
	ds_read_b128 v[128:131], v245 offset:2048
	ds_read_b128 v[132:135], v245 offset:3072
	ds_read_b128 v[144:147], v246
	ds_read_b128 v[148:151], v246 offset:1024
	ds_read_b128 v[152:155], v246 offset:2048
	ds_read_b128 v[156:159], v246 offset:3072
	s_add_u32 s59, s86, 0xfff50080
	s_addc_u32 s66, s87, -1
	s_cmp_eq_u32 s58, 40
	s_cselect_b32 s91, s11, s66
	s_cselect_b32 s90, s10, s59
	s_cselect_b32 s89, s85, s57
	s_cselect_b32 s88, s84, s56
	v_lshl_add_u64 v[204:205], s[86:87], 0, v[200:201]
	s_add_i32 m0, s16, 0xc000
	ds_read_b128 v[160:163], v247
	ds_read_b128 v[164:167], v247 offset:1024
	ds_read_b128 v[168:171], v247 offset:2048
	ds_read_b128 v[172:175], v247 offset:3072
	ds_read_b128 v[176:179], v247 offset:4096
	ds_read_b128 v[180:183], v247 offset:5120
	ds_read_b128 v[184:187], v247 offset:6144
	ds_read_b128 v[188:191], v247 offset:7168
	global_load_lds_dwordx4 v[204:205], off
	s_add_i32 m0, s16, 0xe000
	v_lshl_add_u64 v[204:205], s[86:87], 0, v[202:203]
	global_load_lds_dwordx4 v[204:205], off
	s_cmp_eq_u32 s58, -2
	s_waitcnt vmcnt(8) lgkmcnt(0)
	s_setprio 1
	s_cbranch_scc1 .Lzv_1_0
	s_barrier
	v_mfma_f32_16x16x32_bf16 v[140:143], v[120:123], v[160:163], v[140:143]
	v_mfma_f32_16x16x32_bf16 v[140:143], v[124:127], v[164:167], v[140:143]
	v_mfma_f32_16x16x32_bf16 v[136:139], v[128:131], v[160:163], v[136:139]
	v_mfma_f32_16x16x32_bf16 v[136:139], v[132:135], v[164:167], v[136:139]
	v_mfma_f32_16x16x32_bf16 v[108:111], v[120:123], v[168:171], v[108:111]
	v_mfma_f32_16x16x32_bf16 v[108:111], v[124:127], v[172:175], v[108:111]
	v_mfma_f32_16x16x32_bf16 v[104:107], v[128:131], v[168:171], v[104:107]
	v_mfma_f32_16x16x32_bf16 v[104:107], v[132:135], v[172:175], v[104:107]
	v_mfma_f32_16x16x32_bf16 v[92:95], v[120:123], v[176:179], v[92:95]
	v_mfma_f32_16x16x32_bf16 v[92:95], v[124:127], v[180:183], v[92:95]
	v_mfma_f32_16x16x32_bf16 v[88:91], v[128:131], v[176:179], v[88:91]
	v_mfma_f32_16x16x32_bf16 v[88:91], v[132:135], v[180:183], v[88:91]
	v_mfma_f32_16x16x32_bf16 v[76:79], v[120:123], v[184:187], v[76:79]
	v_mfma_f32_16x16x32_bf16 v[76:79], v[124:127], v[188:191], v[76:79]
	v_mfma_f32_16x16x32_bf16 v[72:75], v[128:131], v[184:187], v[72:75]
	v_mfma_f32_16x16x32_bf16 v[72:75], v[132:135], v[188:191], v[72:75]
	v_mfma_f32_16x16x32_bf16 v[116:119], v[144:147], v[160:163], v[116:119]
	v_mfma_f32_16x16x32_bf16 v[116:119], v[148:151], v[164:167], v[116:119]
	v_mfma_f32_16x16x32_bf16 v[112:115], v[152:155], v[160:163], v[112:115]
	v_mfma_f32_16x16x32_bf16 v[112:115], v[156:159], v[164:167], v[112:115]
	v_mfma_f32_16x16x32_bf16 v[100:103], v[144:147], v[168:171], v[100:103]
	v_mfma_f32_16x16x32_bf16 v[100:103], v[148:151], v[172:175], v[100:103]
	v_mfma_f32_16x16x32_bf16 v[96:99], v[152:155], v[168:171], v[96:99]
	v_mfma_f32_16x16x32_bf16 v[96:99], v[156:159], v[172:175], v[96:99]
	v_mfma_f32_16x16x32_bf16 v[84:87], v[144:147], v[176:179], v[84:87]
	v_mfma_f32_16x16x32_bf16 v[84:87], v[148:151], v[180:183], v[84:87]
	v_mfma_f32_16x16x32_bf16 v[80:83], v[152:155], v[176:179], v[80:83]
	v_mfma_f32_16x16x32_bf16 v[80:83], v[156:159], v[180:183], v[80:83]
	v_mfma_f32_16x16x32_bf16 v[68:71], v[144:147], v[184:187], v[68:71]
	v_mfma_f32_16x16x32_bf16 v[68:71], v[148:151], v[188:191], v[68:71]
	s_setprio 3
	s_barrier
	v_mfma_f32_16x16x32_bf16 v[64:67], v[152:155], v[184:187], v[64:67]
	v_mfma_f32_16x16x32_bf16 v[64:67], v[156:159], v[188:191], v[64:67]
	s_setprio 0
.Lzj_1_0:
	s_add_i32 s59, s26, s15
	v_lshl_add_u64 v[204:205], s[88:89], 0, v[194:195]
	s_mov_b32 m0, s59
	ds_read_b128 v[160:163], v247 offset:16384
	ds_read_b128 v[164:167], v247 offset:17408
	ds_read_b128 v[168:171], v247 offset:18432
	ds_read_b128 v[172:175], v247 offset:19456
	ds_read_b128 v[176:179], v247 offset:20480
	ds_read_b128 v[180:183], v247 offset:21504
	ds_read_b128 v[184:187], v247 offset:22528
	ds_read_b128 v[188:191], v247 offset:23552
	global_load_lds_dwordx4 v[204:205], off
	s_add_i32 m0, s59, 0x2000
	s_add_u32 s66, s88, 0xb0000
	v_lshl_add_u64 v[206:207], s[88:89], 0, v[198:199]
	s_addc_u32 s67, s89, 0
	s_add_i32 s59, s27, s15
	global_load_lds_dwordx4 v[206:207], off
	v_lshl_add_u64 v[208:209], s[66:67], 0, v[194:195]
	s_mov_b32 m0, s59
	global_load_lds_dwordx4 v[208:209], off
	s_add_i32 m0, s59, 0x2000
	v_lshl_add_u64 v[208:209], s[66:67], 0, v[198:199]
	global_load_lds_dwordx4 v[208:209], off
	s_mov_b32 m0, s16
	v_lshl_add_u64 v[208:209], s[90:91], 0, v[192:193]
	global_load_lds_dwordx4 v[208:209], off
	s_mov_b32 m0, s17
	v_lshl_add_u64 v[210:211], s[90:91], 0, v[196:197]
	global_load_lds_dwordx4 v[210:211], off
	s_cmp_eq_u32 s58, -2
	s_waitcnt vmcnt(8) lgkmcnt(0)
	s_setprio 1
	s_cbranch_scc1 .Lzv_1_1
	s_barrier
	v_mfma_f32_16x16x32_bf16 v[60:63], v[120:123], v[160:163], v[60:63]
	v_mfma_f32_16x16x32_bf16 v[60:63], v[124:127], v[164:167], v[60:63]
	v_mfma_f32_16x16x32_bf16 v[56:59], v[128:131], v[160:163], v[56:59]
	v_mfma_f32_16x16x32_bf16 v[56:59], v[132:135], v[164:167], v[56:59]
	v_mfma_f32_16x16x32_bf16 v[44:47], v[120:123], v[168:171], v[44:47]
	v_mfma_f32_16x16x32_bf16 v[44:47], v[124:127], v[172:175], v[44:47]
	v_mfma_f32_16x16x32_bf16 v[40:43], v[128:131], v[168:171], v[40:43]
	v_mfma_f32_16x16x32_bf16 v[40:43], v[132:135], v[172:175], v[40:43]
	v_mfma_f32_16x16x32_bf16 v[28:31], v[120:123], v[176:179], v[28:31]
	v_mfma_f32_16x16x32_bf16 v[28:31], v[124:127], v[180:183], v[28:31]
	v_mfma_f32_16x16x32_bf16 v[24:27], v[128:131], v[176:179], v[24:27]
	v_mfma_f32_16x16x32_bf16 v[24:27], v[132:135], v[180:183], v[24:27]
	v_mfma_f32_16x16x32_bf16 v[12:15], v[120:123], v[184:187], v[12:15]
	v_mfma_f32_16x16x32_bf16 v[12:15], v[124:127], v[188:191], v[12:15]
	v_mfma_f32_16x16x32_bf16 v[8:11], v[128:131], v[184:187], v[8:11]
	v_mfma_f32_16x16x32_bf16 v[8:11], v[132:135], v[188:191], v[8:11]
	v_mfma_f32_16x16x32_bf16 v[52:55], v[144:147], v[160:163], v[52:55]
	v_mfma_f32_16x16x32_bf16 v[52:55], v[148:151], v[164:167], v[52:55]
	v_mfma_f32_16x16x32_bf16 v[48:51], v[152:155], v[160:163], v[48:51]
	v_mfma_f32_16x16x32_bf16 v[48:51], v[156:159], v[164:167], v[48:51]
	v_mfma_f32_16x16x32_bf16 v[36:39], v[144:147], v[168:171], v[36:39]
	v_mfma_f32_16x16x32_bf16 v[36:39], v[148:151], v[172:175], v[36:39]
	v_mfma_f32_16x16x32_bf16 v[32:35], v[152:155], v[168:171], v[32:35]
	v_mfma_f32_16x16x32_bf16 v[32:35], v[156:159], v[172:175], v[32:35]
	v_mfma_f32_16x16x32_bf16 v[20:23], v[144:147], v[176:179], v[20:23]
	v_mfma_f32_16x16x32_bf16 v[20:23], v[148:151], v[180:183], v[20:23]
	v_mfma_f32_16x16x32_bf16 v[16:19], v[152:155], v[176:179], v[16:19]
	v_mfma_f32_16x16x32_bf16 v[16:19], v[156:159], v[180:183], v[16:19]
	v_mfma_f32_16x16x32_bf16 v[4:7], v[144:147], v[184:187], v[4:7]
	v_mfma_f32_16x16x32_bf16 v[4:7], v[148:151], v[188:191], v[4:7]
	s_setprio 3
	s_barrier
	v_mfma_f32_16x16x32_bf16 v[0:3], v[152:155], v[184:187], v[0:3]
	v_mfma_f32_16x16x32_bf16 v[0:3], v[156:159], v[188:191], v[0:3]
	s_setprio 0
.Lzj_1_1:
	s_add_i32 s59, 0, 0x18000
	s_add_i32 s68, 0, 0x1c000
	v_add_u32_e32 v132, s59, v243
	v_add_u32_e32 v156, s68, v243
	ds_read_b128 v[120:123], v132
	ds_read_b128 v[124:127], v132 offset:1024
	ds_read_b128 v[128:131], v132 offset:2048
	ds_read_b128 v[132:135], v132 offset:3072
	ds_read_b128 v[144:147], v156
	ds_read_b128 v[148:151], v156 offset:1024
	ds_read_b128 v[152:155], v156 offset:2048
	ds_read_b128 v[156:159], v156 offset:3072
	s_add_u32 s66, s90, 0xb0000
	s_addc_u32 s67, s91, 0
	s_mov_b32 m0, s18
	v_lshl_add_u64 v[212:213], s[66:67], 0, v[192:193]
	ds_read_b128 v[160:163], v247 offset:32768
	ds_read_b128 v[164:167], v247 offset:33792
	ds_read_b128 v[168:171], v247 offset:34816
	ds_read_b128 v[172:175], v247 offset:35840
	ds_read_b128 v[176:179], v247 offset:36864
	ds_read_b128 v[180:183], v247 offset:37888
	ds_read_b128 v[184:187], v247 offset:38912
	ds_read_b128 v[188:191], v247 offset:39936
	global_load_lds_dwordx4 v[212:213], off
	s_mov_b32 m0, s19
	v_lshl_add_u64 v[212:213], s[66:67], 0, v[196:197]
	global_load_lds_dwordx4 v[212:213], off
	s_waitcnt vmcnt(8) lgkmcnt(0)
	s_setprio 1
	s_barrier
	v_mfma_f32_16x16x32_bf16 v[140:143], v[120:123], v[160:163], v[140:143]
	v_mfma_f32_16x16x32_bf16 v[140:143], v[124:127], v[164:167], v[140:143]
	v_mfma_f32_16x16x32_bf16 v[136:139], v[128:131], v[160:163], v[136:139]
	v_mfma_f32_16x16x32_bf16 v[136:139], v[132:135], v[164:167], v[136:139]
	v_mfma_f32_16x16x32_bf16 v[108:111], v[120:123], v[168:171], v[108:111]
	v_mfma_f32_16x16x32_bf16 v[108:111], v[124:127], v[172:175], v[108:111]
	v_mfma_f32_16x16x32_bf16 v[104:107], v[128:131], v[168:171], v[104:107]
	v_mfma_f32_16x16x32_bf16 v[104:107], v[132:135], v[172:175], v[104:107]
	v_mfma_f32_16x16x32_bf16 v[92:95], v[120:123], v[176:179], v[92:95]
	v_mfma_f32_16x16x32_bf16 v[92:95], v[124:127], v[180:183], v[92:95]
	v_mfma_f32_16x16x32_bf16 v[88:91], v[128:131], v[176:179], v[88:91]
	v_mfma_f32_16x16x32_bf16 v[88:91], v[132:135], v[180:183], v[88:91]
	v_mfma_f32_16x16x32_bf16 v[76:79], v[120:123], v[184:187], v[76:79]
	v_mfma_f32_16x16x32_bf16 v[76:79], v[124:127], v[188:191], v[76:79]
	v_mfma_f32_16x16x32_bf16 v[72:75], v[128:131], v[184:187], v[72:75]
	v_mfma_f32_16x16x32_bf16 v[72:75], v[132:135], v[188:191], v[72:75]
	v_mfma_f32_16x16x32_bf16 v[116:119], v[144:147], v[160:163], v[116:119]
	v_mfma_f32_16x16x32_bf16 v[116:119], v[148:151], v[164:167], v[116:119]
	v_mfma_f32_16x16x32_bf16 v[112:115], v[152:155], v[160:163], v[112:115]
	v_mfma_f32_16x16x32_bf16 v[112:115], v[156:159], v[164:167], v[112:115]
	v_mfma_f32_16x16x32_bf16 v[100:103], v[144:147], v[168:171], v[100:103]
	v_mfma_f32_16x16x32_bf16 v[100:103], v[148:151], v[172:175], v[100:103]
	v_mfma_f32_16x16x32_bf16 v[96:99], v[152:155], v[168:171], v[96:99]
	v_mfma_f32_16x16x32_bf16 v[96:99], v[156:159], v[172:175], v[96:99]
	v_mfma_f32_16x16x32_bf16 v[84:87], v[144:147], v[176:179], v[84:87]
	v_mfma_f32_16x16x32_bf16 v[84:87], v[148:151], v[180:183], v[84:87]
	v_mfma_f32_16x16x32_bf16 v[80:83], v[152:155], v[176:179], v[80:83]
	v_mfma_f32_16x16x32_bf16 v[80:83], v[156:159], v[180:183], v[80:83]
	v_mfma_f32_16x16x32_bf16 v[68:71], v[144:147], v[184:187], v[68:71]
	v_mfma_f32_16x16x32_bf16 v[68:71], v[148:151], v[188:191], v[68:71]
	s_setprio 3
	s_barrier
	v_mfma_f32_16x16x32_bf16 v[64:67], v[152:155], v[184:187], v[64:67]
	v_mfma_f32_16x16x32_bf16 v[64:67], v[156:159], v[188:191], v[64:67]
	s_setprio 0
	s_add_i32 s59, s59, s15
	v_lshl_add_u64 v[204:205], v[204:205], 0, s[80:81]
	s_mov_b32 m0, s59
	ds_read_b128 v[160:163], v247 offset:49152
	ds_read_b128 v[164:167], v247 offset:50176
	ds_read_b128 v[168:171], v247 offset:51200
	ds_read_b128 v[172:175], v247 offset:52224
	ds_read_b128 v[176:179], v247 offset:53248
	ds_read_b128 v[180:183], v247 offset:54272
	ds_read_b128 v[184:187], v247 offset:55296
	ds_read_b128 v[188:191], v247 offset:56320
	global_load_lds_dwordx4 v[204:205], off
	s_add_i32 m0, s59, 0x2000
	s_add_u32 s66, s88, 0xb0080
	v_lshl_add_u64 v[204:205], v[206:207], 0, s[80:81]
	s_addc_u32 s67, s89, 0
	s_add_i32 s59, s68, s15
	global_load_lds_dwordx4 v[204:205], off
	s_mov_b32 m0, s59
	v_lshl_add_u64 v[204:205], s[66:67], 0, v[194:195]
	global_load_lds_dwordx4 v[204:205], off
	s_add_i32 m0, s59, 0x2000
	v_lshl_add_u64 v[204:205], s[66:67], 0, v[198:199]
	global_load_lds_dwordx4 v[204:205], off
	s_mov_b32 m0, s21
	v_lshl_add_u64 v[204:205], v[208:209], 0, s[80:81]
	global_load_lds_dwordx4 v[204:205], off
	s_mov_b32 m0, s22
	v_lshl_add_u64 v[204:205], v[210:211], 0, s[80:81]
	global_load_lds_dwordx4 v[204:205], off
	s_waitcnt vmcnt(8) lgkmcnt(0)
	s_setprio 1
	s_barrier
	v_mfma_f32_16x16x32_bf16 v[60:63], v[120:123], v[160:163], v[60:63]
	v_mfma_f32_16x16x32_bf16 v[60:63], v[124:127], v[164:167], v[60:63]
	v_mfma_f32_16x16x32_bf16 v[56:59], v[128:131], v[160:163], v[56:59]
	v_mfma_f32_16x16x32_bf16 v[56:59], v[132:135], v[164:167], v[56:59]
	v_mfma_f32_16x16x32_bf16 v[44:47], v[120:123], v[168:171], v[44:47]
	v_mfma_f32_16x16x32_bf16 v[44:47], v[124:127], v[172:175], v[44:47]
	v_mfma_f32_16x16x32_bf16 v[40:43], v[128:131], v[168:171], v[40:43]
	v_mfma_f32_16x16x32_bf16 v[40:43], v[132:135], v[172:175], v[40:43]
	v_mfma_f32_16x16x32_bf16 v[28:31], v[120:123], v[176:179], v[28:31]
	v_mfma_f32_16x16x32_bf16 v[28:31], v[124:127], v[180:183], v[28:31]
	v_mfma_f32_16x16x32_bf16 v[24:27], v[128:131], v[176:179], v[24:27]
	v_mfma_f32_16x16x32_bf16 v[24:27], v[132:135], v[180:183], v[24:27]
	v_mfma_f32_16x16x32_bf16 v[12:15], v[120:123], v[184:187], v[12:15]
	v_mfma_f32_16x16x32_bf16 v[12:15], v[124:127], v[188:191], v[12:15]
	v_mfma_f32_16x16x32_bf16 v[8:11], v[128:131], v[184:187], v[8:11]
	v_mfma_f32_16x16x32_bf16 v[8:11], v[132:135], v[188:191], v[8:11]
	v_mfma_f32_16x16x32_bf16 v[52:55], v[144:147], v[160:163], v[52:55]
	v_mfma_f32_16x16x32_bf16 v[52:55], v[148:151], v[164:167], v[52:55]
	v_mfma_f32_16x16x32_bf16 v[48:51], v[152:155], v[160:163], v[48:51]
	v_mfma_f32_16x16x32_bf16 v[48:51], v[156:159], v[164:167], v[48:51]
	v_mfma_f32_16x16x32_bf16 v[36:39], v[144:147], v[168:171], v[36:39]
	v_mfma_f32_16x16x32_bf16 v[36:39], v[148:151], v[172:175], v[36:39]
	v_mfma_f32_16x16x32_bf16 v[32:35], v[152:155], v[168:171], v[32:35]
	v_mfma_f32_16x16x32_bf16 v[32:35], v[156:159], v[172:175], v[32:35]
	v_mfma_f32_16x16x32_bf16 v[20:23], v[144:147], v[176:179], v[20:23]
	v_mfma_f32_16x16x32_bf16 v[20:23], v[148:151], v[180:183], v[20:23]
	v_mfma_f32_16x16x32_bf16 v[16:19], v[152:155], v[176:179], v[16:19]
	v_mfma_f32_16x16x32_bf16 v[16:19], v[156:159], v[180:183], v[16:19]
	v_mfma_f32_16x16x32_bf16 v[4:7], v[144:147], v[184:187], v[4:7]
	v_mfma_f32_16x16x32_bf16 v[4:7], v[148:151], v[188:191], v[4:7]
	s_setprio 3
	s_barrier
	v_mfma_f32_16x16x32_bf16 v[0:3], v[152:155], v[184:187], v[0:3]
	v_mfma_f32_16x16x32_bf16 v[0:3], v[156:159], v[188:191], v[0:3]
	s_setprio 0
	s_add_i32 s58, s58, 2
	s_add_u32 s86, s86, 0x100
	s_addc_u32 s87, s87, 0
	s_add_u32 s56, s56, 0x100
	s_addc_u32 s57, s57, 0
	s_cmp_gt_u32 s58, 41
	s_cbranch_scc0 .LBB0_272
	s_branch .Lzskip_1
.Lzv_1_0:
	s_barrier
	v_mfma_f32_16x16x32_bf16 v[140:143], v[120:123], v[160:163], 0
	v_mfma_f32_16x16x32_bf16 v[140:143], v[124:127], v[164:167], v[140:143]
	v_mfma_f32_16x16x32_bf16 v[136:139], v[128:131], v[160:163], 0
	v_mfma_f32_16x16x32_bf16 v[136:139], v[132:135], v[164:167], v[136:139]
	v_mfma_f32_16x16x32_bf16 v[108:111], v[120:123], v[168:171], 0
	v_mfma_f32_16x16x32_bf16 v[108:111], v[124:127], v[172:175], v[108:111]
	v_mfma_f32_16x16x32_bf16 v[104:107], v[128:131], v[168:171], 0
	v_mfma_f32_16x16x32_bf16 v[104:107], v[132:135], v[172:175], v[104:107]
	v_mfma_f32_16x16x32_bf16 v[92:95], v[120:123], v[176:179], 0
	v_mfma_f32_16x16x32_bf16 v[92:95], v[124:127], v[180:183], v[92:95]
	v_mfma_f32_16x16x32_bf16 v[88:91], v[128:131], v[176:179], 0
	v_mfma_f32_16x16x32_bf16 v[88:91], v[132:135], v[180:183], v[88:91]
	v_mfma_f32_16x16x32_bf16 v[76:79], v[120:123], v[184:187], 0
	v_mfma_f32_16x16x32_bf16 v[76:79], v[124:127], v[188:191], v[76:79]
	v_mfma_f32_16x16x32_bf16 v[72:75], v[128:131], v[184:187], 0
	v_mfma_f32_16x16x32_bf16 v[72:75], v[132:135], v[188:191], v[72:75]
	v_mfma_f32_16x16x32_bf16 v[116:119], v[144:147], v[160:163], 0
	v_mfma_f32_16x16x32_bf16 v[116:119], v[148:151], v[164:167], v[116:119]
	v_mfma_f32_16x16x32_bf16 v[112:115], v[152:155], v[160:163], 0
	v_mfma_f32_16x16x32_bf16 v[112:115], v[156:159], v[164:167], v[112:115]
	v_mfma_f32_16x16x32_bf16 v[100:103], v[144:147], v[168:171], 0
	v_mfma_f32_16x16x32_bf16 v[100:103], v[148:151], v[172:175], v[100:103]
	v_mfma_f32_16x16x32_bf16 v[96:99], v[152:155], v[168:171], 0
	v_mfma_f32_16x16x32_bf16 v[96:99], v[156:159], v[172:175], v[96:99]
	v_mfma_f32_16x16x32_bf16 v[84:87], v[144:147], v[176:179], 0
	v_mfma_f32_16x16x32_bf16 v[84:87], v[148:151], v[180:183], v[84:87]
	v_mfma_f32_16x16x32_bf16 v[80:83], v[152:155], v[176:179], 0
	v_mfma_f32_16x16x32_bf16 v[80:83], v[156:159], v[180:183], v[80:83]
	v_mfma_f32_16x16x32_bf16 v[68:71], v[144:147], v[184:187], 0
	v_mfma_f32_16x16x32_bf16 v[68:71], v[148:151], v[188:191], v[68:71]
	s_setprio 3
	s_barrier
	v_mfma_f32_16x16x32_bf16 v[64:67], v[152:155], v[184:187], 0
	v_mfma_f32_16x16x32_bf16 v[64:67], v[156:159], v[188:191], v[64:67]
	s_setprio 0
	s_branch .Lzj_1_0
.Lzv_1_1:
	s_barrier
	v_mfma_f32_16x16x32_bf16 v[60:63], v[120:123], v[160:163], 0
	v_mfma_f32_16x16x32_bf16 v[60:63], v[124:127], v[164:167], v[60:63]
	v_mfma_f32_16x16x32_bf16 v[56:59], v[128:131], v[160:163], 0
	v_mfma_f32_16x16x32_bf16 v[56:59], v[132:135], v[164:167], v[56:59]
	v_mfma_f32_16x16x32_bf16 v[44:47], v[120:123], v[168:171], 0
	v_mfma_f32_16x16x32_bf16 v[44:47], v[124:127], v[172:175], v[44:47]
	v_mfma_f32_16x16x32_bf16 v[40:43], v[128:131], v[168:171], 0
	v_mfma_f32_16x16x32_bf16 v[40:43], v[132:135], v[172:175], v[40:43]
	v_mfma_f32_16x16x32_bf16 v[28:31], v[120:123], v[176:179], 0
	v_mfma_f32_16x16x32_bf16 v[28:31], v[124:127], v[180:183], v[28:31]
	v_mfma_f32_16x16x32_bf16 v[24:27], v[128:131], v[176:179], 0
	v_mfma_f32_16x16x32_bf16 v[24:27], v[132:135], v[180:183], v[24:27]
	v_mfma_f32_16x16x32_bf16 v[12:15], v[120:123], v[184:187], 0
	v_mfma_f32_16x16x32_bf16 v[12:15], v[124:127], v[188:191], v[12:15]
	v_mfma_f32_16x16x32_bf16 v[8:11], v[128:131], v[184:187], 0
	v_mfma_f32_16x16x32_bf16 v[8:11], v[132:135], v[188:191], v[8:11]
	v_mfma_f32_16x16x32_bf16 v[52:55], v[144:147], v[160:163], 0
	v_mfma_f32_16x16x32_bf16 v[52:55], v[148:151], v[164:167], v[52:55]
	v_mfma_f32_16x16x32_bf16 v[48:51], v[152:155], v[160:163], 0
	v_mfma_f32_16x16x32_bf16 v[48:51], v[156:159], v[164:167], v[48:51]
	v_mfma_f32_16x16x32_bf16 v[36:39], v[144:147], v[168:171], 0
	v_mfma_f32_16x16x32_bf16 v[36:39], v[148:151], v[172:175], v[36:39]
	v_mfma_f32_16x16x32_bf16 v[32:35], v[152:155], v[168:171], 0
	v_mfma_f32_16x16x32_bf16 v[32:35], v[156:159], v[172:175], v[32:35]
	v_mfma_f32_16x16x32_bf16 v[20:23], v[144:147], v[176:179], 0
	v_mfma_f32_16x16x32_bf16 v[20:23], v[148:151], v[180:183], v[20:23]
	v_mfma_f32_16x16x32_bf16 v[16:19], v[152:155], v[176:179], 0
	v_mfma_f32_16x16x32_bf16 v[16:19], v[156:159], v[180:183], v[16:19]
	v_mfma_f32_16x16x32_bf16 v[4:7], v[144:147], v[184:187], 0
	v_mfma_f32_16x16x32_bf16 v[4:7], v[148:151], v[188:191], v[4:7]
	s_setprio 3
	s_barrier
	v_mfma_f32_16x16x32_bf16 v[0:3], v[152:155], v[184:187], 0
	v_mfma_f32_16x16x32_bf16 v[0:3], v[156:159], v[188:191], v[0:3]
	s_setprio 0
	s_branch .Lzj_1_1

.LBB0_429:
	ds_read_b128 v[128:131], v203
	ds_read_b128 v[132:135], v203 offset:1024
	ds_read_b128 v[136:139], v203 offset:2048
	ds_read_b128 v[164:167], v203 offset:3072
	ds_read_b128 v[168:171], v204
	ds_read_b128 v[172:175], v204 offset:1024
	ds_read_b128 v[176:179], v204 offset:2048
	ds_read_b128 v[180:183], v204 offset:3072
	s_add_u32 s6, s88, 0xfffc0080
	s_addc_u32 s7, s89, -1
	s_cmp_eq_u32 s21, 12
	s_cselect_b32 vcc_hi, s15, s7
	s_cselect_b32 vcc_lo, s16, s6
	s_cselect_b32 s7, s17, s20
	s_cselect_b32 s6, s18, s19
	v_lshl_add_u64 v[196:197], s[88:89], 0, v[156:157]
	s_add_i32 m0, s58, 0xc000
	ds_read_b128 v[184:187], v205
	ds_read_b128 v[188:191], v205 offset:1024
	ds_read_b128 v[192:195], v205 offset:2048
	ds_read_b128 v[212:215], v205 offset:3072
	ds_read_b128 v[216:219], v205 offset:4096
	ds_read_b128 v[220:223], v205 offset:5120
	ds_read_b128 v[224:227], v205 offset:6144
	ds_read_b128 v[228:231], v205 offset:7168
	global_load_lds_dwordx4 v[196:197], off
	s_add_i32 m0, s58, 0xe000
	v_lshl_add_u64 v[196:197], s[88:89], 0, v[158:159]
	global_load_lds_dwordx4 v[196:197], off
	s_cmp_eq_u32 s21, -2
	s_waitcnt vmcnt(8) lgkmcnt(0)
	s_setprio 1
	s_cbranch_scc1 .Lzv_2_0
	s_barrier
	v_mfma_f32_16x16x32_bf16 v[124:127], v[128:131], v[184:187], v[124:127]
	v_mfma_f32_16x16x32_bf16 v[124:127], v[132:135], v[188:191], v[124:127]
	v_mfma_f32_16x16x32_bf16 v[116:119], v[136:139], v[184:187], v[116:119]
	v_mfma_f32_16x16x32_bf16 v[116:119], v[164:167], v[188:191], v[116:119]
	v_mfma_f32_16x16x32_bf16 v[108:111], v[128:131], v[192:195], v[108:111]
	v_mfma_f32_16x16x32_bf16 v[108:111], v[132:135], v[212:215], v[108:111]
	v_mfma_f32_16x16x32_bf16 v[100:103], v[136:139], v[192:195], v[100:103]
	v_mfma_f32_16x16x32_bf16 v[100:103], v[164:167], v[212:215], v[100:103]
	v_mfma_f32_16x16x32_bf16 v[92:95], v[128:131], v[216:219], v[92:95]
	v_mfma_f32_16x16x32_bf16 v[92:95], v[132:135], v[220:223], v[92:95]
	v_mfma_f32_16x16x32_bf16 v[84:87], v[136:139], v[216:219], v[84:87]
	v_mfma_f32_16x16x32_bf16 v[84:87], v[164:167], v[220:223], v[84:87]
	v_mfma_f32_16x16x32_bf16 v[76:79], v[128:131], v[224:227], v[76:79]
	v_mfma_f32_16x16x32_bf16 v[76:79], v[132:135], v[228:231], v[76:79]
	v_mfma_f32_16x16x32_bf16 v[68:71], v[136:139], v[224:227], v[68:71]
	v_mfma_f32_16x16x32_bf16 v[68:71], v[164:167], v[228:231], v[68:71]
	v_mfma_f32_16x16x32_bf16 v[120:123], v[168:171], v[184:187], v[120:123]
	v_mfma_f32_16x16x32_bf16 v[120:123], v[172:175], v[188:191], v[120:123]
	v_mfma_f32_16x16x32_bf16 v[112:115], v[176:179], v[184:187], v[112:115]
	v_mfma_f32_16x16x32_bf16 v[112:115], v[180:183], v[188:191], v[112:115]
	v_mfma_f32_16x16x32_bf16 v[104:107], v[168:171], v[192:195], v[104:107]
	v_mfma_f32_16x16x32_bf16 v[104:107], v[172:175], v[212:215], v[104:107]
	v_mfma_f32_16x16x32_bf16 v[96:99], v[176:179], v[192:195], v[96:99]
	v_mfma_f32_16x16x32_bf16 v[96:99], v[180:183], v[212:215], v[96:99]
	v_mfma_f32_16x16x32_bf16 v[88:91], v[168:171], v[216:219], v[88:91]
	v_mfma_f32_16x16x32_bf16 v[88:91], v[172:175], v[220:223], v[88:91]
	v_mfma_f32_16x16x32_bf16 v[80:83], v[176:179], v[216:219], v[80:83]
	v_mfma_f32_16x16x32_bf16 v[80:83], v[180:183], v[220:223], v[80:83]
	v_mfma_f32_16x16x32_bf16 v[72:75], v[168:171], v[224:227], v[72:75]
	v_mfma_f32_16x16x32_bf16 v[72:75], v[172:175], v[228:231], v[72:75]
	s_setprio 3
	s_barrier
	v_mfma_f32_16x16x32_bf16 v[64:67], v[176:179], v[224:227], v[64:67]
	v_mfma_f32_16x16x32_bf16 v[64:67], v[180:183], v[228:231], v[64:67]
	s_setprio 0
.Lzj_2_0:
	s_add_i32 s22, s76, s57
	v_lshl_add_u64 v[196:197], s[6:7], 0, v[142:143]
	s_mov_b32 m0, s22
	ds_read_b128 v[184:187], v205 offset:16384
	ds_read_b128 v[188:191], v205 offset:17408
	ds_read_b128 v[192:195], v205 offset:18432
	ds_read_b128 v[212:215], v205 offset:19456
	ds_read_b128 v[216:219], v205 offset:20480
	ds_read_b128 v[220:223], v205 offset:21504
	ds_read_b128 v[224:227], v205 offset:22528
	ds_read_b128 v[228:231], v205 offset:23552
	global_load_lds_dwordx4 v[196:197], off
	s_add_i32 m0, s22, 0x2000
	s_add_u32 s22, s6, 0x40000
	v_lshl_add_u64 v[232:233], s[6:7], 0, v[146:147]
	s_addc_u32 s23, s7, 0
	s_add_i32 s24, s77, s57
	global_load_lds_dwordx4 v[232:233], off
	v_lshl_add_u64 v[234:235], s[22:23], 0, v[142:143]
	s_mov_b32 m0, s24
	global_load_lds_dwordx4 v[234:235], off
	s_add_i32 m0, s24, 0x2000
	v_lshl_add_u64 v[234:235], s[22:23], 0, v[146:147]
	global_load_lds_dwordx4 v[234:235], off
	s_mov_b32 m0, s58
	v_lshl_add_u64 v[234:235], vcc, 0, v[140:141]
	global_load_lds_dwordx4 v[234:235], off
	s_mov_b32 m0, s59
	v_lshl_add_u64 v[236:237], vcc, 0, v[144:145]
	global_load_lds_dwordx4 v[236:237], off
	s_cmp_eq_u32 s21, -2
	s_waitcnt vmcnt(8) lgkmcnt(0)
	s_setprio 1
	s_cbranch_scc1 .Lzv_2_1
	s_barrier
	v_mfma_f32_16x16x32_bf16 v[60:63], v[128:131], v[184:187], v[60:63]
	v_mfma_f32_16x16x32_bf16 v[60:63], v[132:135], v[188:191], v[60:63]
	v_mfma_f32_16x16x32_bf16 v[52:55], v[136:139], v[184:187], v[52:55]
	v_mfma_f32_16x16x32_bf16 v[52:55], v[164:167], v[188:191], v[52:55]
	v_mfma_f32_16x16x32_bf16 v[44:47], v[128:131], v[192:195], v[44:47]
	v_mfma_f32_16x16x32_bf16 v[44:47], v[132:135], v[212:215], v[44:47]
	v_mfma_f32_16x16x32_bf16 v[36:39], v[136:139], v[192:195], v[36:39]
	v_mfma_f32_16x16x32_bf16 v[36:39], v[164:167], v[212:215], v[36:39]
	v_mfma_f32_16x16x32_bf16 v[28:31], v[128:131], v[216:219], v[28:31]
	v_mfma_f32_16x16x32_bf16 v[28:31], v[132:135], v[220:223], v[28:31]
	v_mfma_f32_16x16x32_bf16 v[20:23], v[136:139], v[216:219], v[20:23]
	v_mfma_f32_16x16x32_bf16 v[20:23], v[164:167], v[220:223], v[20:23]
	v_mfma_f32_16x16x32_bf16 v[12:15], v[128:131], v[224:227], v[12:15]
	v_mfma_f32_16x16x32_bf16 v[12:15], v[132:135], v[228:231], v[12:15]
	v_mfma_f32_16x16x32_bf16 v[4:7], v[136:139], v[224:227], v[4:7]
	v_mfma_f32_16x16x32_bf16 v[4:7], v[164:167], v[228:231], v[4:7]
	v_mfma_f32_16x16x32_bf16 v[56:59], v[168:171], v[184:187], v[56:59]
	v_mfma_f32_16x16x32_bf16 v[56:59], v[172:175], v[188:191], v[56:59]
	v_mfma_f32_16x16x32_bf16 v[48:51], v[176:179], v[184:187], v[48:51]
	v_mfma_f32_16x16x32_bf16 v[48:51], v[180:183], v[188:191], v[48:51]
	v_mfma_f32_16x16x32_bf16 v[40:43], v[168:171], v[192:195], v[40:43]
	v_mfma_f32_16x16x32_bf16 v[40:43], v[172:175], v[212:215], v[40:43]
	v_mfma_f32_16x16x32_bf16 v[32:35], v[176:179], v[192:195], v[32:35]
	v_mfma_f32_16x16x32_bf16 v[32:35], v[180:183], v[212:215], v[32:35]
	v_mfma_f32_16x16x32_bf16 v[24:27], v[168:171], v[216:219], v[24:27]
	v_mfma_f32_16x16x32_bf16 v[24:27], v[172:175], v[220:223], v[24:27]
	v_mfma_f32_16x16x32_bf16 v[16:19], v[176:179], v[216:219], v[16:19]
	v_mfma_f32_16x16x32_bf16 v[16:19], v[180:183], v[220:223], v[16:19]
	v_mfma_f32_16x16x32_bf16 v[8:11], v[168:171], v[224:227], v[8:11]
	v_mfma_f32_16x16x32_bf16 v[8:11], v[172:175], v[228:231], v[8:11]
	s_setprio 3
	s_barrier
	v_mfma_f32_16x16x32_bf16 v[0:3], v[176:179], v[224:227], v[0:3]
	v_mfma_f32_16x16x32_bf16 v[0:3], v[180:183], v[228:231], v[0:3]
	s_setprio 0
.Lzj_2_1:
	s_add_i32 s24, 0, 0x18000
	v_add_u32_e32 v150, s24, v200
	s_add_i32 s25, 0, 0x1c000
	ds_read_b128 v[128:131], v150
	ds_read_b128 v[132:135], v150 offset:1024
	ds_read_b128 v[136:139], v150 offset:2048
	ds_read_b128 v[164:167], v150 offset:3072
	v_add_u32_e32 v150, s25, v200
	ds_read_b128 v[168:171], v150
	ds_read_b128 v[172:175], v150 offset:1024
	ds_read_b128 v[176:179], v150 offset:2048
	ds_read_b128 v[180:183], v150 offset:3072
	s_add_u32 s22, vcc_lo, 0x40000
	s_addc_u32 s23, vcc_hi, 0
	s_mov_b32 m0, s66
	v_lshl_add_u64 v[238:239], s[22:23], 0, v[140:141]
	ds_read_b128 v[184:187], v205 offset:32768
	ds_read_b128 v[188:191], v205 offset:33792
	ds_read_b128 v[192:195], v205 offset:34816
	ds_read_b128 v[212:215], v205 offset:35840
	ds_read_b128 v[216:219], v205 offset:36864
	ds_read_b128 v[220:223], v205 offset:37888
	ds_read_b128 v[224:227], v205 offset:38912
	ds_read_b128 v[228:231], v205 offset:39936
	global_load_lds_dwordx4 v[238:239], off
	s_mov_b32 m0, s67
	v_lshl_add_u64 v[238:239], s[22:23], 0, v[144:145]
	global_load_lds_dwordx4 v[238:239], off
	s_waitcnt vmcnt(8) lgkmcnt(0)
	s_setprio 1
	s_barrier
	v_mfma_f32_16x16x32_bf16 v[124:127], v[128:131], v[184:187], v[124:127]
	v_mfma_f32_16x16x32_bf16 v[124:127], v[132:135], v[188:191], v[124:127]
	v_mfma_f32_16x16x32_bf16 v[116:119], v[136:139], v[184:187], v[116:119]
	v_mfma_f32_16x16x32_bf16 v[116:119], v[164:167], v[188:191], v[116:119]
	v_mfma_f32_16x16x32_bf16 v[108:111], v[128:131], v[192:195], v[108:111]
	v_mfma_f32_16x16x32_bf16 v[108:111], v[132:135], v[212:215], v[108:111]
	v_mfma_f32_16x16x32_bf16 v[100:103], v[136:139], v[192:195], v[100:103]
	v_mfma_f32_16x16x32_bf16 v[100:103], v[164:167], v[212:215], v[100:103]
	v_mfma_f32_16x16x32_bf16 v[92:95], v[128:131], v[216:219], v[92:95]
	v_mfma_f32_16x16x32_bf16 v[92:95], v[132:135], v[220:223], v[92:95]
	v_mfma_f32_16x16x32_bf16 v[84:87], v[136:139], v[216:219], v[84:87]
	v_mfma_f32_16x16x32_bf16 v[84:87], v[164:167], v[220:223], v[84:87]
	v_mfma_f32_16x16x32_bf16 v[76:79], v[128:131], v[224:227], v[76:79]
	v_mfma_f32_16x16x32_bf16 v[76:79], v[132:135], v[228:231], v[76:79]
	v_mfma_f32_16x16x32_bf16 v[68:71], v[136:139], v[224:227], v[68:71]
	v_mfma_f32_16x16x32_bf16 v[68:71], v[164:167], v[228:231], v[68:71]
	v_mfma_f32_16x16x32_bf16 v[120:123], v[168:171], v[184:187], v[120:123]
	v_mfma_f32_16x16x32_bf16 v[120:123], v[172:175], v[188:191], v[120:123]
	v_mfma_f32_16x16x32_bf16 v[112:115], v[176:179], v[184:187], v[112:115]
	v_mfma_f32_16x16x32_bf16 v[112:115], v[180:183], v[188:191], v[112:115]
	v_mfma_f32_16x16x32_bf16 v[104:107], v[168:171], v[192:195], v[104:107]
	v_mfma_f32_16x16x32_bf16 v[104:107], v[172:175], v[212:215], v[104:107]
	v_mfma_f32_16x16x32_bf16 v[96:99], v[176:179], v[192:195], v[96:99]
	v_mfma_f32_16x16x32_bf16 v[96:99], v[180:183], v[212:215], v[96:99]
	v_mfma_f32_16x16x32_bf16 v[88:91], v[168:171], v[216:219], v[88:91]
	v_mfma_f32_16x16x32_bf16 v[88:91], v[172:175], v[220:223], v[88:91]
	v_mfma_f32_16x16x32_bf16 v[80:83], v[176:179], v[216:219], v[80:83]
	v_mfma_f32_16x16x32_bf16 v[80:83], v[180:183], v[220:223], v[80:83]
	v_mfma_f32_16x16x32_bf16 v[72:75], v[168:171], v[224:227], v[72:75]
	v_mfma_f32_16x16x32_bf16 v[72:75], v[172:175], v[228:231], v[72:75]
	s_setprio 3
	s_barrier
	v_mfma_f32_16x16x32_bf16 v[64:67], v[176:179], v[224:227], v[64:67]
	v_mfma_f32_16x16x32_bf16 v[64:67], v[180:183], v[228:231], v[64:67]
	s_setprio 0
	s_add_i32 s22, s24, s57
	v_lshl_add_u64 v[196:197], v[196:197], 0, s[80:81]
	s_mov_b32 m0, s22
	ds_read_b128 v[184:187], v205 offset:49152
	ds_read_b128 v[188:191], v205 offset:50176
	ds_read_b128 v[192:195], v205 offset:51200
	ds_read_b128 v[212:215], v205 offset:52224
	ds_read_b128 v[216:219], v205 offset:53248
	ds_read_b128 v[220:223], v205 offset:54272
	ds_read_b128 v[224:227], v205 offset:55296
	ds_read_b128 v[228:231], v205 offset:56320
	global_load_lds_dwordx4 v[196:197], off
	s_add_i32 m0, s22, 0x2000
	s_add_u32 s6, s6, 0x40080
	v_lshl_add_u64 v[196:197], v[232:233], 0, s[80:81]
	s_addc_u32 s7, s7, 0
	s_add_i32 s22, s25, s57
	global_load_lds_dwordx4 v[196:197], off
	s_mov_b32 m0, s22
	v_lshl_add_u64 v[196:197], s[6:7], 0, v[142:143]
	global_load_lds_dwordx4 v[196:197], off
	s_add_i32 m0, s22, 0x2000
	v_lshl_add_u64 v[196:197], s[6:7], 0, v[146:147]
	global_load_lds_dwordx4 v[196:197], off
	s_mov_b32 m0, s93
	v_lshl_add_u64 v[196:197], v[234:235], 0, s[80:81]
	global_load_lds_dwordx4 v[196:197], off
	s_mov_b32 m0, s69
	v_lshl_add_u64 v[196:197], v[236:237], 0, s[80:81]
	global_load_lds_dwordx4 v[196:197], off
	s_waitcnt vmcnt(8) lgkmcnt(0)
	s_setprio 1
	s_barrier
	v_mfma_f32_16x16x32_bf16 v[60:63], v[128:131], v[184:187], v[60:63]
	v_mfma_f32_16x16x32_bf16 v[60:63], v[132:135], v[188:191], v[60:63]
	v_mfma_f32_16x16x32_bf16 v[52:55], v[136:139], v[184:187], v[52:55]
	v_mfma_f32_16x16x32_bf16 v[52:55], v[164:167], v[188:191], v[52:55]
	v_mfma_f32_16x16x32_bf16 v[44:47], v[128:131], v[192:195], v[44:47]
	v_mfma_f32_16x16x32_bf16 v[44:47], v[132:135], v[212:215], v[44:47]
	v_mfma_f32_16x16x32_bf16 v[36:39], v[136:139], v[192:195], v[36:39]
	v_mfma_f32_16x16x32_bf16 v[36:39], v[164:167], v[212:215], v[36:39]
	v_mfma_f32_16x16x32_bf16 v[28:31], v[128:131], v[216:219], v[28:31]
	v_mfma_f32_16x16x32_bf16 v[28:31], v[132:135], v[220:223], v[28:31]
	v_mfma_f32_16x16x32_bf16 v[20:23], v[136:139], v[216:219], v[20:23]
	v_mfma_f32_16x16x32_bf16 v[20:23], v[164:167], v[220:223], v[20:23]
	v_mfma_f32_16x16x32_bf16 v[12:15], v[128:131], v[224:227], v[12:15]
	v_mfma_f32_16x16x32_bf16 v[12:15], v[132:135], v[228:231], v[12:15]
	v_mfma_f32_16x16x32_bf16 v[4:7], v[136:139], v[224:227], v[4:7]
	v_mfma_f32_16x16x32_bf16 v[4:7], v[164:167], v[228:231], v[4:7]
	v_mfma_f32_16x16x32_bf16 v[56:59], v[168:171], v[184:187], v[56:59]
	v_mfma_f32_16x16x32_bf16 v[56:59], v[172:175], v[188:191], v[56:59]
	v_mfma_f32_16x16x32_bf16 v[48:51], v[176:179], v[184:187], v[48:51]
	v_mfma_f32_16x16x32_bf16 v[48:51], v[180:183], v[188:191], v[48:51]
	v_mfma_f32_16x16x32_bf16 v[40:43], v[168:171], v[192:195], v[40:43]
	v_mfma_f32_16x16x32_bf16 v[40:43], v[172:175], v[212:215], v[40:43]
	v_mfma_f32_16x16x32_bf16 v[32:35], v[176:179], v[192:195], v[32:35]
	v_mfma_f32_16x16x32_bf16 v[32:35], v[180:183], v[212:215], v[32:35]
	v_mfma_f32_16x16x32_bf16 v[24:27], v[168:171], v[216:219], v[24:27]
	v_mfma_f32_16x16x32_bf16 v[24:27], v[172:175], v[220:223], v[24:27]
	v_mfma_f32_16x16x32_bf16 v[16:19], v[176:179], v[216:219], v[16:19]
	v_mfma_f32_16x16x32_bf16 v[16:19], v[180:183], v[220:223], v[16:19]
	v_mfma_f32_16x16x32_bf16 v[8:11], v[168:171], v[224:227], v[8:11]
	v_mfma_f32_16x16x32_bf16 v[8:11], v[172:175], v[228:231], v[8:11]
	s_setprio 3
	s_barrier
	v_mfma_f32_16x16x32_bf16 v[0:3], v[176:179], v[224:227], v[0:3]
	v_mfma_f32_16x16x32_bf16 v[0:3], v[180:183], v[228:231], v[0:3]
	s_setprio 0
	s_add_i32 s21, s21, 2
	s_add_u32 s88, s88, 0x100
	s_addc_u32 s89, s89, 0
	s_add_u32 s19, s19, 0x100
	s_addc_u32 s20, s20, 0
	s_cmp_gt_u32 s21, 13
	s_cbranch_scc0 .LBB0_429
	s_branch .Lzskip_2
.Lzv_2_0:
	s_barrier
	v_mfma_f32_16x16x32_bf16 v[124:127], v[128:131], v[184:187], 0
	v_mfma_f32_16x16x32_bf16 v[124:127], v[132:135], v[188:191], v[124:127]
	v_mfma_f32_16x16x32_bf16 v[116:119], v[136:139], v[184:187], 0
	v_mfma_f32_16x16x32_bf16 v[116:119], v[164:167], v[188:191], v[116:119]
	v_mfma_f32_16x16x32_bf16 v[108:111], v[128:131], v[192:195], 0
	v_mfma_f32_16x16x32_bf16 v[108:111], v[132:135], v[212:215], v[108:111]
	v_mfma_f32_16x16x32_bf16 v[100:103], v[136:139], v[192:195], 0
	v_mfma_f32_16x16x32_bf16 v[100:103], v[164:167], v[212:215], v[100:103]
	v_mfma_f32_16x16x32_bf16 v[92:95], v[128:131], v[216:219], 0
	v_mfma_f32_16x16x32_bf16 v[92:95], v[132:135], v[220:223], v[92:95]
	v_mfma_f32_16x16x32_bf16 v[84:87], v[136:139], v[216:219], 0
	v_mfma_f32_16x16x32_bf16 v[84:87], v[164:167], v[220:223], v[84:87]
	v_mfma_f32_16x16x32_bf16 v[76:79], v[128:131], v[224:227], 0
	v_mfma_f32_16x16x32_bf16 v[76:79], v[132:135], v[228:231], v[76:79]
	v_mfma_f32_16x16x32_bf16 v[68:71], v[136:139], v[224:227], 0
	v_mfma_f32_16x16x32_bf16 v[68:71], v[164:167], v[228:231], v[68:71]
	v_mfma_f32_16x16x32_bf16 v[120:123], v[168:171], v[184:187], 0
	v_mfma_f32_16x16x32_bf16 v[120:123], v[172:175], v[188:191], v[120:123]
	v_mfma_f32_16x16x32_bf16 v[112:115], v[176:179], v[184:187], 0
	v_mfma_f32_16x16x32_bf16 v[112:115], v[180:183], v[188:191], v[112:115]
	v_mfma_f32_16x16x32_bf16 v[104:107], v[168:171], v[192:195], 0
	v_mfma_f32_16x16x32_bf16 v[104:107], v[172:175], v[212:215], v[104:107]
	v_mfma_f32_16x16x32_bf16 v[96:99], v[176:179], v[192:195], 0
	v_mfma_f32_16x16x32_bf16 v[96:99], v[180:183], v[212:215], v[96:99]
	v_mfma_f32_16x16x32_bf16 v[88:91], v[168:171], v[216:219], 0
	v_mfma_f32_16x16x32_bf16 v[88:91], v[172:175], v[220:223], v[88:91]
	v_mfma_f32_16x16x32_bf16 v[80:83], v[176:179], v[216:219], 0
	v_mfma_f32_16x16x32_bf16 v[80:83], v[180:183], v[220:223], v[80:83]
	v_mfma_f32_16x16x32_bf16 v[72:75], v[168:171], v[224:227], 0
	v_mfma_f32_16x16x32_bf16 v[72:75], v[172:175], v[228:231], v[72:75]
	s_setprio 3
	s_barrier
	v_mfma_f32_16x16x32_bf16 v[64:67], v[176:179], v[224:227], 0
	v_mfma_f32_16x16x32_bf16 v[64:67], v[180:183], v[228:231], v[64:67]
	s_setprio 0
	s_branch .Lzj_2_0
.Lzv_2_1:
	s_barrier
	v_mfma_f32_16x16x32_bf16 v[60:63], v[128:131], v[184:187], 0
	v_mfma_f32_16x16x32_bf16 v[60:63], v[132:135], v[188:191], v[60:63]
	v_mfma_f32_16x16x32_bf16 v[52:55], v[136:139], v[184:187], 0
	v_mfma_f32_16x16x32_bf16 v[52:55], v[164:167], v[188:191], v[52:55]
	v_mfma_f32_16x16x32_bf16 v[44:47], v[128:131], v[192:195], 0
	v_mfma_f32_16x16x32_bf16 v[44:47], v[132:135], v[212:215], v[44:47]
	v_mfma_f32_16x16x32_bf16 v[36:39], v[136:139], v[192:195], 0
	v_mfma_f32_16x16x32_bf16 v[36:39], v[164:167], v[212:215], v[36:39]
	v_mfma_f32_16x16x32_bf16 v[28:31], v[128:131], v[216:219], 0
	v_mfma_f32_16x16x32_bf16 v[28:31], v[132:135], v[220:223], v[28:31]
	v_mfma_f32_16x16x32_bf16 v[20:23], v[136:139], v[216:219], 0
	v_mfma_f32_16x16x32_bf16 v[20:23], v[164:167], v[220:223], v[20:23]
	v_mfma_f32_16x16x32_bf16 v[12:15], v[128:131], v[224:227], 0
	v_mfma_f32_16x16x32_bf16 v[12:15], v[132:135], v[228:231], v[12:15]
	v_mfma_f32_16x16x32_bf16 v[4:7], v[136:139], v[224:227], 0
	v_mfma_f32_16x16x32_bf16 v[4:7], v[164:167], v[228:231], v[4:7]
	v_mfma_f32_16x16x32_bf16 v[56:59], v[168:171], v[184:187], 0
	v_mfma_f32_16x16x32_bf16 v[56:59], v[172:175], v[188:191], v[56:59]
	v_mfma_f32_16x16x32_bf16 v[48:51], v[176:179], v[184:187], 0
	v_mfma_f32_16x16x32_bf16 v[48:51], v[180:183], v[188:191], v[48:51]
	v_mfma_f32_16x16x32_bf16 v[40:43], v[168:171], v[192:195], 0
	v_mfma_f32_16x16x32_bf16 v[40:43], v[172:175], v[212:215], v[40:43]
	v_mfma_f32_16x16x32_bf16 v[32:35], v[176:179], v[192:195], 0
	v_mfma_f32_16x16x32_bf16 v[32:35], v[180:183], v[212:215], v[32:35]
	v_mfma_f32_16x16x32_bf16 v[24:27], v[168:171], v[216:219], 0
	v_mfma_f32_16x16x32_bf16 v[24:27], v[172:175], v[220:223], v[24:27]
	v_mfma_f32_16x16x32_bf16 v[16:19], v[176:179], v[216:219], 0
	v_mfma_f32_16x16x32_bf16 v[16:19], v[180:183], v[220:223], v[16:19]
	v_mfma_f32_16x16x32_bf16 v[8:11], v[168:171], v[224:227], 0
	v_mfma_f32_16x16x32_bf16 v[8:11], v[172:175], v[228:231], v[8:11]
	s_setprio 3
	s_barrier
	v_mfma_f32_16x16x32_bf16 v[0:3], v[176:179], v[224:227], 0
	v_mfma_f32_16x16x32_bf16 v[0:3], v[180:183], v[228:231], v[0:3]
	s_setprio 0
	s_branch .Lzj_2_1

.LBB0_993:
	ds_read_b128 v[120:123], v245
	ds_read_b128 v[124:127], v245 offset:1024
	ds_read_b128 v[128:131], v245 offset:2048
	ds_read_b128 v[132:135], v245 offset:3072
	ds_read_b128 v[144:147], v246
	ds_read_b128 v[148:151], v246 offset:1024
	ds_read_b128 v[152:155], v246 offset:2048
	ds_read_b128 v[156:159], v246 offset:3072
	s_add_u32 s59, s82, 0xfffc0080
	s_addc_u32 s66, s83, -1
	s_cmp_eq_u32 s58, 12
	s_cselect_b32 s87, s53, s66
	s_cselect_b32 s86, s54, s59
	s_cselect_b32 s85, s51, s57
	s_cselect_b32 s84, s55, s56
	v_lshl_add_u64 v[204:205], s[82:83], 0, v[200:201]
	s_add_i32 m0, s16, 0xc000
	ds_read_b128 v[160:163], v247
	ds_read_b128 v[164:167], v247 offset:1024
	ds_read_b128 v[168:171], v247 offset:2048
	ds_read_b128 v[172:175], v247 offset:3072
	ds_read_b128 v[176:179], v247 offset:4096
	ds_read_b128 v[180:183], v247 offset:5120
	ds_read_b128 v[184:187], v247 offset:6144
	ds_read_b128 v[188:191], v247 offset:7168
	global_load_lds_dwordx4 v[204:205], off
	s_add_i32 m0, s16, 0xe000
	v_lshl_add_u64 v[204:205], s[82:83], 0, v[202:203]
	global_load_lds_dwordx4 v[204:205], off
	s_cmp_eq_u32 s58, -2
	s_waitcnt vmcnt(8) lgkmcnt(0)
	s_setprio 1
	s_cbranch_scc1 .Lzv_3_0
	s_barrier
	v_mfma_f32_16x16x32_bf16 v[140:143], v[120:123], v[160:163], v[140:143]
	v_mfma_f32_16x16x32_bf16 v[140:143], v[124:127], v[164:167], v[140:143]
	v_mfma_f32_16x16x32_bf16 v[136:139], v[128:131], v[160:163], v[136:139]
	v_mfma_f32_16x16x32_bf16 v[136:139], v[132:135], v[164:167], v[136:139]
	v_mfma_f32_16x16x32_bf16 v[108:111], v[120:123], v[168:171], v[108:111]
	v_mfma_f32_16x16x32_bf16 v[108:111], v[124:127], v[172:175], v[108:111]
	v_mfma_f32_16x16x32_bf16 v[104:107], v[128:131], v[168:171], v[104:107]
	v_mfma_f32_16x16x32_bf16 v[104:107], v[132:135], v[172:175], v[104:107]
	v_mfma_f32_16x16x32_bf16 v[92:95], v[120:123], v[176:179], v[92:95]
	v_mfma_f32_16x16x32_bf16 v[92:95], v[124:127], v[180:183], v[92:95]
	v_mfma_f32_16x16x32_bf16 v[88:91], v[128:131], v[176:179], v[88:91]
	v_mfma_f32_16x16x32_bf16 v[88:91], v[132:135], v[180:183], v[88:91]
	v_mfma_f32_16x16x32_bf16 v[76:79], v[120:123], v[184:187], v[76:79]
	v_mfma_f32_16x16x32_bf16 v[76:79], v[124:127], v[188:191], v[76:79]
	v_mfma_f32_16x16x32_bf16 v[72:75], v[128:131], v[184:187], v[72:75]
	v_mfma_f32_16x16x32_bf16 v[72:75], v[132:135], v[188:191], v[72:75]
	v_mfma_f32_16x16x32_bf16 v[116:119], v[144:147], v[160:163], v[116:119]
	v_mfma_f32_16x16x32_bf16 v[116:119], v[148:151], v[164:167], v[116:119]
	v_mfma_f32_16x16x32_bf16 v[112:115], v[152:155], v[160:163], v[112:115]
	v_mfma_f32_16x16x32_bf16 v[112:115], v[156:159], v[164:167], v[112:115]
	v_mfma_f32_16x16x32_bf16 v[100:103], v[144:147], v[168:171], v[100:103]
	v_mfma_f32_16x16x32_bf16 v[100:103], v[148:151], v[172:175], v[100:103]
	v_mfma_f32_16x16x32_bf16 v[96:99], v[152:155], v[168:171], v[96:99]
	v_mfma_f32_16x16x32_bf16 v[96:99], v[156:159], v[172:175], v[96:99]
	v_mfma_f32_16x16x32_bf16 v[84:87], v[144:147], v[176:179], v[84:87]
	v_mfma_f32_16x16x32_bf16 v[84:87], v[148:151], v[180:183], v[84:87]
	v_mfma_f32_16x16x32_bf16 v[80:83], v[152:155], v[176:179], v[80:83]
	v_mfma_f32_16x16x32_bf16 v[80:83], v[156:159], v[180:183], v[80:83]
	v_mfma_f32_16x16x32_bf16 v[68:71], v[144:147], v[184:187], v[68:71]
	v_mfma_f32_16x16x32_bf16 v[68:71], v[148:151], v[188:191], v[68:71]
	s_setprio 3
	s_barrier
	v_mfma_f32_16x16x32_bf16 v[64:67], v[152:155], v[184:187], v[64:67]
	v_mfma_f32_16x16x32_bf16 v[64:67], v[156:159], v[188:191], v[64:67]
	s_setprio 0
.Lzj_3_0:
	s_add_i32 s59, s26, s15
	v_lshl_add_u64 v[204:205], s[84:85], 0, v[194:195]
	s_mov_b32 m0, s59
	ds_read_b128 v[160:163], v247 offset:16384
	ds_read_b128 v[164:167], v247 offset:17408
	ds_read_b128 v[168:171], v247 offset:18432
	ds_read_b128 v[172:175], v247 offset:19456
	ds_read_b128 v[176:179], v247 offset:20480
	ds_read_b128 v[180:183], v247 offset:21504
	ds_read_b128 v[184:187], v247 offset:22528
	ds_read_b128 v[188:191], v247 offset:23552
	global_load_lds_dwordx4 v[204:205], off
	s_add_i32 m0, s59, 0x2000
	s_add_u32 s66, s84, 0x40000
	v_lshl_add_u64 v[206:207], s[84:85], 0, v[198:199]
	s_addc_u32 s67, s85, 0
	s_add_i32 s59, s27, s15
	global_load_lds_dwordx4 v[206:207], off
	v_lshl_add_u64 v[208:209], s[66:67], 0, v[194:195]
	s_mov_b32 m0, s59
	global_load_lds_dwordx4 v[208:209], off
	s_add_i32 m0, s59, 0x2000
	v_lshl_add_u64 v[208:209], s[66:67], 0, v[198:199]
	global_load_lds_dwordx4 v[208:209], off
	s_mov_b32 m0, s16
	v_lshl_add_u64 v[208:209], s[86:87], 0, v[192:193]
	global_load_lds_dwordx4 v[208:209], off
	s_mov_b32 m0, s17
	v_lshl_add_u64 v[210:211], s[86:87], 0, v[196:197]
	global_load_lds_dwordx4 v[210:211], off
	s_cmp_eq_u32 s58, -2
	s_waitcnt vmcnt(8) lgkmcnt(0)
	s_setprio 1
	s_cbranch_scc1 .Lzv_3_1
	s_barrier
	v_mfma_f32_16x16x32_bf16 v[60:63], v[120:123], v[160:163], v[60:63]
	v_mfma_f32_16x16x32_bf16 v[60:63], v[124:127], v[164:167], v[60:63]
	v_mfma_f32_16x16x32_bf16 v[56:59], v[128:131], v[160:163], v[56:59]
	v_mfma_f32_16x16x32_bf16 v[56:59], v[132:135], v[164:167], v[56:59]
	v_mfma_f32_16x16x32_bf16 v[44:47], v[120:123], v[168:171], v[44:47]
	v_mfma_f32_16x16x32_bf16 v[44:47], v[124:127], v[172:175], v[44:47]
	v_mfma_f32_16x16x32_bf16 v[40:43], v[128:131], v[168:171], v[40:43]
	v_mfma_f32_16x16x32_bf16 v[40:43], v[132:135], v[172:175], v[40:43]
	v_mfma_f32_16x16x32_bf16 v[28:31], v[120:123], v[176:179], v[28:31]
	v_mfma_f32_16x16x32_bf16 v[28:31], v[124:127], v[180:183], v[28:31]
	v_mfma_f32_16x16x32_bf16 v[24:27], v[128:131], v[176:179], v[24:27]
	v_mfma_f32_16x16x32_bf16 v[24:27], v[132:135], v[180:183], v[24:27]
	v_mfma_f32_16x16x32_bf16 v[12:15], v[120:123], v[184:187], v[12:15]
	v_mfma_f32_16x16x32_bf16 v[12:15], v[124:127], v[188:191], v[12:15]
	v_mfma_f32_16x16x32_bf16 v[8:11], v[128:131], v[184:187], v[8:11]
	v_mfma_f32_16x16x32_bf16 v[8:11], v[132:135], v[188:191], v[8:11]
	v_mfma_f32_16x16x32_bf16 v[52:55], v[144:147], v[160:163], v[52:55]
	v_mfma_f32_16x16x32_bf16 v[52:55], v[148:151], v[164:167], v[52:55]
	v_mfma_f32_16x16x32_bf16 v[48:51], v[152:155], v[160:163], v[48:51]
	v_mfma_f32_16x16x32_bf16 v[48:51], v[156:159], v[164:167], v[48:51]
	v_mfma_f32_16x16x32_bf16 v[36:39], v[144:147], v[168:171], v[36:39]
	v_mfma_f32_16x16x32_bf16 v[36:39], v[148:151], v[172:175], v[36:39]
	v_mfma_f32_16x16x32_bf16 v[32:35], v[152:155], v[168:171], v[32:35]
	v_mfma_f32_16x16x32_bf16 v[32:35], v[156:159], v[172:175], v[32:35]
	v_mfma_f32_16x16x32_bf16 v[20:23], v[144:147], v[176:179], v[20:23]
	v_mfma_f32_16x16x32_bf16 v[20:23], v[148:151], v[180:183], v[20:23]
	v_mfma_f32_16x16x32_bf16 v[16:19], v[152:155], v[176:179], v[16:19]
	v_mfma_f32_16x16x32_bf16 v[16:19], v[156:159], v[180:183], v[16:19]
	v_mfma_f32_16x16x32_bf16 v[4:7], v[144:147], v[184:187], v[4:7]
	v_mfma_f32_16x16x32_bf16 v[4:7], v[148:151], v[188:191], v[4:7]
	s_setprio 3
	s_barrier
	v_mfma_f32_16x16x32_bf16 v[0:3], v[152:155], v[184:187], v[0:3]
	v_mfma_f32_16x16x32_bf16 v[0:3], v[156:159], v[188:191], v[0:3]
	s_setprio 0
.Lzj_3_1:
	s_add_i32 s59, 0, 0x18000
	s_add_i32 s68, 0, 0x1c000
	v_add_u32_e32 v132, s59, v243
	v_add_u32_e32 v156, s68, v243
	ds_read_b128 v[120:123], v132
	ds_read_b128 v[124:127], v132 offset:1024
	ds_read_b128 v[128:131], v132 offset:2048
	ds_read_b128 v[132:135], v132 offset:3072
	ds_read_b128 v[144:147], v156
	ds_read_b128 v[148:151], v156 offset:1024
	ds_read_b128 v[152:155], v156 offset:2048
	ds_read_b128 v[156:159], v156 offset:3072
	s_add_u32 s66, s86, 0x40000
	s_addc_u32 s67, s87, 0
	s_mov_b32 m0, s18
	v_lshl_add_u64 v[212:213], s[66:67], 0, v[192:193]
	ds_read_b128 v[160:163], v247 offset:32768
	ds_read_b128 v[164:167], v247 offset:33792
	ds_read_b128 v[168:171], v247 offset:34816
	ds_read_b128 v[172:175], v247 offset:35840
	ds_read_b128 v[176:179], v247 offset:36864
	ds_read_b128 v[180:183], v247 offset:37888
	ds_read_b128 v[184:187], v247 offset:38912
	ds_read_b128 v[188:191], v247 offset:39936
	global_load_lds_dwordx4 v[212:213], off
	s_mov_b32 m0, s19
	v_lshl_add_u64 v[212:213], s[66:67], 0, v[196:197]
	global_load_lds_dwordx4 v[212:213], off
	s_waitcnt vmcnt(8) lgkmcnt(0)
	s_setprio 1
	s_barrier
	v_mfma_f32_16x16x32_bf16 v[140:143], v[120:123], v[160:163], v[140:143]
	v_mfma_f32_16x16x32_bf16 v[140:143], v[124:127], v[164:167], v[140:143]
	v_mfma_f32_16x16x32_bf16 v[136:139], v[128:131], v[160:163], v[136:139]
	v_mfma_f32_16x16x32_bf16 v[136:139], v[132:135], v[164:167], v[136:139]
	v_mfma_f32_16x16x32_bf16 v[108:111], v[120:123], v[168:171], v[108:111]
	v_mfma_f32_16x16x32_bf16 v[108:111], v[124:127], v[172:175], v[108:111]
	v_mfma_f32_16x16x32_bf16 v[104:107], v[128:131], v[168:171], v[104:107]
	v_mfma_f32_16x16x32_bf16 v[104:107], v[132:135], v[172:175], v[104:107]
	v_mfma_f32_16x16x32_bf16 v[92:95], v[120:123], v[176:179], v[92:95]
	v_mfma_f32_16x16x32_bf16 v[92:95], v[124:127], v[180:183], v[92:95]
	v_mfma_f32_16x16x32_bf16 v[88:91], v[128:131], v[176:179], v[88:91]
	v_mfma_f32_16x16x32_bf16 v[88:91], v[132:135], v[180:183], v[88:91]
	v_mfma_f32_16x16x32_bf16 v[76:79], v[120:123], v[184:187], v[76:79]
	v_mfma_f32_16x16x32_bf16 v[76:79], v[124:127], v[188:191], v[76:79]
	v_mfma_f32_16x16x32_bf16 v[72:75], v[128:131], v[184:187], v[72:75]
	v_mfma_f32_16x16x32_bf16 v[72:75], v[132:135], v[188:191], v[72:75]
	v_mfma_f32_16x16x32_bf16 v[116:119], v[144:147], v[160:163], v[116:119]
	v_mfma_f32_16x16x32_bf16 v[116:119], v[148:151], v[164:167], v[116:119]
	v_mfma_f32_16x16x32_bf16 v[112:115], v[152:155], v[160:163], v[112:115]
	v_mfma_f32_16x16x32_bf16 v[112:115], v[156:159], v[164:167], v[112:115]
	v_mfma_f32_16x16x32_bf16 v[100:103], v[144:147], v[168:171], v[100:103]
	v_mfma_f32_16x16x32_bf16 v[100:103], v[148:151], v[172:175], v[100:103]
	v_mfma_f32_16x16x32_bf16 v[96:99], v[152:155], v[168:171], v[96:99]
	v_mfma_f32_16x16x32_bf16 v[96:99], v[156:159], v[172:175], v[96:99]
	v_mfma_f32_16x16x32_bf16 v[84:87], v[144:147], v[176:179], v[84:87]
	v_mfma_f32_16x16x32_bf16 v[84:87], v[148:151], v[180:183], v[84:87]
	v_mfma_f32_16x16x32_bf16 v[80:83], v[152:155], v[176:179], v[80:83]
	v_mfma_f32_16x16x32_bf16 v[80:83], v[156:159], v[180:183], v[80:83]
	v_mfma_f32_16x16x32_bf16 v[68:71], v[144:147], v[184:187], v[68:71]
	v_mfma_f32_16x16x32_bf16 v[68:71], v[148:151], v[188:191], v[68:71]
	s_setprio 3
	s_barrier
	v_mfma_f32_16x16x32_bf16 v[64:67], v[152:155], v[184:187], v[64:67]
	v_mfma_f32_16x16x32_bf16 v[64:67], v[156:159], v[188:191], v[64:67]
	s_setprio 0
	s_add_i32 s59, s59, s15
	v_lshl_add_u64 v[204:205], v[204:205], 0, s[46:47]
	s_mov_b32 m0, s59
	ds_read_b128 v[160:163], v247 offset:49152
	ds_read_b128 v[164:167], v247 offset:50176
	ds_read_b128 v[168:171], v247 offset:51200
	ds_read_b128 v[172:175], v247 offset:52224
	ds_read_b128 v[176:179], v247 offset:53248
	ds_read_b128 v[180:183], v247 offset:54272
	ds_read_b128 v[184:187], v247 offset:55296
	ds_read_b128 v[188:191], v247 offset:56320
	global_load_lds_dwordx4 v[204:205], off
	s_add_i32 m0, s59, 0x2000
	s_add_u32 s66, s84, 0x40080
	v_lshl_add_u64 v[204:205], v[206:207], 0, s[46:47]
	s_addc_u32 s67, s85, 0
	s_add_i32 s59, s68, s15
	global_load_lds_dwordx4 v[204:205], off
	s_mov_b32 m0, s59
	v_lshl_add_u64 v[204:205], s[66:67], 0, v[194:195]
	global_load_lds_dwordx4 v[204:205], off
	s_add_i32 m0, s59, 0x2000
	v_lshl_add_u64 v[204:205], s[66:67], 0, v[198:199]
	global_load_lds_dwordx4 v[204:205], off
	s_mov_b32 m0, s21
	v_lshl_add_u64 v[204:205], v[208:209], 0, s[46:47]
	global_load_lds_dwordx4 v[204:205], off
	s_mov_b32 m0, s22
	v_lshl_add_u64 v[204:205], v[210:211], 0, s[46:47]
	global_load_lds_dwordx4 v[204:205], off
	s_waitcnt vmcnt(8) lgkmcnt(0)
	s_setprio 1
	s_barrier
	v_mfma_f32_16x16x32_bf16 v[60:63], v[120:123], v[160:163], v[60:63]
	v_mfma_f32_16x16x32_bf16 v[60:63], v[124:127], v[164:167], v[60:63]
	v_mfma_f32_16x16x32_bf16 v[56:59], v[128:131], v[160:163], v[56:59]
	v_mfma_f32_16x16x32_bf16 v[56:59], v[132:135], v[164:167], v[56:59]
	v_mfma_f32_16x16x32_bf16 v[44:47], v[120:123], v[168:171], v[44:47]
	v_mfma_f32_16x16x32_bf16 v[44:47], v[124:127], v[172:175], v[44:47]
	v_mfma_f32_16x16x32_bf16 v[40:43], v[128:131], v[168:171], v[40:43]
	v_mfma_f32_16x16x32_bf16 v[40:43], v[132:135], v[172:175], v[40:43]
	v_mfma_f32_16x16x32_bf16 v[28:31], v[120:123], v[176:179], v[28:31]
	v_mfma_f32_16x16x32_bf16 v[28:31], v[124:127], v[180:183], v[28:31]
	v_mfma_f32_16x16x32_bf16 v[24:27], v[128:131], v[176:179], v[24:27]
	v_mfma_f32_16x16x32_bf16 v[24:27], v[132:135], v[180:183], v[24:27]
	v_mfma_f32_16x16x32_bf16 v[12:15], v[120:123], v[184:187], v[12:15]
	v_mfma_f32_16x16x32_bf16 v[12:15], v[124:127], v[188:191], v[12:15]
	v_mfma_f32_16x16x32_bf16 v[8:11], v[128:131], v[184:187], v[8:11]
	v_mfma_f32_16x16x32_bf16 v[8:11], v[132:135], v[188:191], v[8:11]
	v_mfma_f32_16x16x32_bf16 v[52:55], v[144:147], v[160:163], v[52:55]
	v_mfma_f32_16x16x32_bf16 v[52:55], v[148:151], v[164:167], v[52:55]
	v_mfma_f32_16x16x32_bf16 v[48:51], v[152:155], v[160:163], v[48:51]
	v_mfma_f32_16x16x32_bf16 v[48:51], v[156:159], v[164:167], v[48:51]
	v_mfma_f32_16x16x32_bf16 v[36:39], v[144:147], v[168:171], v[36:39]
	v_mfma_f32_16x16x32_bf16 v[36:39], v[148:151], v[172:175], v[36:39]
	v_mfma_f32_16x16x32_bf16 v[32:35], v[152:155], v[168:171], v[32:35]
	v_mfma_f32_16x16x32_bf16 v[32:35], v[156:159], v[172:175], v[32:35]
	v_mfma_f32_16x16x32_bf16 v[20:23], v[144:147], v[176:179], v[20:23]
	v_mfma_f32_16x16x32_bf16 v[20:23], v[148:151], v[180:183], v[20:23]
	v_mfma_f32_16x16x32_bf16 v[16:19], v[152:155], v[176:179], v[16:19]
	v_mfma_f32_16x16x32_bf16 v[16:19], v[156:159], v[180:183], v[16:19]
	v_mfma_f32_16x16x32_bf16 v[4:7], v[144:147], v[184:187], v[4:7]
	v_mfma_f32_16x16x32_bf16 v[4:7], v[148:151], v[188:191], v[4:7]
	s_setprio 3
	s_barrier
	v_mfma_f32_16x16x32_bf16 v[0:3], v[152:155], v[184:187], v[0:3]
	v_mfma_f32_16x16x32_bf16 v[0:3], v[156:159], v[188:191], v[0:3]
	s_setprio 0
	s_add_i32 s58, s58, 2
	s_add_u32 s82, s82, 0x100
	s_addc_u32 s83, s83, 0
	s_add_u32 s56, s56, 0x100
	s_addc_u32 s57, s57, 0
	s_cmp_gt_u32 s58, 13
	s_cbranch_scc0 .LBB0_993
	s_branch .Lzskip_3

.LBB0_1148:
	ds_read_b128 v[146:149], v174
	ds_read_b128 v[150:153], v174 offset:1024
	ds_read_b128 v[154:157], v174 offset:2048
	ds_read_b128 v[158:161], v174 offset:3072
	ds_read_b128 v[162:165], v175
	ds_read_b128 v[178:181], v175 offset:1024
	ds_read_b128 v[182:185], v175 offset:2048
	ds_read_b128 v[186:189], v175 offset:3072
	s_add_u32 s67, s78, 0xfffc0080
	s_addc_u32 s68, s79, -1
	s_cmp_eq_u32 s66, 12
	s_cselect_b32 s83, s49, s68
	s_cselect_b32 s82, s54, s67
	s_cselect_b32 s81, s47, s59
	s_cselect_b32 s80, s55, s58
	v_lshl_add_u64 v[166:167], s[78:79], 0, v[136:137]
	s_add_i32 m0, s17, 0xc000
	ds_read_b128 v[190:193], v176
	ds_read_b128 v[194:197], v176 offset:1024
	ds_read_b128 v[198:201], v176 offset:2048
	ds_read_b128 v[202:205], v176 offset:3072
	ds_read_b128 v[206:209], v176 offset:4096
	ds_read_b128 v[210:213], v176 offset:5120
	ds_read_b128 v[214:217], v176 offset:6144
	ds_read_b128 v[218:221], v176 offset:7168
	global_load_lds_dwordx4 v[166:167], off
	s_add_i32 m0, s17, 0xe000
	v_lshl_add_u64 v[166:167], s[78:79], 0, v[140:141]
	global_load_lds_dwordx4 v[166:167], off
	s_cmp_eq_u32 s66, -2
	s_waitcnt vmcnt(8) lgkmcnt(0)
	s_setprio 1
	s_cbranch_scc1 .Lzv_4_0
	s_barrier
	v_mfma_f32_16x16x32_bf16 v[124:127], v[146:149], v[190:193], v[124:127]
	v_mfma_f32_16x16x32_bf16 v[124:127], v[150:153], v[194:197], v[124:127]
	v_mfma_f32_16x16x32_bf16 v[116:119], v[154:157], v[190:193], v[116:119]
	v_mfma_f32_16x16x32_bf16 v[116:119], v[158:161], v[194:197], v[116:119]
	v_mfma_f32_16x16x32_bf16 v[108:111], v[146:149], v[198:201], v[108:111]
	v_mfma_f32_16x16x32_bf16 v[108:111], v[150:153], v[202:205], v[108:111]
	v_mfma_f32_16x16x32_bf16 v[100:103], v[154:157], v[198:201], v[100:103]
	v_mfma_f32_16x16x32_bf16 v[100:103], v[158:161], v[202:205], v[100:103]
	v_mfma_f32_16x16x32_bf16 v[92:95], v[146:149], v[206:209], v[92:95]
	v_mfma_f32_16x16x32_bf16 v[92:95], v[150:153], v[210:213], v[92:95]
	v_mfma_f32_16x16x32_bf16 v[84:87], v[154:157], v[206:209], v[84:87]
	v_mfma_f32_16x16x32_bf16 v[84:87], v[158:161], v[210:213], v[84:87]
	v_mfma_f32_16x16x32_bf16 v[76:79], v[146:149], v[214:217], v[76:79]
	v_mfma_f32_16x16x32_bf16 v[76:79], v[150:153], v[218:221], v[76:79]
	v_mfma_f32_16x16x32_bf16 v[68:71], v[154:157], v[214:217], v[68:71]
	v_mfma_f32_16x16x32_bf16 v[68:71], v[158:161], v[218:221], v[68:71]
	v_mfma_f32_16x16x32_bf16 v[120:123], v[162:165], v[190:193], v[120:123]
	v_mfma_f32_16x16x32_bf16 v[120:123], v[178:181], v[194:197], v[120:123]
	v_mfma_f32_16x16x32_bf16 v[112:115], v[182:185], v[190:193], v[112:115]
	v_mfma_f32_16x16x32_bf16 v[112:115], v[186:189], v[194:197], v[112:115]
	v_mfma_f32_16x16x32_bf16 v[104:107], v[162:165], v[198:201], v[104:107]
	v_mfma_f32_16x16x32_bf16 v[104:107], v[178:181], v[202:205], v[104:107]
	v_mfma_f32_16x16x32_bf16 v[96:99], v[182:185], v[198:201], v[96:99]
	v_mfma_f32_16x16x32_bf16 v[96:99], v[186:189], v[202:205], v[96:99]
	v_mfma_f32_16x16x32_bf16 v[88:91], v[162:165], v[206:209], v[88:91]
	v_mfma_f32_16x16x32_bf16 v[88:91], v[178:181], v[210:213], v[88:91]
	v_mfma_f32_16x16x32_bf16 v[80:83], v[182:185], v[206:209], v[80:83]
	v_mfma_f32_16x16x32_bf16 v[80:83], v[186:189], v[210:213], v[80:83]
	v_mfma_f32_16x16x32_bf16 v[72:75], v[162:165], v[214:217], v[72:75]
	v_mfma_f32_16x16x32_bf16 v[72:75], v[178:181], v[218:221], v[72:75]
	s_setprio 3
	s_barrier
	v_mfma_f32_16x16x32_bf16 v[64:67], v[182:185], v[214:217], v[64:67]
	v_mfma_f32_16x16x32_bf16 v[64:67], v[186:189], v[218:221], v[64:67]
	s_setprio 0
.Lzj_4_0:
	s_add_i32 s67, s25, s16
	v_lshl_add_u64 v[166:167], s[80:81], 0, v[132:133]
	s_mov_b32 m0, s67
	ds_read_b128 v[190:193], v176 offset:16384
	ds_read_b128 v[194:197], v176 offset:17408
	ds_read_b128 v[198:201], v176 offset:18432
	ds_read_b128 v[202:205], v176 offset:19456
	ds_read_b128 v[206:209], v176 offset:20480
	ds_read_b128 v[210:213], v176 offset:21504
	ds_read_b128 v[214:217], v176 offset:22528
	ds_read_b128 v[218:221], v176 offset:23552
	global_load_lds_dwordx4 v[166:167], off
	s_add_i32 m0, s67, 0x2000
	s_add_u32 s68, s80, 0x40000
	v_lshl_add_u64 v[222:223], s[80:81], 0, v[128:129]
	s_addc_u32 s69, s81, 0
	s_add_i32 s67, s26, s16
	global_load_lds_dwordx4 v[222:223], off
	v_lshl_add_u64 v[224:225], s[68:69], 0, v[132:133]
	s_mov_b32 m0, s67
	global_load_lds_dwordx4 v[224:225], off
	s_add_i32 m0, s67, 0x2000
	v_lshl_add_u64 v[224:225], s[68:69], 0, v[128:129]
	global_load_lds_dwordx4 v[224:225], off
	s_mov_b32 m0, s17
	v_lshl_add_u64 v[224:225], s[82:83], 0, v[134:135]
	global_load_lds_dwordx4 v[224:225], off
	s_mov_b32 m0, s18
	v_lshl_add_u64 v[226:227], s[82:83], 0, v[130:131]
	global_load_lds_dwordx4 v[226:227], off
	s_cmp_eq_u32 s66, -2
	s_waitcnt vmcnt(8) lgkmcnt(0)
	s_setprio 1
	s_cbranch_scc1 .Lzv_4_1
	s_barrier
	v_mfma_f32_16x16x32_bf16 v[60:63], v[146:149], v[190:193], v[60:63]
	v_mfma_f32_16x16x32_bf16 v[60:63], v[150:153], v[194:197], v[60:63]
	v_mfma_f32_16x16x32_bf16 v[52:55], v[154:157], v[190:193], v[52:55]
	v_mfma_f32_16x16x32_bf16 v[52:55], v[158:161], v[194:197], v[52:55]
	v_mfma_f32_16x16x32_bf16 v[44:47], v[146:149], v[198:201], v[44:47]
	v_mfma_f32_16x16x32_bf16 v[44:47], v[150:153], v[202:205], v[44:47]
	v_mfma_f32_16x16x32_bf16 v[36:39], v[154:157], v[198:201], v[36:39]
	v_mfma_f32_16x16x32_bf16 v[36:39], v[158:161], v[202:205], v[36:39]
	v_mfma_f32_16x16x32_bf16 v[28:31], v[146:149], v[206:209], v[28:31]
	v_mfma_f32_16x16x32_bf16 v[28:31], v[150:153], v[210:213], v[28:31]
	v_mfma_f32_16x16x32_bf16 v[20:23], v[154:157], v[206:209], v[20:23]
	v_mfma_f32_16x16x32_bf16 v[20:23], v[158:161], v[210:213], v[20:23]
	v_mfma_f32_16x16x32_bf16 v[12:15], v[146:149], v[214:217], v[12:15]
	v_mfma_f32_16x16x32_bf16 v[12:15], v[150:153], v[218:221], v[12:15]
	v_mfma_f32_16x16x32_bf16 v[4:7], v[154:157], v[214:217], v[4:7]
	v_mfma_f32_16x16x32_bf16 v[4:7], v[158:161], v[218:221], v[4:7]
	v_mfma_f32_16x16x32_bf16 v[56:59], v[162:165], v[190:193], v[56:59]
	v_mfma_f32_16x16x32_bf16 v[56:59], v[178:181], v[194:197], v[56:59]
	v_mfma_f32_16x16x32_bf16 v[48:51], v[182:185], v[190:193], v[48:51]
	v_mfma_f32_16x16x32_bf16 v[48:51], v[186:189], v[194:197], v[48:51]
	v_mfma_f32_16x16x32_bf16 v[40:43], v[162:165], v[198:201], v[40:43]
	v_mfma_f32_16x16x32_bf16 v[40:43], v[178:181], v[202:205], v[40:43]
	v_mfma_f32_16x16x32_bf16 v[32:35], v[182:185], v[198:201], v[32:35]
	v_mfma_f32_16x16x32_bf16 v[32:35], v[186:189], v[202:205], v[32:35]
	v_mfma_f32_16x16x32_bf16 v[24:27], v[162:165], v[206:209], v[24:27]
	v_mfma_f32_16x16x32_bf16 v[24:27], v[178:181], v[210:213], v[24:27]
	v_mfma_f32_16x16x32_bf16 v[16:19], v[182:185], v[206:209], v[16:19]
	v_mfma_f32_16x16x32_bf16 v[16:19], v[186:189], v[210:213], v[16:19]
	v_mfma_f32_16x16x32_bf16 v[8:11], v[162:165], v[214:217], v[8:11]
	v_mfma_f32_16x16x32_bf16 v[8:11], v[178:181], v[218:221], v[8:11]
	s_setprio 3
	s_barrier
	v_mfma_f32_16x16x32_bf16 v[0:3], v[182:185], v[214:217], v[0:3]
	v_mfma_f32_16x16x32_bf16 v[0:3], v[186:189], v[218:221], v[0:3]
	s_setprio 0
.Lzj_4_1:
	s_add_i32 s67, 0, 0x18000
	s_add_i32 s73, 0, 0x1c000
	v_add_u32_e32 v158, s67, v171
	v_add_u32_e32 v186, s73, v171
	ds_read_b128 v[146:149], v158
	ds_read_b128 v[150:153], v158 offset:1024
	ds_read_b128 v[154:157], v158 offset:2048
	ds_read_b128 v[158:161], v158 offset:3072
	ds_read_b128 v[162:165], v186
	ds_read_b128 v[178:181], v186 offset:1024
	ds_read_b128 v[182:185], v186 offset:2048
	ds_read_b128 v[186:189], v186 offset:3072
	s_add_u32 s68, s82, 0x40000
	s_addc_u32 s69, s83, 0
	s_mov_b32 m0, s19
	v_lshl_add_u64 v[228:229], s[68:69], 0, v[134:135]
	ds_read_b128 v[190:193], v176 offset:32768
	ds_read_b128 v[194:197], v176 offset:33792
	ds_read_b128 v[198:201], v176 offset:34816
	ds_read_b128 v[202:205], v176 offset:35840
	ds_read_b128 v[206:209], v176 offset:36864
	ds_read_b128 v[210:213], v176 offset:37888
	ds_read_b128 v[214:217], v176 offset:38912
	ds_read_b128 v[218:221], v176 offset:39936
	global_load_lds_dwordx4 v[228:229], off
	s_mov_b32 m0, s20
	v_lshl_add_u64 v[228:229], s[68:69], 0, v[130:131]
	global_load_lds_dwordx4 v[228:229], off
	s_waitcnt vmcnt(8) lgkmcnt(0)
	s_setprio 1
	s_barrier
	v_mfma_f32_16x16x32_bf16 v[124:127], v[146:149], v[190:193], v[124:127]
	v_mfma_f32_16x16x32_bf16 v[124:127], v[150:153], v[194:197], v[124:127]
	v_mfma_f32_16x16x32_bf16 v[116:119], v[154:157], v[190:193], v[116:119]
	v_mfma_f32_16x16x32_bf16 v[116:119], v[158:161], v[194:197], v[116:119]
	v_mfma_f32_16x16x32_bf16 v[108:111], v[146:149], v[198:201], v[108:111]
	v_mfma_f32_16x16x32_bf16 v[108:111], v[150:153], v[202:205], v[108:111]
	v_mfma_f32_16x16x32_bf16 v[100:103], v[154:157], v[198:201], v[100:103]
	v_mfma_f32_16x16x32_bf16 v[100:103], v[158:161], v[202:205], v[100:103]
	v_mfma_f32_16x16x32_bf16 v[92:95], v[146:149], v[206:209], v[92:95]
	v_mfma_f32_16x16x32_bf16 v[92:95], v[150:153], v[210:213], v[92:95]
	v_mfma_f32_16x16x32_bf16 v[84:87], v[154:157], v[206:209], v[84:87]
	v_mfma_f32_16x16x32_bf16 v[84:87], v[158:161], v[210:213], v[84:87]
	v_mfma_f32_16x16x32_bf16 v[76:79], v[146:149], v[214:217], v[76:79]
	v_mfma_f32_16x16x32_bf16 v[76:79], v[150:153], v[218:221], v[76:79]
	v_mfma_f32_16x16x32_bf16 v[68:71], v[154:157], v[214:217], v[68:71]
	v_mfma_f32_16x16x32_bf16 v[68:71], v[158:161], v[218:221], v[68:71]
	v_mfma_f32_16x16x32_bf16 v[120:123], v[162:165], v[190:193], v[120:123]
	v_mfma_f32_16x16x32_bf16 v[120:123], v[178:181], v[194:197], v[120:123]
	v_mfma_f32_16x16x32_bf16 v[112:115], v[182:185], v[190:193], v[112:115]
	v_mfma_f32_16x16x32_bf16 v[112:115], v[186:189], v[194:197], v[112:115]
	v_mfma_f32_16x16x32_bf16 v[104:107], v[162:165], v[198:201], v[104:107]
	v_mfma_f32_16x16x32_bf16 v[104:107], v[178:181], v[202:205], v[104:107]
	v_mfma_f32_16x16x32_bf16 v[96:99], v[182:185], v[198:201], v[96:99]
	v_mfma_f32_16x16x32_bf16 v[96:99], v[186:189], v[202:205], v[96:99]
	v_mfma_f32_16x16x32_bf16 v[88:91], v[162:165], v[206:209], v[88:91]
	v_mfma_f32_16x16x32_bf16 v[88:91], v[178:181], v[210:213], v[88:91]
	v_mfma_f32_16x16x32_bf16 v[80:83], v[182:185], v[206:209], v[80:83]
	v_mfma_f32_16x16x32_bf16 v[80:83], v[186:189], v[210:213], v[80:83]
	v_mfma_f32_16x16x32_bf16 v[72:75], v[162:165], v[214:217], v[72:75]
	v_mfma_f32_16x16x32_bf16 v[72:75], v[178:181], v[218:221], v[72:75]
	s_setprio 3
	s_barrier
	v_mfma_f32_16x16x32_bf16 v[64:67], v[182:185], v[214:217], v[64:67]
	v_mfma_f32_16x16x32_bf16 v[64:67], v[186:189], v[218:221], v[64:67]
	s_setprio 0
	s_add_i32 s67, s67, s16
	v_lshl_add_u64 v[166:167], v[166:167], 0, s[10:11]
	s_mov_b32 m0, s67
	ds_read_b128 v[190:193], v176 offset:49152
	ds_read_b128 v[194:197], v176 offset:50176
	ds_read_b128 v[198:201], v176 offset:51200
	ds_read_b128 v[202:205], v176 offset:52224
	ds_read_b128 v[206:209], v176 offset:53248
	ds_read_b128 v[210:213], v176 offset:54272
	ds_read_b128 v[214:217], v176 offset:55296
	ds_read_b128 v[218:221], v176 offset:56320
	global_load_lds_dwordx4 v[166:167], off
	s_add_i32 m0, s67, 0x2000
	s_add_u32 s68, s80, 0x40080
	v_lshl_add_u64 v[166:167], v[222:223], 0, s[10:11]
	s_addc_u32 s69, s81, 0
	s_add_i32 s67, s73, s16
	global_load_lds_dwordx4 v[166:167], off
	s_mov_b32 m0, s67
	v_lshl_add_u64 v[166:167], s[68:69], 0, v[132:133]
	global_load_lds_dwordx4 v[166:167], off
	s_add_i32 m0, s67, 0x2000
	v_lshl_add_u64 v[166:167], s[68:69], 0, v[128:129]
	global_load_lds_dwordx4 v[166:167], off
	s_mov_b32 m0, s23
	v_lshl_add_u64 v[166:167], v[224:225], 0, s[10:11]
	global_load_lds_dwordx4 v[166:167], off
	s_mov_b32 m0, s24
	v_lshl_add_u64 v[166:167], v[226:227], 0, s[10:11]
	global_load_lds_dwordx4 v[166:167], off
	s_waitcnt vmcnt(8) lgkmcnt(0)
	s_setprio 1
	s_barrier
	v_mfma_f32_16x16x32_bf16 v[60:63], v[146:149], v[190:193], v[60:63]
	v_mfma_f32_16x16x32_bf16 v[60:63], v[150:153], v[194:197], v[60:63]
	v_mfma_f32_16x16x32_bf16 v[52:55], v[154:157], v[190:193], v[52:55]
	v_mfma_f32_16x16x32_bf16 v[52:55], v[158:161], v[194:197], v[52:55]
	v_mfma_f32_16x16x32_bf16 v[44:47], v[146:149], v[198:201], v[44:47]
	v_mfma_f32_16x16x32_bf16 v[44:47], v[150:153], v[202:205], v[44:47]
	v_mfma_f32_16x16x32_bf16 v[36:39], v[154:157], v[198:201], v[36:39]
	v_mfma_f32_16x16x32_bf16 v[36:39], v[158:161], v[202:205], v[36:39]
	v_mfma_f32_16x16x32_bf16 v[28:31], v[146:149], v[206:209], v[28:31]
	v_mfma_f32_16x16x32_bf16 v[28:31], v[150:153], v[210:213], v[28:31]
	v_mfma_f32_16x16x32_bf16 v[20:23], v[154:157], v[206:209], v[20:23]
	v_mfma_f32_16x16x32_bf16 v[20:23], v[158:161], v[210:213], v[20:23]
	v_mfma_f32_16x16x32_bf16 v[12:15], v[146:149], v[214:217], v[12:15]
	v_mfma_f32_16x16x32_bf16 v[12:15], v[150:153], v[218:221], v[12:15]
	v_mfma_f32_16x16x32_bf16 v[4:7], v[154:157], v[214:217], v[4:7]
	v_mfma_f32_16x16x32_bf16 v[4:7], v[158:161], v[218:221], v[4:7]
	v_mfma_f32_16x16x32_bf16 v[56:59], v[162:165], v[190:193], v[56:59]
	v_mfma_f32_16x16x32_bf16 v[56:59], v[178:181], v[194:197], v[56:59]
	v_mfma_f32_16x16x32_bf16 v[48:51], v[182:185], v[190:193], v[48:51]
	v_mfma_f32_16x16x32_bf16 v[48:51], v[186:189], v[194:197], v[48:51]
	v_mfma_f32_16x16x32_bf16 v[40:43], v[162:165], v[198:201], v[40:43]
	v_mfma_f32_16x16x32_bf16 v[40:43], v[178:181], v[202:205], v[40:43]
	v_mfma_f32_16x16x32_bf16 v[32:35], v[182:185], v[198:201], v[32:35]
	v_mfma_f32_16x16x32_bf16 v[32:35], v[186:189], v[202:205], v[32:35]
	v_mfma_f32_16x16x32_bf16 v[24:27], v[162:165], v[206:209], v[24:27]
	v_mfma_f32_16x16x32_bf16 v[24:27], v[178:181], v[210:213], v[24:27]
	v_mfma_f32_16x16x32_bf16 v[16:19], v[182:185], v[206:209], v[16:19]
	v_mfma_f32_16x16x32_bf16 v[16:19], v[186:189], v[210:213], v[16:19]
	v_mfma_f32_16x16x32_bf16 v[8:11], v[162:165], v[214:217], v[8:11]
	v_mfma_f32_16x16x32_bf16 v[8:11], v[178:181], v[218:221], v[8:11]
	s_setprio 3
	s_barrier
	v_mfma_f32_16x16x32_bf16 v[0:3], v[182:185], v[214:217], v[0:3]
	v_mfma_f32_16x16x32_bf16 v[0:3], v[186:189], v[218:221], v[0:3]
	s_setprio 0
	s_add_i32 s66, s66, 2
	s_add_u32 s78, s78, 0x100
	s_addc_u32 s79, s79, 0
	s_add_u32 s58, s58, 0x100
	s_addc_u32 s59, s59, 0
	s_cmp_gt_u32 s66, 13
	s_cbranch_scc0 .LBB0_1148
	s_branch .Lzskip_4
.Lzv_4_0:
	s_barrier
	v_mfma_f32_16x16x32_bf16 v[124:127], v[146:149], v[190:193], 0
	v_mfma_f32_16x16x32_bf16 v[124:127], v[150:153], v[194:197], v[124:127]
	v_mfma_f32_16x16x32_bf16 v[116:119], v[154:157], v[190:193], 0
	v_mfma_f32_16x16x32_bf16 v[116:119], v[158:161], v[194:197], v[116:119]
	v_mfma_f32_16x16x32_bf16 v[108:111], v[146:149], v[198:201], 0
	v_mfma_f32_16x16x32_bf16 v[108:111], v[150:153], v[202:205], v[108:111]
	v_mfma_f32_16x16x32_bf16 v[100:103], v[154:157], v[198:201], 0
	v_mfma_f32_16x16x32_bf16 v[100:103], v[158:161], v[202:205], v[100:103]
	v_mfma_f32_16x16x32_bf16 v[92:95], v[146:149], v[206:209], 0
	v_mfma_f32_16x16x32_bf16 v[92:95], v[150:153], v[210:213], v[92:95]
	v_mfma_f32_16x16x32_bf16 v[84:87], v[154:157], v[206:209], 0
	v_mfma_f32_16x16x32_bf16 v[84:87], v[158:161], v[210:213], v[84:87]
	v_mfma_f32_16x16x32_bf16 v[76:79], v[146:149], v[214:217], 0
	v_mfma_f32_16x16x32_bf16 v[76:79], v[150:153], v[218:221], v[76:79]
	v_mfma_f32_16x16x32_bf16 v[68:71], v[154:157], v[214:217], 0
	v_mfma_f32_16x16x32_bf16 v[68:71], v[158:161], v[218:221], v[68:71]
	v_mfma_f32_16x16x32_bf16 v[120:123], v[162:165], v[190:193], 0
	v_mfma_f32_16x16x32_bf16 v[120:123], v[178:181], v[194:197], v[120:123]
	v_mfma_f32_16x16x32_bf16 v[112:115], v[182:185], v[190:193], 0
	v_mfma_f32_16x16x32_bf16 v[112:115], v[186:189], v[194:197], v[112:115]
	v_mfma_f32_16x16x32_bf16 v[104:107], v[162:165], v[198:201], 0
	v_mfma_f32_16x16x32_bf16 v[104:107], v[178:181], v[202:205], v[104:107]
	v_mfma_f32_16x16x32_bf16 v[96:99], v[182:185], v[198:201], 0
	v_mfma_f32_16x16x32_bf16 v[96:99], v[186:189], v[202:205], v[96:99]
	v_mfma_f32_16x16x32_bf16 v[88:91], v[162:165], v[206:209], 0
	v_mfma_f32_16x16x32_bf16 v[88:91], v[178:181], v[210:213], v[88:91]
	v_mfma_f32_16x16x32_bf16 v[80:83], v[182:185], v[206:209], 0
	v_mfma_f32_16x16x32_bf16 v[80:83], v[186:189], v[210:213], v[80:83]
	v_mfma_f32_16x16x32_bf16 v[72:75], v[162:165], v[214:217], 0
	v_mfma_f32_16x16x32_bf16 v[72:75], v[178:181], v[218:221], v[72:75]
	s_setprio 3
	s_barrier
	v_mfma_f32_16x16x32_bf16 v[64:67], v[182:185], v[214:217], 0
	v_mfma_f32_16x16x32_bf16 v[64:67], v[186:189], v[218:221], v[64:67]
	s_setprio 0
	s_branch .Lzj_4_0
.Lzv_4_1:
	s_barrier
	v_mfma_f32_16x16x32_bf16 v[60:63], v[146:149], v[190:193], 0
	v_mfma_f32_16x16x32_bf16 v[60:63], v[150:153], v[194:197], v[60:63]
	v_mfma_f32_16x16x32_bf16 v[52:55], v[154:157], v[190:193], 0
	v_mfma_f32_16x16x32_bf16 v[52:55], v[158:161], v[194:197], v[52:55]
	v_mfma_f32_16x16x32_bf16 v[44:47], v[146:149], v[198:201], 0
	v_mfma_f32_16x16x32_bf16 v[44:47], v[150:153], v[202:205], v[44:47]
	v_mfma_f32_16x16x32_bf16 v[36:39], v[154:157], v[198:201], 0
	v_mfma_f32_16x16x32_bf16 v[36:39], v[158:161], v[202:205], v[36:39]
	v_mfma_f32_16x16x32_bf16 v[28:31], v[146:149], v[206:209], 0
	v_mfma_f32_16x16x32_bf16 v[28:31], v[150:153], v[210:213], v[28:31]
	v_mfma_f32_16x16x32_bf16 v[20:23], v[154:157], v[206:209], 0
	v_mfma_f32_16x16x32_bf16 v[20:23], v[158:161], v[210:213], v[20:23]
	v_mfma_f32_16x16x32_bf16 v[12:15], v[146:149], v[214:217], 0
	v_mfma_f32_16x16x32_bf16 v[12:15], v[150:153], v[218:221], v[12:15]
	v_mfma_f32_16x16x32_bf16 v[4:7], v[154:157], v[214:217], 0
	v_mfma_f32_16x16x32_bf16 v[4:7], v[158:161], v[218:221], v[4:7]
	v_mfma_f32_16x16x32_bf16 v[56:59], v[162:165], v[190:193], 0
	v_mfma_f32_16x16x32_bf16 v[56:59], v[178:181], v[194:197], v[56:59]
	v_mfma_f32_16x16x32_bf16 v[48:51], v[182:185], v[190:193], 0
	v_mfma_f32_16x16x32_bf16 v[48:51], v[186:189], v[194:197], v[48:51]
	v_mfma_f32_16x16x32_bf16 v[40:43], v[162:165], v[198:201], 0
	v_mfma_f32_16x16x32_bf16 v[40:43], v[178:181], v[202:205], v[40:43]
	v_mfma_f32_16x16x32_bf16 v[32:35], v[182:185], v[198:201], 0
	v_mfma_f32_16x16x32_bf16 v[32:35], v[186:189], v[202:205], v[32:35]
	v_mfma_f32_16x16x32_bf16 v[24:27], v[162:165], v[206:209], 0
	v_mfma_f32_16x16x32_bf16 v[24:27], v[178:181], v[210:213], v[24:27]
	v_mfma_f32_16x16x32_bf16 v[16:19], v[182:185], v[206:209], 0
	v_mfma_f32_16x16x32_bf16 v[16:19], v[186:189], v[210:213], v[16:19]
	v_mfma_f32_16x16x32_bf16 v[8:11], v[162:165], v[214:217], 0
	v_mfma_f32_16x16x32_bf16 v[8:11], v[178:181], v[218:221], v[8:11]
	s_setprio 3
	s_barrier
	v_mfma_f32_16x16x32_bf16 v[0:3], v[182:185], v[214:217], 0
	v_mfma_f32_16x16x32_bf16 v[0:3], v[186:189], v[218:221], v[0:3]
	s_setprio 0
	s_branch .Lzj_4_1

.LBB0_1299:
	ds_read_b128 v[120:123], v245
	ds_read_b128 v[124:127], v245 offset:1024
	ds_read_b128 v[128:131], v245 offset:2048
	ds_read_b128 v[132:135], v245 offset:3072
	ds_read_b128 v[144:147], v246
	ds_read_b128 v[148:151], v246 offset:1024
	ds_read_b128 v[152:155], v246 offset:2048
	ds_read_b128 v[156:159], v246 offset:3072
	s_add_u32 s66, s76, 0xfff50080
	s_addc_u32 s67, s77, -1
	s_cmp_eq_u32 s59, 40
	s_cselect_b32 s81, s9, s67
	s_cselect_b32 s80, s8, s66
	s_cselect_b32 s79, s53, s58
	s_cselect_b32 s78, s52, s55
	v_lshl_add_u64 v[204:205], s[76:77], 0, v[200:201]
	s_add_i32 m0, s16, 0xc000
	ds_read_b128 v[160:163], v247
	ds_read_b128 v[164:167], v247 offset:1024
	ds_read_b128 v[168:171], v247 offset:2048
	ds_read_b128 v[172:175], v247 offset:3072
	ds_read_b128 v[176:179], v247 offset:4096
	ds_read_b128 v[180:183], v247 offset:5120
	ds_read_b128 v[184:187], v247 offset:6144
	ds_read_b128 v[188:191], v247 offset:7168
	global_load_lds_dwordx4 v[204:205], off
	s_add_i32 m0, s16, 0xe000
	v_lshl_add_u64 v[204:205], s[76:77], 0, v[202:203]
	global_load_lds_dwordx4 v[204:205], off
	s_cmp_eq_u32 s59, -2
	s_waitcnt vmcnt(8) lgkmcnt(0)
	s_setprio 1
	s_cbranch_scc1 .Lzv_5_0
	s_barrier
	v_mfma_f32_16x16x32_bf16 v[140:143], v[120:123], v[160:163], v[140:143]
	v_mfma_f32_16x16x32_bf16 v[140:143], v[124:127], v[164:167], v[140:143]
	v_mfma_f32_16x16x32_bf16 v[136:139], v[128:131], v[160:163], v[136:139]
	v_mfma_f32_16x16x32_bf16 v[136:139], v[132:135], v[164:167], v[136:139]
	v_mfma_f32_16x16x32_bf16 v[108:111], v[120:123], v[168:171], v[108:111]
	v_mfma_f32_16x16x32_bf16 v[108:111], v[124:127], v[172:175], v[108:111]
	v_mfma_f32_16x16x32_bf16 v[104:107], v[128:131], v[168:171], v[104:107]
	v_mfma_f32_16x16x32_bf16 v[104:107], v[132:135], v[172:175], v[104:107]
	v_mfma_f32_16x16x32_bf16 v[92:95], v[120:123], v[176:179], v[92:95]
	v_mfma_f32_16x16x32_bf16 v[92:95], v[124:127], v[180:183], v[92:95]
	v_mfma_f32_16x16x32_bf16 v[88:91], v[128:131], v[176:179], v[88:91]
	v_mfma_f32_16x16x32_bf16 v[88:91], v[132:135], v[180:183], v[88:91]
	v_mfma_f32_16x16x32_bf16 v[76:79], v[120:123], v[184:187], v[76:79]
	v_mfma_f32_16x16x32_bf16 v[76:79], v[124:127], v[188:191], v[76:79]
	v_mfma_f32_16x16x32_bf16 v[72:75], v[128:131], v[184:187], v[72:75]
	v_mfma_f32_16x16x32_bf16 v[72:75], v[132:135], v[188:191], v[72:75]
	v_mfma_f32_16x16x32_bf16 v[116:119], v[144:147], v[160:163], v[116:119]
	v_mfma_f32_16x16x32_bf16 v[116:119], v[148:151], v[164:167], v[116:119]
	v_mfma_f32_16x16x32_bf16 v[112:115], v[152:155], v[160:163], v[112:115]
	v_mfma_f32_16x16x32_bf16 v[112:115], v[156:159], v[164:167], v[112:115]
	v_mfma_f32_16x16x32_bf16 v[100:103], v[144:147], v[168:171], v[100:103]
	v_mfma_f32_16x16x32_bf16 v[100:103], v[148:151], v[172:175], v[100:103]
	v_mfma_f32_16x16x32_bf16 v[96:99], v[152:155], v[168:171], v[96:99]
	v_mfma_f32_16x16x32_bf16 v[96:99], v[156:159], v[172:175], v[96:99]
	v_mfma_f32_16x16x32_bf16 v[84:87], v[144:147], v[176:179], v[84:87]
	v_mfma_f32_16x16x32_bf16 v[84:87], v[148:151], v[180:183], v[84:87]
	v_mfma_f32_16x16x32_bf16 v[80:83], v[152:155], v[176:179], v[80:83]
	v_mfma_f32_16x16x32_bf16 v[80:83], v[156:159], v[180:183], v[80:83]
	v_mfma_f32_16x16x32_bf16 v[68:71], v[144:147], v[184:187], v[68:71]
	v_mfma_f32_16x16x32_bf16 v[68:71], v[148:151], v[188:191], v[68:71]
	s_setprio 3
	s_barrier
	v_mfma_f32_16x16x32_bf16 v[64:67], v[152:155], v[184:187], v[64:67]
	v_mfma_f32_16x16x32_bf16 v[64:67], v[156:159], v[188:191], v[64:67]
	s_setprio 0
.Lzj_5_0:
	s_add_i32 s66, s26, s15
	v_lshl_add_u64 v[204:205], s[78:79], 0, v[194:195]
	s_mov_b32 m0, s66
	ds_read_b128 v[160:163], v247 offset:16384
	ds_read_b128 v[164:167], v247 offset:17408
	ds_read_b128 v[168:171], v247 offset:18432
	ds_read_b128 v[172:175], v247 offset:19456
	ds_read_b128 v[176:179], v247 offset:20480
	ds_read_b128 v[180:183], v247 offset:21504
	ds_read_b128 v[184:187], v247 offset:22528
	ds_read_b128 v[188:191], v247 offset:23552
	global_load_lds_dwordx4 v[204:205], off
	s_add_i32 m0, s66, 0x2000
	s_add_u32 s66, s78, 0xb0000
	v_lshl_add_u64 v[206:207], s[78:79], 0, v[198:199]
	s_addc_u32 s67, s79, 0
	s_add_i32 s68, s27, s15
	global_load_lds_dwordx4 v[206:207], off
	v_lshl_add_u64 v[208:209], s[66:67], 0, v[194:195]
	s_mov_b32 m0, s68
	global_load_lds_dwordx4 v[208:209], off
	s_add_i32 m0, s68, 0x2000
	v_lshl_add_u64 v[208:209], s[66:67], 0, v[198:199]
	global_load_lds_dwordx4 v[208:209], off
	s_mov_b32 m0, s16
	v_lshl_add_u64 v[208:209], s[80:81], 0, v[192:193]
	global_load_lds_dwordx4 v[208:209], off
	s_mov_b32 m0, s17
	v_lshl_add_u64 v[210:211], s[80:81], 0, v[196:197]
	global_load_lds_dwordx4 v[210:211], off
	s_cmp_eq_u32 s59, -2
	s_waitcnt vmcnt(8) lgkmcnt(0)
	s_setprio 1
	s_cbranch_scc1 .Lzv_5_1
	s_barrier
	v_mfma_f32_16x16x32_bf16 v[60:63], v[120:123], v[160:163], v[60:63]
	v_mfma_f32_16x16x32_bf16 v[60:63], v[124:127], v[164:167], v[60:63]
	v_mfma_f32_16x16x32_bf16 v[56:59], v[128:131], v[160:163], v[56:59]
	v_mfma_f32_16x16x32_bf16 v[56:59], v[132:135], v[164:167], v[56:59]
	v_mfma_f32_16x16x32_bf16 v[44:47], v[120:123], v[168:171], v[44:47]
	v_mfma_f32_16x16x32_bf16 v[44:47], v[124:127], v[172:175], v[44:47]
	v_mfma_f32_16x16x32_bf16 v[40:43], v[128:131], v[168:171], v[40:43]
	v_mfma_f32_16x16x32_bf16 v[40:43], v[132:135], v[172:175], v[40:43]
	v_mfma_f32_16x16x32_bf16 v[28:31], v[120:123], v[176:179], v[28:31]
	v_mfma_f32_16x16x32_bf16 v[28:31], v[124:127], v[180:183], v[28:31]
	v_mfma_f32_16x16x32_bf16 v[24:27], v[128:131], v[176:179], v[24:27]
	v_mfma_f32_16x16x32_bf16 v[24:27], v[132:135], v[180:183], v[24:27]
	v_mfma_f32_16x16x32_bf16 v[12:15], v[120:123], v[184:187], v[12:15]
	v_mfma_f32_16x16x32_bf16 v[12:15], v[124:127], v[188:191], v[12:15]
	v_mfma_f32_16x16x32_bf16 v[8:11], v[128:131], v[184:187], v[8:11]
	v_mfma_f32_16x16x32_bf16 v[8:11], v[132:135], v[188:191], v[8:11]
	v_mfma_f32_16x16x32_bf16 v[52:55], v[144:147], v[160:163], v[52:55]
	v_mfma_f32_16x16x32_bf16 v[52:55], v[148:151], v[164:167], v[52:55]
	v_mfma_f32_16x16x32_bf16 v[48:51], v[152:155], v[160:163], v[48:51]
	v_mfma_f32_16x16x32_bf16 v[48:51], v[156:159], v[164:167], v[48:51]
	v_mfma_f32_16x16x32_bf16 v[36:39], v[144:147], v[168:171], v[36:39]
	v_mfma_f32_16x16x32_bf16 v[36:39], v[148:151], v[172:175], v[36:39]
	v_mfma_f32_16x16x32_bf16 v[32:35], v[152:155], v[168:171], v[32:35]
	v_mfma_f32_16x16x32_bf16 v[32:35], v[156:159], v[172:175], v[32:35]
	v_mfma_f32_16x16x32_bf16 v[20:23], v[144:147], v[176:179], v[20:23]
	v_mfma_f32_16x16x32_bf16 v[20:23], v[148:151], v[180:183], v[20:23]
	v_mfma_f32_16x16x32_bf16 v[16:19], v[152:155], v[176:179], v[16:19]
	v_mfma_f32_16x16x32_bf16 v[16:19], v[156:159], v[180:183], v[16:19]
	v_mfma_f32_16x16x32_bf16 v[4:7], v[144:147], v[184:187], v[4:7]
	v_mfma_f32_16x16x32_bf16 v[4:7], v[148:151], v[188:191], v[4:7]
	s_setprio 3
	s_barrier
	v_mfma_f32_16x16x32_bf16 v[0:3], v[152:155], v[184:187], v[0:3]
	v_mfma_f32_16x16x32_bf16 v[0:3], v[156:159], v[188:191], v[0:3]
	s_setprio 0
.Lzj_5_1:
	s_add_i32 s68, 0, 0x18000
	s_add_i32 s69, 0, 0x1c000
	v_add_u32_e32 v132, s68, v243
	v_add_u32_e32 v156, s69, v243
	ds_read_b128 v[120:123], v132
	ds_read_b128 v[124:127], v132 offset:1024
	ds_read_b128 v[128:131], v132 offset:2048
	ds_read_b128 v[132:135], v132 offset:3072
	ds_read_b128 v[144:147], v156
	ds_read_b128 v[148:151], v156 offset:1024
	ds_read_b128 v[152:155], v156 offset:2048
	ds_read_b128 v[156:159], v156 offset:3072
	s_add_u32 s66, s80, 0xb0000
	s_addc_u32 s67, s81, 0
	s_mov_b32 m0, s18
	v_lshl_add_u64 v[212:213], s[66:67], 0, v[192:193]
	ds_read_b128 v[160:163], v247 offset:32768
	ds_read_b128 v[164:167], v247 offset:33792
	ds_read_b128 v[168:171], v247 offset:34816
	ds_read_b128 v[172:175], v247 offset:35840
	ds_read_b128 v[176:179], v247 offset:36864
	ds_read_b128 v[180:183], v247 offset:37888
	ds_read_b128 v[184:187], v247 offset:38912
	ds_read_b128 v[188:191], v247 offset:39936
	global_load_lds_dwordx4 v[212:213], off
	s_mov_b32 m0, s19
	v_lshl_add_u64 v[212:213], s[66:67], 0, v[196:197]
	global_load_lds_dwordx4 v[212:213], off
	s_waitcnt vmcnt(8) lgkmcnt(0)
	s_setprio 1
	s_barrier
	v_mfma_f32_16x16x32_bf16 v[140:143], v[120:123], v[160:163], v[140:143]
	v_mfma_f32_16x16x32_bf16 v[140:143], v[124:127], v[164:167], v[140:143]
	v_mfma_f32_16x16x32_bf16 v[136:139], v[128:131], v[160:163], v[136:139]
	v_mfma_f32_16x16x32_bf16 v[136:139], v[132:135], v[164:167], v[136:139]
	v_mfma_f32_16x16x32_bf16 v[108:111], v[120:123], v[168:171], v[108:111]
	v_mfma_f32_16x16x32_bf16 v[108:111], v[124:127], v[172:175], v[108:111]
	v_mfma_f32_16x16x32_bf16 v[104:107], v[128:131], v[168:171], v[104:107]
	v_mfma_f32_16x16x32_bf16 v[104:107], v[132:135], v[172:175], v[104:107]
	v_mfma_f32_16x16x32_bf16 v[92:95], v[120:123], v[176:179], v[92:95]
	v_mfma_f32_16x16x32_bf16 v[92:95], v[124:127], v[180:183], v[92:95]
	v_mfma_f32_16x16x32_bf16 v[88:91], v[128:131], v[176:179], v[88:91]
	v_mfma_f32_16x16x32_bf16 v[88:91], v[132:135], v[180:183], v[88:91]
	v_mfma_f32_16x16x32_bf16 v[76:79], v[120:123], v[184:187], v[76:79]
	v_mfma_f32_16x16x32_bf16 v[76:79], v[124:127], v[188:191], v[76:79]
	v_mfma_f32_16x16x32_bf16 v[72:75], v[128:131], v[184:187], v[72:75]
	v_mfma_f32_16x16x32_bf16 v[72:75], v[132:135], v[188:191], v[72:75]
	v_mfma_f32_16x16x32_bf16 v[116:119], v[144:147], v[160:163], v[116:119]
	v_mfma_f32_16x16x32_bf16 v[116:119], v[148:151], v[164:167], v[116:119]
	v_mfma_f32_16x16x32_bf16 v[112:115], v[152:155], v[160:163], v[112:115]
	v_mfma_f32_16x16x32_bf16 v[112:115], v[156:159], v[164:167], v[112:115]
	v_mfma_f32_16x16x32_bf16 v[100:103], v[144:147], v[168:171], v[100:103]
	v_mfma_f32_16x16x32_bf16 v[100:103], v[148:151], v[172:175], v[100:103]
	v_mfma_f32_16x16x32_bf16 v[96:99], v[152:155], v[168:171], v[96:99]
	v_mfma_f32_16x16x32_bf16 v[96:99], v[156:159], v[172:175], v[96:99]
	v_mfma_f32_16x16x32_bf16 v[84:87], v[144:147], v[176:179], v[84:87]
	v_mfma_f32_16x16x32_bf16 v[84:87], v[148:151], v[180:183], v[84:87]
	v_mfma_f32_16x16x32_bf16 v[80:83], v[152:155], v[176:179], v[80:83]
	v_mfma_f32_16x16x32_bf16 v[80:83], v[156:159], v[180:183], v[80:83]
	v_mfma_f32_16x16x32_bf16 v[68:71], v[144:147], v[184:187], v[68:71]
	v_mfma_f32_16x16x32_bf16 v[68:71], v[148:151], v[188:191], v[68:71]
	s_setprio 3
	s_barrier
	v_mfma_f32_16x16x32_bf16 v[64:67], v[152:155], v[184:187], v[64:67]
	v_mfma_f32_16x16x32_bf16 v[64:67], v[156:159], v[188:191], v[64:67]
	s_setprio 0
	s_add_i32 s66, s68, s15
	v_lshl_add_u64 v[204:205], v[204:205], 0, s[48:49]
	s_mov_b32 m0, s66
	ds_read_b128 v[160:163], v247 offset:49152
	ds_read_b128 v[164:167], v247 offset:50176
	ds_read_b128 v[168:171], v247 offset:51200
	ds_read_b128 v[172:175], v247 offset:52224
	ds_read_b128 v[176:179], v247 offset:53248
	ds_read_b128 v[180:183], v247 offset:54272
	ds_read_b128 v[184:187], v247 offset:55296
	ds_read_b128 v[188:191], v247 offset:56320
	global_load_lds_dwordx4 v[204:205], off
	s_add_i32 m0, s66, 0x2000
	s_add_u32 s66, s78, 0xb0080
	v_lshl_add_u64 v[204:205], v[206:207], 0, s[48:49]
	s_addc_u32 s67, s79, 0
	s_add_i32 s68, s69, s15
	global_load_lds_dwordx4 v[204:205], off
	s_mov_b32 m0, s68
	v_lshl_add_u64 v[204:205], s[66:67], 0, v[194:195]
	global_load_lds_dwordx4 v[204:205], off
	s_add_i32 m0, s68, 0x2000
	v_lshl_add_u64 v[204:205], s[66:67], 0, v[198:199]
	global_load_lds_dwordx4 v[204:205], off
	s_mov_b32 m0, s21
	v_lshl_add_u64 v[204:205], v[208:209], 0, s[48:49]
	global_load_lds_dwordx4 v[204:205], off
	s_mov_b32 m0, s22
	v_lshl_add_u64 v[204:205], v[210:211], 0, s[48:49]
	global_load_lds_dwordx4 v[204:205], off
	s_waitcnt vmcnt(8) lgkmcnt(0)
	s_setprio 1
	s_barrier
	v_mfma_f32_16x16x32_bf16 v[60:63], v[120:123], v[160:163], v[60:63]
	v_mfma_f32_16x16x32_bf16 v[60:63], v[124:127], v[164:167], v[60:63]
	v_mfma_f32_16x16x32_bf16 v[56:59], v[128:131], v[160:163], v[56:59]
	v_mfma_f32_16x16x32_bf16 v[56:59], v[132:135], v[164:167], v[56:59]
	v_mfma_f32_16x16x32_bf16 v[44:47], v[120:123], v[168:171], v[44:47]
	v_mfma_f32_16x16x32_bf16 v[44:47], v[124:127], v[172:175], v[44:47]
	v_mfma_f32_16x16x32_bf16 v[40:43], v[128:131], v[168:171], v[40:43]
	v_mfma_f32_16x16x32_bf16 v[40:43], v[132:135], v[172:175], v[40:43]
	v_mfma_f32_16x16x32_bf16 v[28:31], v[120:123], v[176:179], v[28:31]
	v_mfma_f32_16x16x32_bf16 v[28:31], v[124:127], v[180:183], v[28:31]
	v_mfma_f32_16x16x32_bf16 v[24:27], v[128:131], v[176:179], v[24:27]
	v_mfma_f32_16x16x32_bf16 v[24:27], v[132:135], v[180:183], v[24:27]
	v_mfma_f32_16x16x32_bf16 v[12:15], v[120:123], v[184:187], v[12:15]
	v_mfma_f32_16x16x32_bf16 v[12:15], v[124:127], v[188:191], v[12:15]
	v_mfma_f32_16x16x32_bf16 v[8:11], v[128:131], v[184:187], v[8:11]
	v_mfma_f32_16x16x32_bf16 v[8:11], v[132:135], v[188:191], v[8:11]
	v_mfma_f32_16x16x32_bf16 v[52:55], v[144:147], v[160:163], v[52:55]
	v_mfma_f32_16x16x32_bf16 v[52:55], v[148:151], v[164:167], v[52:55]
	v_mfma_f32_16x16x32_bf16 v[48:51], v[152:155], v[160:163], v[48:51]
	v_mfma_f32_16x16x32_bf16 v[48:51], v[156:159], v[164:167], v[48:51]
	v_mfma_f32_16x16x32_bf16 v[36:39], v[144:147], v[168:171], v[36:39]
	v_mfma_f32_16x16x32_bf16 v[36:39], v[148:151], v[172:175], v[36:39]
	v_mfma_f32_16x16x32_bf16 v[32:35], v[152:155], v[168:171], v[32:35]
	v_mfma_f32_16x16x32_bf16 v[32:35], v[156:159], v[172:175], v[32:35]
	v_mfma_f32_16x16x32_bf16 v[20:23], v[144:147], v[176:179], v[20:23]
	v_mfma_f32_16x16x32_bf16 v[20:23], v[148:151], v[180:183], v[20:23]
	v_mfma_f32_16x16x32_bf16 v[16:19], v[152:155], v[176:179], v[16:19]
	v_mfma_f32_16x16x32_bf16 v[16:19], v[156:159], v[180:183], v[16:19]
	v_mfma_f32_16x16x32_bf16 v[4:7], v[144:147], v[184:187], v[4:7]
	v_mfma_f32_16x16x32_bf16 v[4:7], v[148:151], v[188:191], v[4:7]
	s_setprio 3
	s_barrier
	v_mfma_f32_16x16x32_bf16 v[0:3], v[152:155], v[184:187], v[0:3]
	v_mfma_f32_16x16x32_bf16 v[0:3], v[156:159], v[188:191], v[0:3]
	s_setprio 0
	s_add_i32 s59, s59, 2
	s_add_u32 s76, s76, 0x100
	s_addc_u32 s77, s77, 0
	s_add_u32 s55, s55, 0x100
	s_addc_u32 s58, s58, 0
	s_cmp_gt_u32 s59, 41
	s_cbranch_scc0 .LBB0_1299
	s_branch .Lzskip_5

.LBB0_1760:
	ds_read_b128 v[128:131], v181
	ds_read_b128 v[132:135], v181 offset:1024
	ds_read_b128 v[136:139], v181 offset:2048
	ds_read_b128 v[160:163], v181 offset:3072
	ds_read_b128 v[164:167], v182
	ds_read_b128 v[168:171], v182 offset:1024
	ds_read_b128 v[186:189], v182 offset:2048
	ds_read_b128 v[190:193], v182 offset:3072
	s_add_u32 s69, s78, 0xfffc0080
	s_addc_u32 s73, s79, -1
	s_cmp_eq_u32 s68, 12
	s_cselect_b32 s83, s49, s73
	s_cselect_b32 s82, s54, s69
	s_cselect_b32 s81, s47, s67
	s_cselect_b32 s80, s55, s66
	v_lshl_add_u64 v[172:173], s[78:79], 0, v[152:153]
	s_add_i32 m0, s18, 0xc000
	ds_read_b128 v[194:197], v183
	ds_read_b128 v[198:201], v183 offset:1024
	ds_read_b128 v[202:205], v183 offset:2048
	ds_read_b128 v[206:209], v183 offset:3072
	ds_read_b128 v[210:213], v183 offset:4096
	ds_read_b128 v[214:217], v183 offset:5120
	ds_read_b128 v[218:221], v183 offset:6144
	ds_read_b128 v[222:225], v183 offset:7168
	global_load_lds_dwordx4 v[172:173], off
	s_add_i32 m0, s18, 0xe000
	v_lshl_add_u64 v[172:173], s[78:79], 0, v[154:155]
	global_load_lds_dwordx4 v[172:173], off
	s_cmp_eq_u32 s68, -2
	s_waitcnt vmcnt(8) lgkmcnt(0)
	s_setprio 1
	s_cbranch_scc1 .Lzv_8_0
	s_barrier
	v_mfma_f32_16x16x32_bf16 v[124:127], v[128:131], v[194:197], v[124:127]
	v_mfma_f32_16x16x32_bf16 v[124:127], v[132:135], v[198:201], v[124:127]
	v_mfma_f32_16x16x32_bf16 v[120:123], v[136:139], v[194:197], v[120:123]
	v_mfma_f32_16x16x32_bf16 v[120:123], v[160:163], v[198:201], v[120:123]
	v_mfma_f32_16x16x32_bf16 v[108:111], v[128:131], v[202:205], v[108:111]
	v_mfma_f32_16x16x32_bf16 v[108:111], v[132:135], v[206:209], v[108:111]
	v_mfma_f32_16x16x32_bf16 v[104:107], v[136:139], v[202:205], v[104:107]
	v_mfma_f32_16x16x32_bf16 v[104:107], v[160:163], v[206:209], v[104:107]
	v_mfma_f32_16x16x32_bf16 v[92:95], v[128:131], v[210:213], v[92:95]
	v_mfma_f32_16x16x32_bf16 v[92:95], v[132:135], v[214:217], v[92:95]
	v_mfma_f32_16x16x32_bf16 v[88:91], v[136:139], v[210:213], v[88:91]
	v_mfma_f32_16x16x32_bf16 v[88:91], v[160:163], v[214:217], v[88:91]
	v_mfma_f32_16x16x32_bf16 v[76:79], v[128:131], v[218:221], v[76:79]
	v_mfma_f32_16x16x32_bf16 v[76:79], v[132:135], v[222:225], v[76:79]
	v_mfma_f32_16x16x32_bf16 v[72:75], v[136:139], v[218:221], v[72:75]
	v_mfma_f32_16x16x32_bf16 v[72:75], v[160:163], v[222:225], v[72:75]
	v_mfma_f32_16x16x32_bf16 v[116:119], v[164:167], v[194:197], v[116:119]
	v_mfma_f32_16x16x32_bf16 v[116:119], v[168:171], v[198:201], v[116:119]
	v_mfma_f32_16x16x32_bf16 v[112:115], v[186:189], v[194:197], v[112:115]
	v_mfma_f32_16x16x32_bf16 v[112:115], v[190:193], v[198:201], v[112:115]
	v_mfma_f32_16x16x32_bf16 v[100:103], v[164:167], v[202:205], v[100:103]
	v_mfma_f32_16x16x32_bf16 v[100:103], v[168:171], v[206:209], v[100:103]
	v_mfma_f32_16x16x32_bf16 v[96:99], v[186:189], v[202:205], v[96:99]
	v_mfma_f32_16x16x32_bf16 v[96:99], v[190:193], v[206:209], v[96:99]
	v_mfma_f32_16x16x32_bf16 v[84:87], v[164:167], v[210:213], v[84:87]
	v_mfma_f32_16x16x32_bf16 v[84:87], v[168:171], v[214:217], v[84:87]
	v_mfma_f32_16x16x32_bf16 v[80:83], v[186:189], v[210:213], v[80:83]
	v_mfma_f32_16x16x32_bf16 v[80:83], v[190:193], v[214:217], v[80:83]
	v_mfma_f32_16x16x32_bf16 v[68:71], v[164:167], v[218:221], v[68:71]
	v_mfma_f32_16x16x32_bf16 v[68:71], v[168:171], v[222:225], v[68:71]
	s_setprio 3
	s_barrier
	v_mfma_f32_16x16x32_bf16 v[64:67], v[186:189], v[218:221], v[64:67]
	v_mfma_f32_16x16x32_bf16 v[64:67], v[190:193], v[222:225], v[64:67]
	s_setprio 0
.Lzj_8_0:
	s_add_i32 s69, s25, s17
	v_lshl_add_u64 v[172:173], s[80:81], 0, v[142:143]
	s_mov_b32 m0, s69
	ds_read_b128 v[194:197], v183 offset:16384
	ds_read_b128 v[198:201], v183 offset:17408
	ds_read_b128 v[202:205], v183 offset:18432
	ds_read_b128 v[206:209], v183 offset:19456
	ds_read_b128 v[210:213], v183 offset:20480
	ds_read_b128 v[214:217], v183 offset:21504
	ds_read_b128 v[218:221], v183 offset:22528
	ds_read_b128 v[222:225], v183 offset:23552
	global_load_lds_dwordx4 v[172:173], off
	s_add_i32 m0, s69, 0x2000
	s_add_u32 s84, s80, 0x40000
	v_lshl_add_u64 v[226:227], s[80:81], 0, v[146:147]
	s_addc_u32 s85, s81, 0
	s_add_i32 s69, s26, s17
	global_load_lds_dwordx4 v[226:227], off
	v_lshl_add_u64 v[228:229], s[84:85], 0, v[142:143]
	s_mov_b32 m0, s69
	global_load_lds_dwordx4 v[228:229], off
	s_add_i32 m0, s69, 0x2000
	v_lshl_add_u64 v[228:229], s[84:85], 0, v[146:147]
	global_load_lds_dwordx4 v[228:229], off
	s_mov_b32 m0, s18
	v_lshl_add_u64 v[228:229], s[82:83], 0, v[140:141]
	global_load_lds_dwordx4 v[228:229], off
	s_mov_b32 m0, s19
	v_lshl_add_u64 v[230:231], s[82:83], 0, v[144:145]
	global_load_lds_dwordx4 v[230:231], off
	s_cmp_eq_u32 s68, -2
	s_waitcnt vmcnt(8) lgkmcnt(0)
	s_setprio 1
	s_cbranch_scc1 .Lzv_8_1
	s_barrier
	v_mfma_f32_16x16x32_bf16 v[60:63], v[128:131], v[194:197], v[60:63]
	v_mfma_f32_16x16x32_bf16 v[60:63], v[132:135], v[198:201], v[60:63]
	v_mfma_f32_16x16x32_bf16 v[56:59], v[136:139], v[194:197], v[56:59]
	v_mfma_f32_16x16x32_bf16 v[56:59], v[160:163], v[198:201], v[56:59]
	v_mfma_f32_16x16x32_bf16 v[44:47], v[128:131], v[202:205], v[44:47]
	v_mfma_f32_16x16x32_bf16 v[44:47], v[132:135], v[206:209], v[44:47]
	v_mfma_f32_16x16x32_bf16 v[40:43], v[136:139], v[202:205], v[40:43]
	v_mfma_f32_16x16x32_bf16 v[40:43], v[160:163], v[206:209], v[40:43]
	v_mfma_f32_16x16x32_bf16 v[28:31], v[128:131], v[210:213], v[28:31]
	v_mfma_f32_16x16x32_bf16 v[28:31], v[132:135], v[214:217], v[28:31]
	v_mfma_f32_16x16x32_bf16 v[24:27], v[136:139], v[210:213], v[24:27]
	v_mfma_f32_16x16x32_bf16 v[24:27], v[160:163], v[214:217], v[24:27]
	v_mfma_f32_16x16x32_bf16 v[12:15], v[128:131], v[218:221], v[12:15]
	v_mfma_f32_16x16x32_bf16 v[12:15], v[132:135], v[222:225], v[12:15]
	v_mfma_f32_16x16x32_bf16 v[8:11], v[136:139], v[218:221], v[8:11]
	v_mfma_f32_16x16x32_bf16 v[8:11], v[160:163], v[222:225], v[8:11]
	v_mfma_f32_16x16x32_bf16 v[52:55], v[164:167], v[194:197], v[52:55]
	v_mfma_f32_16x16x32_bf16 v[52:55], v[168:171], v[198:201], v[52:55]
	v_mfma_f32_16x16x32_bf16 v[48:51], v[186:189], v[194:197], v[48:51]
	v_mfma_f32_16x16x32_bf16 v[48:51], v[190:193], v[198:201], v[48:51]
	v_mfma_f32_16x16x32_bf16 v[36:39], v[164:167], v[202:205], v[36:39]
	v_mfma_f32_16x16x32_bf16 v[36:39], v[168:171], v[206:209], v[36:39]
	v_mfma_f32_16x16x32_bf16 v[32:35], v[186:189], v[202:205], v[32:35]
	v_mfma_f32_16x16x32_bf16 v[32:35], v[190:193], v[206:209], v[32:35]
	v_mfma_f32_16x16x32_bf16 v[20:23], v[164:167], v[210:213], v[20:23]
	v_mfma_f32_16x16x32_bf16 v[20:23], v[168:171], v[214:217], v[20:23]
	v_mfma_f32_16x16x32_bf16 v[16:19], v[186:189], v[210:213], v[16:19]
	v_mfma_f32_16x16x32_bf16 v[16:19], v[190:193], v[214:217], v[16:19]
	v_mfma_f32_16x16x32_bf16 v[4:7], v[164:167], v[218:221], v[4:7]
	v_mfma_f32_16x16x32_bf16 v[4:7], v[168:171], v[222:225], v[4:7]
	s_setprio 3
	s_barrier
	v_mfma_f32_16x16x32_bf16 v[0:3], v[186:189], v[218:221], v[0:3]
	v_mfma_f32_16x16x32_bf16 v[0:3], v[190:193], v[222:225], v[0:3]
	s_setprio 0
.Lzj_8_1:
	s_add_i32 s69, 0, 0x18000
	v_add_u32_e32 v148, s69, v177
	s_add_i32 s73, 0, 0x1c000
	ds_read_b128 v[128:131], v148
	ds_read_b128 v[132:135], v148 offset:1024
	ds_read_b128 v[136:139], v148 offset:2048
	ds_read_b128 v[160:163], v148 offset:3072
	v_add_u32_e32 v148, s73, v177
	ds_read_b128 v[164:167], v148
	ds_read_b128 v[168:171], v148 offset:1024
	ds_read_b128 v[186:189], v148 offset:2048
	ds_read_b128 v[190:193], v148 offset:3072
	s_add_u32 s82, s82, 0x40000
	s_addc_u32 s83, s83, 0
	s_mov_b32 m0, s20
	v_lshl_add_u64 v[232:233], s[82:83], 0, v[140:141]
	ds_read_b128 v[194:197], v183 offset:32768
	ds_read_b128 v[198:201], v183 offset:33792
	ds_read_b128 v[202:205], v183 offset:34816
	ds_read_b128 v[206:209], v183 offset:35840
	ds_read_b128 v[210:213], v183 offset:36864
	ds_read_b128 v[214:217], v183 offset:37888
	ds_read_b128 v[218:221], v183 offset:38912
	ds_read_b128 v[222:225], v183 offset:39936
	global_load_lds_dwordx4 v[232:233], off
	s_mov_b32 m0, s21
	v_lshl_add_u64 v[232:233], s[82:83], 0, v[144:145]
	global_load_lds_dwordx4 v[232:233], off
	s_waitcnt vmcnt(8) lgkmcnt(0)
	s_setprio 1
	s_barrier
	v_mfma_f32_16x16x32_bf16 v[124:127], v[128:131], v[194:197], v[124:127]
	v_mfma_f32_16x16x32_bf16 v[124:127], v[132:135], v[198:201], v[124:127]
	v_mfma_f32_16x16x32_bf16 v[120:123], v[136:139], v[194:197], v[120:123]
	v_mfma_f32_16x16x32_bf16 v[120:123], v[160:163], v[198:201], v[120:123]
	v_mfma_f32_16x16x32_bf16 v[108:111], v[128:131], v[202:205], v[108:111]
	v_mfma_f32_16x16x32_bf16 v[108:111], v[132:135], v[206:209], v[108:111]
	v_mfma_f32_16x16x32_bf16 v[104:107], v[136:139], v[202:205], v[104:107]
	v_mfma_f32_16x16x32_bf16 v[104:107], v[160:163], v[206:209], v[104:107]
	v_mfma_f32_16x16x32_bf16 v[92:95], v[128:131], v[210:213], v[92:95]
	v_mfma_f32_16x16x32_bf16 v[92:95], v[132:135], v[214:217], v[92:95]
	v_mfma_f32_16x16x32_bf16 v[88:91], v[136:139], v[210:213], v[88:91]
	v_mfma_f32_16x16x32_bf16 v[88:91], v[160:163], v[214:217], v[88:91]
	v_mfma_f32_16x16x32_bf16 v[76:79], v[128:131], v[218:221], v[76:79]
	v_mfma_f32_16x16x32_bf16 v[76:79], v[132:135], v[222:225], v[76:79]
	v_mfma_f32_16x16x32_bf16 v[72:75], v[136:139], v[218:221], v[72:75]
	v_mfma_f32_16x16x32_bf16 v[72:75], v[160:163], v[222:225], v[72:75]
	v_mfma_f32_16x16x32_bf16 v[116:119], v[164:167], v[194:197], v[116:119]
	v_mfma_f32_16x16x32_bf16 v[116:119], v[168:171], v[198:201], v[116:119]
	v_mfma_f32_16x16x32_bf16 v[112:115], v[186:189], v[194:197], v[112:115]
	v_mfma_f32_16x16x32_bf16 v[112:115], v[190:193], v[198:201], v[112:115]
	v_mfma_f32_16x16x32_bf16 v[100:103], v[164:167], v[202:205], v[100:103]
	v_mfma_f32_16x16x32_bf16 v[100:103], v[168:171], v[206:209], v[100:103]
	v_mfma_f32_16x16x32_bf16 v[96:99], v[186:189], v[202:205], v[96:99]
	v_mfma_f32_16x16x32_bf16 v[96:99], v[190:193], v[206:209], v[96:99]
	v_mfma_f32_16x16x32_bf16 v[84:87], v[164:167], v[210:213], v[84:87]
	v_mfma_f32_16x16x32_bf16 v[84:87], v[168:171], v[214:217], v[84:87]
	v_mfma_f32_16x16x32_bf16 v[80:83], v[186:189], v[210:213], v[80:83]
	v_mfma_f32_16x16x32_bf16 v[80:83], v[190:193], v[214:217], v[80:83]
	v_mfma_f32_16x16x32_bf16 v[68:71], v[164:167], v[218:221], v[68:71]
	v_mfma_f32_16x16x32_bf16 v[68:71], v[168:171], v[222:225], v[68:71]
	s_setprio 3
	s_barrier
	v_mfma_f32_16x16x32_bf16 v[64:67], v[186:189], v[218:221], v[64:67]
	v_mfma_f32_16x16x32_bf16 v[64:67], v[190:193], v[222:225], v[64:67]
	s_setprio 0
	s_add_i32 s69, s69, s17
	v_lshl_add_u64 v[172:173], v[172:173], 0, s[10:11]
	s_mov_b32 m0, s69
	ds_read_b128 v[194:197], v183 offset:49152
	ds_read_b128 v[198:201], v183 offset:50176
	ds_read_b128 v[202:205], v183 offset:51200
	ds_read_b128 v[206:209], v183 offset:52224
	ds_read_b128 v[210:213], v183 offset:53248
	ds_read_b128 v[214:217], v183 offset:54272
	ds_read_b128 v[218:221], v183 offset:55296
	ds_read_b128 v[222:225], v183 offset:56320
	global_load_lds_dwordx4 v[172:173], off
	s_add_i32 m0, s69, 0x2000
	s_add_u32 s80, s80, 0x40080
	v_lshl_add_u64 v[172:173], v[226:227], 0, s[10:11]
	s_addc_u32 s81, s81, 0
	s_add_i32 s69, s73, s17
	global_load_lds_dwordx4 v[172:173], off
	s_mov_b32 m0, s69
	v_lshl_add_u64 v[172:173], s[80:81], 0, v[142:143]
	global_load_lds_dwordx4 v[172:173], off
	s_add_i32 m0, s69, 0x2000
	v_lshl_add_u64 v[172:173], s[80:81], 0, v[146:147]
	global_load_lds_dwordx4 v[172:173], off
	s_mov_b32 m0, s23
	v_lshl_add_u64 v[172:173], v[228:229], 0, s[10:11]
	global_load_lds_dwordx4 v[172:173], off
	s_mov_b32 m0, s24
	v_lshl_add_u64 v[172:173], v[230:231], 0, s[10:11]
	global_load_lds_dwordx4 v[172:173], off
	s_waitcnt vmcnt(8) lgkmcnt(0)
	s_setprio 1
	s_barrier
	v_mfma_f32_16x16x32_bf16 v[60:63], v[128:131], v[194:197], v[60:63]
	v_mfma_f32_16x16x32_bf16 v[60:63], v[132:135], v[198:201], v[60:63]
	v_mfma_f32_16x16x32_bf16 v[56:59], v[136:139], v[194:197], v[56:59]
	v_mfma_f32_16x16x32_bf16 v[56:59], v[160:163], v[198:201], v[56:59]
	v_mfma_f32_16x16x32_bf16 v[44:47], v[128:131], v[202:205], v[44:47]
	v_mfma_f32_16x16x32_bf16 v[44:47], v[132:135], v[206:209], v[44:47]
	v_mfma_f32_16x16x32_bf16 v[40:43], v[136:139], v[202:205], v[40:43]
	v_mfma_f32_16x16x32_bf16 v[40:43], v[160:163], v[206:209], v[40:43]
	v_mfma_f32_16x16x32_bf16 v[28:31], v[128:131], v[210:213], v[28:31]
	v_mfma_f32_16x16x32_bf16 v[28:31], v[132:135], v[214:217], v[28:31]
	v_mfma_f32_16x16x32_bf16 v[24:27], v[136:139], v[210:213], v[24:27]
	v_mfma_f32_16x16x32_bf16 v[24:27], v[160:163], v[214:217], v[24:27]
	v_mfma_f32_16x16x32_bf16 v[12:15], v[128:131], v[218:221], v[12:15]
	v_mfma_f32_16x16x32_bf16 v[12:15], v[132:135], v[222:225], v[12:15]
	v_mfma_f32_16x16x32_bf16 v[8:11], v[136:139], v[218:221], v[8:11]
	v_mfma_f32_16x16x32_bf16 v[8:11], v[160:163], v[222:225], v[8:11]
	v_mfma_f32_16x16x32_bf16 v[52:55], v[164:167], v[194:197], v[52:55]
	v_mfma_f32_16x16x32_bf16 v[52:55], v[168:171], v[198:201], v[52:55]
	v_mfma_f32_16x16x32_bf16 v[48:51], v[186:189], v[194:197], v[48:51]
	v_mfma_f32_16x16x32_bf16 v[48:51], v[190:193], v[198:201], v[48:51]
	v_mfma_f32_16x16x32_bf16 v[36:39], v[164:167], v[202:205], v[36:39]
	v_mfma_f32_16x16x32_bf16 v[36:39], v[168:171], v[206:209], v[36:39]
	v_mfma_f32_16x16x32_bf16 v[32:35], v[186:189], v[202:205], v[32:35]
	v_mfma_f32_16x16x32_bf16 v[32:35], v[190:193], v[206:209], v[32:35]
	v_mfma_f32_16x16x32_bf16 v[20:23], v[164:167], v[210:213], v[20:23]
	v_mfma_f32_16x16x32_bf16 v[20:23], v[168:171], v[214:217], v[20:23]
	v_mfma_f32_16x16x32_bf16 v[16:19], v[186:189], v[210:213], v[16:19]
	v_mfma_f32_16x16x32_bf16 v[16:19], v[190:193], v[214:217], v[16:19]
	v_mfma_f32_16x16x32_bf16 v[4:7], v[164:167], v[218:221], v[4:7]
	v_mfma_f32_16x16x32_bf16 v[4:7], v[168:171], v[222:225], v[4:7]
	s_setprio 3
	s_barrier
	v_mfma_f32_16x16x32_bf16 v[0:3], v[186:189], v[218:221], v[0:3]
	v_mfma_f32_16x16x32_bf16 v[0:3], v[190:193], v[222:225], v[0:3]
	s_setprio 0
	s_add_i32 s68, s68, 2
	s_add_u32 s78, s78, 0x100
	s_addc_u32 s79, s79, 0
	s_add_u32 s66, s66, 0x100
	s_addc_u32 s67, s67, 0
	s_cmp_gt_u32 s68, 13
	s_cbranch_scc0 .LBB0_1760
	s_branch .Lzskip_8
.Lzv_8_0:
	s_barrier
	v_mfma_f32_16x16x32_bf16 v[124:127], v[128:131], v[194:197], 0
	v_mfma_f32_16x16x32_bf16 v[124:127], v[132:135], v[198:201], v[124:127]
	v_mfma_f32_16x16x32_bf16 v[120:123], v[136:139], v[194:197], 0
	v_mfma_f32_16x16x32_bf16 v[120:123], v[160:163], v[198:201], v[120:123]
	v_mfma_f32_16x16x32_bf16 v[108:111], v[128:131], v[202:205], 0
	v_mfma_f32_16x16x32_bf16 v[108:111], v[132:135], v[206:209], v[108:111]
	v_mfma_f32_16x16x32_bf16 v[104:107], v[136:139], v[202:205], 0
	v_mfma_f32_16x16x32_bf16 v[104:107], v[160:163], v[206:209], v[104:107]
	v_mfma_f32_16x16x32_bf16 v[92:95], v[128:131], v[210:213], 0
	v_mfma_f32_16x16x32_bf16 v[92:95], v[132:135], v[214:217], v[92:95]
	v_mfma_f32_16x16x32_bf16 v[88:91], v[136:139], v[210:213], 0
	v_mfma_f32_16x16x32_bf16 v[88:91], v[160:163], v[214:217], v[88:91]
	v_mfma_f32_16x16x32_bf16 v[76:79], v[128:131], v[218:221], 0
	v_mfma_f32_16x16x32_bf16 v[76:79], v[132:135], v[222:225], v[76:79]
	v_mfma_f32_16x16x32_bf16 v[72:75], v[136:139], v[218:221], 0
	v_mfma_f32_16x16x32_bf16 v[72:75], v[160:163], v[222:225], v[72:75]
	v_mfma_f32_16x16x32_bf16 v[116:119], v[164:167], v[194:197], 0
	v_mfma_f32_16x16x32_bf16 v[116:119], v[168:171], v[198:201], v[116:119]
	v_mfma_f32_16x16x32_bf16 v[112:115], v[186:189], v[194:197], 0
	v_mfma_f32_16x16x32_bf16 v[112:115], v[190:193], v[198:201], v[112:115]
	v_mfma_f32_16x16x32_bf16 v[100:103], v[164:167], v[202:205], 0
	v_mfma_f32_16x16x32_bf16 v[100:103], v[168:171], v[206:209], v[100:103]
	v_mfma_f32_16x16x32_bf16 v[96:99], v[186:189], v[202:205], 0
	v_mfma_f32_16x16x32_bf16 v[96:99], v[190:193], v[206:209], v[96:99]
	v_mfma_f32_16x16x32_bf16 v[84:87], v[164:167], v[210:213], 0
	v_mfma_f32_16x16x32_bf16 v[84:87], v[168:171], v[214:217], v[84:87]
	v_mfma_f32_16x16x32_bf16 v[80:83], v[186:189], v[210:213], 0
	v_mfma_f32_16x16x32_bf16 v[80:83], v[190:193], v[214:217], v[80:83]
	v_mfma_f32_16x16x32_bf16 v[68:71], v[164:167], v[218:221], 0
	v_mfma_f32_16x16x32_bf16 v[68:71], v[168:171], v[222:225], v[68:71]
	s_setprio 3
	s_barrier
	v_mfma_f32_16x16x32_bf16 v[64:67], v[186:189], v[218:221], 0
	v_mfma_f32_16x16x32_bf16 v[64:67], v[190:193], v[222:225], v[64:67]
	s_setprio 0
	s_branch .Lzj_8_0
.Lzv_8_1:
	s_barrier
	v_mfma_f32_16x16x32_bf16 v[60:63], v[128:131], v[194:197], 0
	v_mfma_f32_16x16x32_bf16 v[60:63], v[132:135], v[198:201], v[60:63]
	v_mfma_f32_16x16x32_bf16 v[56:59], v[136:139], v[194:197], 0
	v_mfma_f32_16x16x32_bf16 v[56:59], v[160:163], v[198:201], v[56:59]
	v_mfma_f32_16x16x32_bf16 v[44:47], v[128:131], v[202:205], 0
	v_mfma_f32_16x16x32_bf16 v[44:47], v[132:135], v[206:209], v[44:47]
	v_mfma_f32_16x16x32_bf16 v[40:43], v[136:139], v[202:205], 0
	v_mfma_f32_16x16x32_bf16 v[40:43], v[160:163], v[206:209], v[40:43]
	v_mfma_f32_16x16x32_bf16 v[28:31], v[128:131], v[210:213], 0
	v_mfma_f32_16x16x32_bf16 v[28:31], v[132:135], v[214:217], v[28:31]
	v_mfma_f32_16x16x32_bf16 v[24:27], v[136:139], v[210:213], 0
	v_mfma_f32_16x16x32_bf16 v[24:27], v[160:163], v[214:217], v[24:27]
	v_mfma_f32_16x16x32_bf16 v[12:15], v[128:131], v[218:221], 0
	v_mfma_f32_16x16x32_bf16 v[12:15], v[132:135], v[222:225], v[12:15]
	v_mfma_f32_16x16x32_bf16 v[8:11], v[136:139], v[218:221], 0
	v_mfma_f32_16x16x32_bf16 v[8:11], v[160:163], v[222:225], v[8:11]
	v_mfma_f32_16x16x32_bf16 v[52:55], v[164:167], v[194:197], 0
	v_mfma_f32_16x16x32_bf16 v[52:55], v[168:171], v[198:201], v[52:55]
	v_mfma_f32_16x16x32_bf16 v[48:51], v[186:189], v[194:197], 0
	v_mfma_f32_16x16x32_bf16 v[48:51], v[190:193], v[198:201], v[48:51]
	v_mfma_f32_16x16x32_bf16 v[36:39], v[164:167], v[202:205], 0
	v_mfma_f32_16x16x32_bf16 v[36:39], v[168:171], v[206:209], v[36:39]
	v_mfma_f32_16x16x32_bf16 v[32:35], v[186:189], v[202:205], 0
	v_mfma_f32_16x16x32_bf16 v[32:35], v[190:193], v[206:209], v[32:35]
	v_mfma_f32_16x16x32_bf16 v[20:23], v[164:167], v[210:213], 0
	v_mfma_f32_16x16x32_bf16 v[20:23], v[168:171], v[214:217], v[20:23]
	v_mfma_f32_16x16x32_bf16 v[16:19], v[186:189], v[210:213], 0
	v_mfma_f32_16x16x32_bf16 v[16:19], v[190:193], v[214:217], v[16:19]
	v_mfma_f32_16x16x32_bf16 v[4:7], v[164:167], v[218:221], 0
	v_mfma_f32_16x16x32_bf16 v[4:7], v[168:171], v[222:225], v[4:7]
	s_setprio 3
	s_barrier
	v_mfma_f32_16x16x32_bf16 v[0:3], v[186:189], v[218:221], 0
	v_mfma_f32_16x16x32_bf16 v[0:3], v[190:193], v[222:225], v[0:3]
	s_setprio 0
	s_branch .Lzj_8_1

.LBB0_2037:
	ds_read_b128 v[120:123], v245
	ds_read_b128 v[124:127], v245 offset:1024
	ds_read_b128 v[128:131], v245 offset:2048
	ds_read_b128 v[132:135], v245 offset:3072
	ds_read_b128 v[144:147], v246
	ds_read_b128 v[148:151], v246 offset:1024
	ds_read_b128 v[152:155], v246 offset:2048
	ds_read_b128 v[156:159], v246 offset:3072
	s_add_u32 s67, s76, 0xfffc0080
	s_addc_u32 s68, s77, -1
	s_cmp_eq_u32 s66, 12
	s_cselect_b32 s81, s53, s68
	s_cselect_b32 s80, s54, s67
	s_cselect_b32 s79, s51, s57
	s_cselect_b32 s78, s55, s56
	v_lshl_add_u64 v[204:205], s[76:77], 0, v[200:201]
	s_add_i32 m0, s16, 0xc000
	ds_read_b128 v[160:163], v247
	ds_read_b128 v[164:167], v247 offset:1024
	ds_read_b128 v[168:171], v247 offset:2048
	ds_read_b128 v[172:175], v247 offset:3072
	ds_read_b128 v[176:179], v247 offset:4096
	ds_read_b128 v[180:183], v247 offset:5120
	ds_read_b128 v[184:187], v247 offset:6144
	ds_read_b128 v[188:191], v247 offset:7168
	global_load_lds_dwordx4 v[204:205], off
	s_add_i32 m0, s16, 0xe000
	v_lshl_add_u64 v[204:205], s[76:77], 0, v[202:203]
	global_load_lds_dwordx4 v[204:205], off
	s_cmp_eq_u32 s66, -2
	s_waitcnt vmcnt(8) lgkmcnt(0)
	s_setprio 1
	s_cbranch_scc1 .Lzv_9_0
	s_barrier
	v_mfma_f32_16x16x32_bf16 v[140:143], v[120:123], v[160:163], v[140:143]
	v_mfma_f32_16x16x32_bf16 v[140:143], v[124:127], v[164:167], v[140:143]
	v_mfma_f32_16x16x32_bf16 v[136:139], v[128:131], v[160:163], v[136:139]
	v_mfma_f32_16x16x32_bf16 v[136:139], v[132:135], v[164:167], v[136:139]
	v_mfma_f32_16x16x32_bf16 v[108:111], v[120:123], v[168:171], v[108:111]
	v_mfma_f32_16x16x32_bf16 v[108:111], v[124:127], v[172:175], v[108:111]
	v_mfma_f32_16x16x32_bf16 v[104:107], v[128:131], v[168:171], v[104:107]
	v_mfma_f32_16x16x32_bf16 v[104:107], v[132:135], v[172:175], v[104:107]
	v_mfma_f32_16x16x32_bf16 v[92:95], v[120:123], v[176:179], v[92:95]
	v_mfma_f32_16x16x32_bf16 v[92:95], v[124:127], v[180:183], v[92:95]
	v_mfma_f32_16x16x32_bf16 v[88:91], v[128:131], v[176:179], v[88:91]
	v_mfma_f32_16x16x32_bf16 v[88:91], v[132:135], v[180:183], v[88:91]
	v_mfma_f32_16x16x32_bf16 v[76:79], v[120:123], v[184:187], v[76:79]
	v_mfma_f32_16x16x32_bf16 v[76:79], v[124:127], v[188:191], v[76:79]
	v_mfma_f32_16x16x32_bf16 v[72:75], v[128:131], v[184:187], v[72:75]
	v_mfma_f32_16x16x32_bf16 v[72:75], v[132:135], v[188:191], v[72:75]
	v_mfma_f32_16x16x32_bf16 v[116:119], v[144:147], v[160:163], v[116:119]
	v_mfma_f32_16x16x32_bf16 v[116:119], v[148:151], v[164:167], v[116:119]
	v_mfma_f32_16x16x32_bf16 v[112:115], v[152:155], v[160:163], v[112:115]
	v_mfma_f32_16x16x32_bf16 v[112:115], v[156:159], v[164:167], v[112:115]
	v_mfma_f32_16x16x32_bf16 v[100:103], v[144:147], v[168:171], v[100:103]
	v_mfma_f32_16x16x32_bf16 v[100:103], v[148:151], v[172:175], v[100:103]
	v_mfma_f32_16x16x32_bf16 v[96:99], v[152:155], v[168:171], v[96:99]
	v_mfma_f32_16x16x32_bf16 v[96:99], v[156:159], v[172:175], v[96:99]
	v_mfma_f32_16x16x32_bf16 v[84:87], v[144:147], v[176:179], v[84:87]
	v_mfma_f32_16x16x32_bf16 v[84:87], v[148:151], v[180:183], v[84:87]
	v_mfma_f32_16x16x32_bf16 v[80:83], v[152:155], v[176:179], v[80:83]
	v_mfma_f32_16x16x32_bf16 v[80:83], v[156:159], v[180:183], v[80:83]
	v_mfma_f32_16x16x32_bf16 v[68:71], v[144:147], v[184:187], v[68:71]
	v_mfma_f32_16x16x32_bf16 v[68:71], v[148:151], v[188:191], v[68:71]
	s_setprio 3
	s_barrier
	v_mfma_f32_16x16x32_bf16 v[64:67], v[152:155], v[184:187], v[64:67]
	v_mfma_f32_16x16x32_bf16 v[64:67], v[156:159], v[188:191], v[64:67]
	s_setprio 0
.Lzj_9_0:
	s_add_i32 s67, s26, s15
	v_lshl_add_u64 v[204:205], s[78:79], 0, v[194:195]
	s_mov_b32 m0, s67
	ds_read_b128 v[160:163], v247 offset:16384
	ds_read_b128 v[164:167], v247 offset:17408
	ds_read_b128 v[168:171], v247 offset:18432
	ds_read_b128 v[172:175], v247 offset:19456
	ds_read_b128 v[176:179], v247 offset:20480
	ds_read_b128 v[180:183], v247 offset:21504
	ds_read_b128 v[184:187], v247 offset:22528
	ds_read_b128 v[188:191], v247 offset:23552
	global_load_lds_dwordx4 v[204:205], off
	s_add_i32 m0, s67, 0x2000
	s_add_u32 s68, s78, 0x40000
	v_lshl_add_u64 v[206:207], s[78:79], 0, v[198:199]
	s_addc_u32 s69, s79, 0
	s_add_i32 s67, s27, s15
	global_load_lds_dwordx4 v[206:207], off
	v_lshl_add_u64 v[208:209], s[68:69], 0, v[194:195]
	s_mov_b32 m0, s67
	global_load_lds_dwordx4 v[208:209], off
	s_add_i32 m0, s67, 0x2000
	v_lshl_add_u64 v[208:209], s[68:69], 0, v[198:199]
	global_load_lds_dwordx4 v[208:209], off
	s_mov_b32 m0, s16
	v_lshl_add_u64 v[208:209], s[80:81], 0, v[192:193]
	global_load_lds_dwordx4 v[208:209], off
	s_mov_b32 m0, s17
	v_lshl_add_u64 v[210:211], s[80:81], 0, v[196:197]
	global_load_lds_dwordx4 v[210:211], off
	s_cmp_eq_u32 s66, -2
	s_waitcnt vmcnt(8) lgkmcnt(0)
	s_setprio 1
	s_cbranch_scc1 .Lzv_9_1
	s_barrier
	v_mfma_f32_16x16x32_bf16 v[60:63], v[120:123], v[160:163], v[60:63]
	v_mfma_f32_16x16x32_bf16 v[60:63], v[124:127], v[164:167], v[60:63]
	v_mfma_f32_16x16x32_bf16 v[56:59], v[128:131], v[160:163], v[56:59]
	v_mfma_f32_16x16x32_bf16 v[56:59], v[132:135], v[164:167], v[56:59]
	v_mfma_f32_16x16x32_bf16 v[44:47], v[120:123], v[168:171], v[44:47]
	v_mfma_f32_16x16x32_bf16 v[44:47], v[124:127], v[172:175], v[44:47]
	v_mfma_f32_16x16x32_bf16 v[40:43], v[128:131], v[168:171], v[40:43]
	v_mfma_f32_16x16x32_bf16 v[40:43], v[132:135], v[172:175], v[40:43]
	v_mfma_f32_16x16x32_bf16 v[28:31], v[120:123], v[176:179], v[28:31]
	v_mfma_f32_16x16x32_bf16 v[28:31], v[124:127], v[180:183], v[28:31]
	v_mfma_f32_16x16x32_bf16 v[24:27], v[128:131], v[176:179], v[24:27]
	v_mfma_f32_16x16x32_bf16 v[24:27], v[132:135], v[180:183], v[24:27]
	v_mfma_f32_16x16x32_bf16 v[12:15], v[120:123], v[184:187], v[12:15]
	v_mfma_f32_16x16x32_bf16 v[12:15], v[124:127], v[188:191], v[12:15]
	v_mfma_f32_16x16x32_bf16 v[8:11], v[128:131], v[184:187], v[8:11]
	v_mfma_f32_16x16x32_bf16 v[8:11], v[132:135], v[188:191], v[8:11]
	v_mfma_f32_16x16x32_bf16 v[52:55], v[144:147], v[160:163], v[52:55]
	v_mfma_f32_16x16x32_bf16 v[52:55], v[148:151], v[164:167], v[52:55]
	v_mfma_f32_16x16x32_bf16 v[48:51], v[152:155], v[160:163], v[48:51]
	v_mfma_f32_16x16x32_bf16 v[48:51], v[156:159], v[164:167], v[48:51]
	v_mfma_f32_16x16x32_bf16 v[36:39], v[144:147], v[168:171], v[36:39]
	v_mfma_f32_16x16x32_bf16 v[36:39], v[148:151], v[172:175], v[36:39]
	v_mfma_f32_16x16x32_bf16 v[32:35], v[152:155], v[168:171], v[32:35]
	v_mfma_f32_16x16x32_bf16 v[32:35], v[156:159], v[172:175], v[32:35]
	v_mfma_f32_16x16x32_bf16 v[20:23], v[144:147], v[176:179], v[20:23]
	v_mfma_f32_16x16x32_bf16 v[20:23], v[148:151], v[180:183], v[20:23]
	v_mfma_f32_16x16x32_bf16 v[16:19], v[152:155], v[176:179], v[16:19]
	v_mfma_f32_16x16x32_bf16 v[16:19], v[156:159], v[180:183], v[16:19]
	v_mfma_f32_16x16x32_bf16 v[4:7], v[144:147], v[184:187], v[4:7]
	v_mfma_f32_16x16x32_bf16 v[4:7], v[148:151], v[188:191], v[4:7]
	s_setprio 3
	s_barrier
	v_mfma_f32_16x16x32_bf16 v[0:3], v[152:155], v[184:187], v[0:3]
	v_mfma_f32_16x16x32_bf16 v[0:3], v[156:159], v[188:191], v[0:3]
	s_setprio 0
.Lzj_9_1:
	s_add_i32 s67, 0, 0x18000
	s_add_i32 s75, 0, 0x1c000
	v_add_u32_e32 v132, s67, v243
	v_add_u32_e32 v156, s75, v243
	ds_read_b128 v[120:123], v132
	ds_read_b128 v[124:127], v132 offset:1024
	ds_read_b128 v[128:131], v132 offset:2048
	ds_read_b128 v[132:135], v132 offset:3072
	ds_read_b128 v[144:147], v156
	ds_read_b128 v[148:151], v156 offset:1024
	ds_read_b128 v[152:155], v156 offset:2048
	ds_read_b128 v[156:159], v156 offset:3072
	s_add_u32 s68, s80, 0x40000
	s_addc_u32 s69, s81, 0
	s_mov_b32 m0, s18
	v_lshl_add_u64 v[212:213], s[68:69], 0, v[192:193]
	ds_read_b128 v[160:163], v247 offset:32768
	ds_read_b128 v[164:167], v247 offset:33792
	ds_read_b128 v[168:171], v247 offset:34816
	ds_read_b128 v[172:175], v247 offset:35840
	ds_read_b128 v[176:179], v247 offset:36864
	ds_read_b128 v[180:183], v247 offset:37888
	ds_read_b128 v[184:187], v247 offset:38912
	ds_read_b128 v[188:191], v247 offset:39936
	global_load_lds_dwordx4 v[212:213], off
	s_mov_b32 m0, s19
	v_lshl_add_u64 v[212:213], s[68:69], 0, v[196:197]
	global_load_lds_dwordx4 v[212:213], off
	s_waitcnt vmcnt(8) lgkmcnt(0)
	s_setprio 1
	s_barrier
	v_mfma_f32_16x16x32_bf16 v[140:143], v[120:123], v[160:163], v[140:143]
	v_mfma_f32_16x16x32_bf16 v[140:143], v[124:127], v[164:167], v[140:143]
	v_mfma_f32_16x16x32_bf16 v[136:139], v[128:131], v[160:163], v[136:139]
	v_mfma_f32_16x16x32_bf16 v[136:139], v[132:135], v[164:167], v[136:139]
	v_mfma_f32_16x16x32_bf16 v[108:111], v[120:123], v[168:171], v[108:111]
	v_mfma_f32_16x16x32_bf16 v[108:111], v[124:127], v[172:175], v[108:111]
	v_mfma_f32_16x16x32_bf16 v[104:107], v[128:131], v[168:171], v[104:107]
	v_mfma_f32_16x16x32_bf16 v[104:107], v[132:135], v[172:175], v[104:107]
	v_mfma_f32_16x16x32_bf16 v[92:95], v[120:123], v[176:179], v[92:95]
	v_mfma_f32_16x16x32_bf16 v[92:95], v[124:127], v[180:183], v[92:95]
	v_mfma_f32_16x16x32_bf16 v[88:91], v[128:131], v[176:179], v[88:91]
	v_mfma_f32_16x16x32_bf16 v[88:91], v[132:135], v[180:183], v[88:91]
	v_mfma_f32_16x16x32_bf16 v[76:79], v[120:123], v[184:187], v[76:79]
	v_mfma_f32_16x16x32_bf16 v[76:79], v[124:127], v[188:191], v[76:79]
	v_mfma_f32_16x16x32_bf16 v[72:75], v[128:131], v[184:187], v[72:75]
	v_mfma_f32_16x16x32_bf16 v[72:75], v[132:135], v[188:191], v[72:75]
	v_mfma_f32_16x16x32_bf16 v[116:119], v[144:147], v[160:163], v[116:119]
	v_mfma_f32_16x16x32_bf16 v[116:119], v[148:151], v[164:167], v[116:119]
	v_mfma_f32_16x16x32_bf16 v[112:115], v[152:155], v[160:163], v[112:115]
	v_mfma_f32_16x16x32_bf16 v[112:115], v[156:159], v[164:167], v[112:115]
	v_mfma_f32_16x16x32_bf16 v[100:103], v[144:147], v[168:171], v[100:103]
	v_mfma_f32_16x16x32_bf16 v[100:103], v[148:151], v[172:175], v[100:103]
	v_mfma_f32_16x16x32_bf16 v[96:99], v[152:155], v[168:171], v[96:99]
	v_mfma_f32_16x16x32_bf16 v[96:99], v[156:159], v[172:175], v[96:99]
	v_mfma_f32_16x16x32_bf16 v[84:87], v[144:147], v[176:179], v[84:87]
	v_mfma_f32_16x16x32_bf16 v[84:87], v[148:151], v[180:183], v[84:87]
	v_mfma_f32_16x16x32_bf16 v[80:83], v[152:155], v[176:179], v[80:83]
	v_mfma_f32_16x16x32_bf16 v[80:83], v[156:159], v[180:183], v[80:83]
	v_mfma_f32_16x16x32_bf16 v[68:71], v[144:147], v[184:187], v[68:71]
	v_mfma_f32_16x16x32_bf16 v[68:71], v[148:151], v[188:191], v[68:71]
	s_setprio 3
	s_barrier
	v_mfma_f32_16x16x32_bf16 v[64:67], v[152:155], v[184:187], v[64:67]
	v_mfma_f32_16x16x32_bf16 v[64:67], v[156:159], v[188:191], v[64:67]
	s_setprio 0
	s_add_i32 s67, s67, s15
	v_lshl_add_u64 v[204:205], v[204:205], 0, s[46:47]
	s_mov_b32 m0, s67
	ds_read_b128 v[160:163], v247 offset:49152
	ds_read_b128 v[164:167], v247 offset:50176
	ds_read_b128 v[168:171], v247 offset:51200
	ds_read_b128 v[172:175], v247 offset:52224
	ds_read_b128 v[176:179], v247 offset:53248
	ds_read_b128 v[180:183], v247 offset:54272
	ds_read_b128 v[184:187], v247 offset:55296
	ds_read_b128 v[188:191], v247 offset:56320
	global_load_lds_dwordx4 v[204:205], off
	s_add_i32 m0, s67, 0x2000
	s_add_u32 s68, s78, 0x40080
	v_lshl_add_u64 v[204:205], v[206:207], 0, s[46:47]
	s_addc_u32 s69, s79, 0
	s_add_i32 s67, s75, s15
	global_load_lds_dwordx4 v[204:205], off
	s_mov_b32 m0, s67
	v_lshl_add_u64 v[204:205], s[68:69], 0, v[194:195]
	global_load_lds_dwordx4 v[204:205], off
	s_add_i32 m0, s67, 0x2000
	v_lshl_add_u64 v[204:205], s[68:69], 0, v[198:199]
	global_load_lds_dwordx4 v[204:205], off
	s_mov_b32 m0, s21
	v_lshl_add_u64 v[204:205], v[208:209], 0, s[46:47]
	global_load_lds_dwordx4 v[204:205], off
	s_mov_b32 m0, s22
	v_lshl_add_u64 v[204:205], v[210:211], 0, s[46:47]
	global_load_lds_dwordx4 v[204:205], off
	s_waitcnt vmcnt(8) lgkmcnt(0)
	s_setprio 1
	s_barrier
	v_mfma_f32_16x16x32_bf16 v[60:63], v[120:123], v[160:163], v[60:63]
	v_mfma_f32_16x16x32_bf16 v[60:63], v[124:127], v[164:167], v[60:63]
	v_mfma_f32_16x16x32_bf16 v[56:59], v[128:131], v[160:163], v[56:59]
	v_mfma_f32_16x16x32_bf16 v[56:59], v[132:135], v[164:167], v[56:59]
	v_mfma_f32_16x16x32_bf16 v[44:47], v[120:123], v[168:171], v[44:47]
	v_mfma_f32_16x16x32_bf16 v[44:47], v[124:127], v[172:175], v[44:47]
	v_mfma_f32_16x16x32_bf16 v[40:43], v[128:131], v[168:171], v[40:43]
	v_mfma_f32_16x16x32_bf16 v[40:43], v[132:135], v[172:175], v[40:43]
	v_mfma_f32_16x16x32_bf16 v[28:31], v[120:123], v[176:179], v[28:31]
	v_mfma_f32_16x16x32_bf16 v[28:31], v[124:127], v[180:183], v[28:31]
	v_mfma_f32_16x16x32_bf16 v[24:27], v[128:131], v[176:179], v[24:27]
	v_mfma_f32_16x16x32_bf16 v[24:27], v[132:135], v[180:183], v[24:27]
	v_mfma_f32_16x16x32_bf16 v[12:15], v[120:123], v[184:187], v[12:15]
	v_mfma_f32_16x16x32_bf16 v[12:15], v[124:127], v[188:191], v[12:15]
	v_mfma_f32_16x16x32_bf16 v[8:11], v[128:131], v[184:187], v[8:11]
	v_mfma_f32_16x16x32_bf16 v[8:11], v[132:135], v[188:191], v[8:11]
	v_mfma_f32_16x16x32_bf16 v[52:55], v[144:147], v[160:163], v[52:55]
	v_mfma_f32_16x16x32_bf16 v[52:55], v[148:151], v[164:167], v[52:55]
	v_mfma_f32_16x16x32_bf16 v[48:51], v[152:155], v[160:163], v[48:51]
	v_mfma_f32_16x16x32_bf16 v[48:51], v[156:159], v[164:167], v[48:51]
	v_mfma_f32_16x16x32_bf16 v[36:39], v[144:147], v[168:171], v[36:39]
	v_mfma_f32_16x16x32_bf16 v[36:39], v[148:151], v[172:175], v[36:39]
	v_mfma_f32_16x16x32_bf16 v[32:35], v[152:155], v[168:171], v[32:35]
	v_mfma_f32_16x16x32_bf16 v[32:35], v[156:159], v[172:175], v[32:35]
	v_mfma_f32_16x16x32_bf16 v[20:23], v[144:147], v[176:179], v[20:23]
	v_mfma_f32_16x16x32_bf16 v[20:23], v[148:151], v[180:183], v[20:23]
	v_mfma_f32_16x16x32_bf16 v[16:19], v[152:155], v[176:179], v[16:19]
	v_mfma_f32_16x16x32_bf16 v[16:19], v[156:159], v[180:183], v[16:19]
	v_mfma_f32_16x16x32_bf16 v[4:7], v[144:147], v[184:187], v[4:7]
	v_mfma_f32_16x16x32_bf16 v[4:7], v[148:151], v[188:191], v[4:7]
	s_setprio 3
	s_barrier
	v_mfma_f32_16x16x32_bf16 v[0:3], v[152:155], v[184:187], v[0:3]
	v_mfma_f32_16x16x32_bf16 v[0:3], v[156:159], v[188:191], v[0:3]
	s_setprio 0
	s_add_i32 s66, s66, 2
	s_add_u32 s76, s76, 0x100
	s_addc_u32 s77, s77, 0
	s_add_u32 s56, s56, 0x100
	s_addc_u32 s57, s57, 0
	s_cmp_gt_u32 s66, 13
	s_cbranch_scc0 .LBB0_2037
	s_branch .Lzskip_9

.LBB0_2192:
	ds_read_b128 v[146:149], v174
	ds_read_b128 v[150:153], v174 offset:1024
	ds_read_b128 v[154:157], v174 offset:2048
	ds_read_b128 v[158:161], v174 offset:3072
	ds_read_b128 v[162:165], v175
	ds_read_b128 v[178:181], v175 offset:1024
	ds_read_b128 v[182:185], v175 offset:2048
	ds_read_b128 v[186:189], v175 offset:3072
	s_add_u32 s70, s58, 0xfffc0080
	s_addc_u32 s71, s59, -1
	s_cmp_eq_u32 s69, 12
	s_cselect_b32 s73, s47, s71
	s_cselect_b32 s72, s53, s70
	s_cselect_b32 s71, s45, s68
	s_cselect_b32 s70, s66, s67
	v_lshl_add_u64 v[166:167], s[58:59], 0, v[136:137]
	s_add_i32 m0, s17, 0xc000
	ds_read_b128 v[190:193], v176
	ds_read_b128 v[194:197], v176 offset:1024
	ds_read_b128 v[198:201], v176 offset:2048
	ds_read_b128 v[202:205], v176 offset:3072
	ds_read_b128 v[206:209], v176 offset:4096
	ds_read_b128 v[210:213], v176 offset:5120
	ds_read_b128 v[214:217], v176 offset:6144
	ds_read_b128 v[218:221], v176 offset:7168
	global_load_lds_dwordx4 v[166:167], off
	s_add_i32 m0, s17, 0xe000
	v_lshl_add_u64 v[166:167], s[58:59], 0, v[140:141]
	global_load_lds_dwordx4 v[166:167], off
	s_cmp_eq_u32 s69, -2
	s_waitcnt vmcnt(8) lgkmcnt(0)
	s_setprio 1
	s_cbranch_scc1 .Lzv_10_0
	s_barrier
	v_mfma_f32_16x16x32_bf16 v[124:127], v[146:149], v[190:193], v[124:127]
	v_mfma_f32_16x16x32_bf16 v[124:127], v[150:153], v[194:197], v[124:127]
	v_mfma_f32_16x16x32_bf16 v[116:119], v[154:157], v[190:193], v[116:119]
	v_mfma_f32_16x16x32_bf16 v[116:119], v[158:161], v[194:197], v[116:119]
	v_mfma_f32_16x16x32_bf16 v[108:111], v[146:149], v[198:201], v[108:111]
	v_mfma_f32_16x16x32_bf16 v[108:111], v[150:153], v[202:205], v[108:111]
	v_mfma_f32_16x16x32_bf16 v[100:103], v[154:157], v[198:201], v[100:103]
	v_mfma_f32_16x16x32_bf16 v[100:103], v[158:161], v[202:205], v[100:103]
	v_mfma_f32_16x16x32_bf16 v[92:95], v[146:149], v[206:209], v[92:95]
	v_mfma_f32_16x16x32_bf16 v[92:95], v[150:153], v[210:213], v[92:95]
	v_mfma_f32_16x16x32_bf16 v[84:87], v[154:157], v[206:209], v[84:87]
	v_mfma_f32_16x16x32_bf16 v[84:87], v[158:161], v[210:213], v[84:87]
	v_mfma_f32_16x16x32_bf16 v[76:79], v[146:149], v[214:217], v[76:79]
	v_mfma_f32_16x16x32_bf16 v[76:79], v[150:153], v[218:221], v[76:79]
	v_mfma_f32_16x16x32_bf16 v[68:71], v[154:157], v[214:217], v[68:71]
	v_mfma_f32_16x16x32_bf16 v[68:71], v[158:161], v[218:221], v[68:71]
	v_mfma_f32_16x16x32_bf16 v[120:123], v[162:165], v[190:193], v[120:123]
	v_mfma_f32_16x16x32_bf16 v[120:123], v[178:181], v[194:197], v[120:123]
	v_mfma_f32_16x16x32_bf16 v[112:115], v[182:185], v[190:193], v[112:115]
	v_mfma_f32_16x16x32_bf16 v[112:115], v[186:189], v[194:197], v[112:115]
	v_mfma_f32_16x16x32_bf16 v[104:107], v[162:165], v[198:201], v[104:107]
	v_mfma_f32_16x16x32_bf16 v[104:107], v[178:181], v[202:205], v[104:107]
	v_mfma_f32_16x16x32_bf16 v[96:99], v[182:185], v[198:201], v[96:99]
	v_mfma_f32_16x16x32_bf16 v[96:99], v[186:189], v[202:205], v[96:99]
	v_mfma_f32_16x16x32_bf16 v[88:91], v[162:165], v[206:209], v[88:91]
	v_mfma_f32_16x16x32_bf16 v[88:91], v[178:181], v[210:213], v[88:91]
	v_mfma_f32_16x16x32_bf16 v[80:83], v[182:185], v[206:209], v[80:83]
	v_mfma_f32_16x16x32_bf16 v[80:83], v[186:189], v[210:213], v[80:83]
	v_mfma_f32_16x16x32_bf16 v[72:75], v[162:165], v[214:217], v[72:75]
	v_mfma_f32_16x16x32_bf16 v[72:75], v[178:181], v[218:221], v[72:75]
	s_setprio 3
	s_barrier
	v_mfma_f32_16x16x32_bf16 v[64:67], v[182:185], v[214:217], v[64:67]
	v_mfma_f32_16x16x32_bf16 v[64:67], v[186:189], v[218:221], v[64:67]
	s_setprio 0
.Lzj_10_0:
	s_add_i32 s74, s26, s16
	v_lshl_add_u64 v[166:167], s[70:71], 0, v[132:133]
	s_mov_b32 m0, s74
	ds_read_b128 v[190:193], v176 offset:16384
	ds_read_b128 v[194:197], v176 offset:17408
	ds_read_b128 v[198:201], v176 offset:18432
	ds_read_b128 v[202:205], v176 offset:19456
	ds_read_b128 v[206:209], v176 offset:20480
	ds_read_b128 v[210:213], v176 offset:21504
	ds_read_b128 v[214:217], v176 offset:22528
	ds_read_b128 v[218:221], v176 offset:23552
	global_load_lds_dwordx4 v[166:167], off
	s_add_i32 m0, s74, 0x2000
	s_add_u32 s74, s70, 0x40000
	v_lshl_add_u64 v[222:223], s[70:71], 0, v[128:129]
	s_addc_u32 s75, s71, 0
	s_add_i32 s76, s27, s16
	global_load_lds_dwordx4 v[222:223], off
	v_lshl_add_u64 v[224:225], s[74:75], 0, v[132:133]
	s_mov_b32 m0, s76
	global_load_lds_dwordx4 v[224:225], off
	s_add_i32 m0, s76, 0x2000
	v_lshl_add_u64 v[224:225], s[74:75], 0, v[128:129]
	global_load_lds_dwordx4 v[224:225], off
	s_mov_b32 m0, s17
	v_lshl_add_u64 v[224:225], s[72:73], 0, v[134:135]
	global_load_lds_dwordx4 v[224:225], off
	s_mov_b32 m0, s18
	v_lshl_add_u64 v[226:227], s[72:73], 0, v[130:131]
	global_load_lds_dwordx4 v[226:227], off
	s_cmp_eq_u32 s69, -2
	s_waitcnt vmcnt(8) lgkmcnt(0)
	s_setprio 1
	s_cbranch_scc1 .Lzv_10_1
	s_barrier
	v_mfma_f32_16x16x32_bf16 v[60:63], v[146:149], v[190:193], v[60:63]
	v_mfma_f32_16x16x32_bf16 v[60:63], v[150:153], v[194:197], v[60:63]
	v_mfma_f32_16x16x32_bf16 v[52:55], v[154:157], v[190:193], v[52:55]
	v_mfma_f32_16x16x32_bf16 v[52:55], v[158:161], v[194:197], v[52:55]
	v_mfma_f32_16x16x32_bf16 v[44:47], v[146:149], v[198:201], v[44:47]
	v_mfma_f32_16x16x32_bf16 v[44:47], v[150:153], v[202:205], v[44:47]
	v_mfma_f32_16x16x32_bf16 v[36:39], v[154:157], v[198:201], v[36:39]
	v_mfma_f32_16x16x32_bf16 v[36:39], v[158:161], v[202:205], v[36:39]
	v_mfma_f32_16x16x32_bf16 v[28:31], v[146:149], v[206:209], v[28:31]
	v_mfma_f32_16x16x32_bf16 v[28:31], v[150:153], v[210:213], v[28:31]
	v_mfma_f32_16x16x32_bf16 v[20:23], v[154:157], v[206:209], v[20:23]
	v_mfma_f32_16x16x32_bf16 v[20:23], v[158:161], v[210:213], v[20:23]
	v_mfma_f32_16x16x32_bf16 v[12:15], v[146:149], v[214:217], v[12:15]
	v_mfma_f32_16x16x32_bf16 v[12:15], v[150:153], v[218:221], v[12:15]
	v_mfma_f32_16x16x32_bf16 v[4:7], v[154:157], v[214:217], v[4:7]
	v_mfma_f32_16x16x32_bf16 v[4:7], v[158:161], v[218:221], v[4:7]
	v_mfma_f32_16x16x32_bf16 v[56:59], v[162:165], v[190:193], v[56:59]
	v_mfma_f32_16x16x32_bf16 v[56:59], v[178:181], v[194:197], v[56:59]
	v_mfma_f32_16x16x32_bf16 v[48:51], v[182:185], v[190:193], v[48:51]
	v_mfma_f32_16x16x32_bf16 v[48:51], v[186:189], v[194:197], v[48:51]
	v_mfma_f32_16x16x32_bf16 v[40:43], v[162:165], v[198:201], v[40:43]
	v_mfma_f32_16x16x32_bf16 v[40:43], v[178:181], v[202:205], v[40:43]
	v_mfma_f32_16x16x32_bf16 v[32:35], v[182:185], v[198:201], v[32:35]
	v_mfma_f32_16x16x32_bf16 v[32:35], v[186:189], v[202:205], v[32:35]
	v_mfma_f32_16x16x32_bf16 v[24:27], v[162:165], v[206:209], v[24:27]
	v_mfma_f32_16x16x32_bf16 v[24:27], v[178:181], v[210:213], v[24:27]
	v_mfma_f32_16x16x32_bf16 v[16:19], v[182:185], v[206:209], v[16:19]
	v_mfma_f32_16x16x32_bf16 v[16:19], v[186:189], v[210:213], v[16:19]
	v_mfma_f32_16x16x32_bf16 v[8:11], v[162:165], v[214:217], v[8:11]
	v_mfma_f32_16x16x32_bf16 v[8:11], v[178:181], v[218:221], v[8:11]
	s_setprio 3
	s_barrier
	v_mfma_f32_16x16x32_bf16 v[0:3], v[182:185], v[214:217], v[0:3]
	v_mfma_f32_16x16x32_bf16 v[0:3], v[186:189], v[218:221], v[0:3]
	s_setprio 0
.Lzj_10_1:
	s_add_i32 s74, 0, 0x18000
	s_add_i32 s75, 0, 0x1c000
	v_add_u32_e32 v158, s74, v171
	v_add_u32_e32 v186, s75, v171
	ds_read_b128 v[146:149], v158
	ds_read_b128 v[150:153], v158 offset:1024
	ds_read_b128 v[154:157], v158 offset:2048
	ds_read_b128 v[158:161], v158 offset:3072
	ds_read_b128 v[162:165], v186
	ds_read_b128 v[178:181], v186 offset:1024
	ds_read_b128 v[182:185], v186 offset:2048
	ds_read_b128 v[186:189], v186 offset:3072
	s_add_u32 s72, s72, 0x40000
	s_addc_u32 s73, s73, 0
	s_mov_b32 m0, s19
	v_lshl_add_u64 v[228:229], s[72:73], 0, v[134:135]
	ds_read_b128 v[190:193], v176 offset:32768
	ds_read_b128 v[194:197], v176 offset:33792
	ds_read_b128 v[198:201], v176 offset:34816
	ds_read_b128 v[202:205], v176 offset:35840
	ds_read_b128 v[206:209], v176 offset:36864
	ds_read_b128 v[210:213], v176 offset:37888
	ds_read_b128 v[214:217], v176 offset:38912
	ds_read_b128 v[218:221], v176 offset:39936
	global_load_lds_dwordx4 v[228:229], off
	s_mov_b32 m0, s20
	v_lshl_add_u64 v[228:229], s[72:73], 0, v[130:131]
	global_load_lds_dwordx4 v[228:229], off
	s_waitcnt vmcnt(8) lgkmcnt(0)
	s_setprio 1
	s_barrier
	v_mfma_f32_16x16x32_bf16 v[124:127], v[146:149], v[190:193], v[124:127]
	v_mfma_f32_16x16x32_bf16 v[124:127], v[150:153], v[194:197], v[124:127]
	v_mfma_f32_16x16x32_bf16 v[116:119], v[154:157], v[190:193], v[116:119]
	v_mfma_f32_16x16x32_bf16 v[116:119], v[158:161], v[194:197], v[116:119]
	v_mfma_f32_16x16x32_bf16 v[108:111], v[146:149], v[198:201], v[108:111]
	v_mfma_f32_16x16x32_bf16 v[108:111], v[150:153], v[202:205], v[108:111]
	v_mfma_f32_16x16x32_bf16 v[100:103], v[154:157], v[198:201], v[100:103]
	v_mfma_f32_16x16x32_bf16 v[100:103], v[158:161], v[202:205], v[100:103]
	v_mfma_f32_16x16x32_bf16 v[92:95], v[146:149], v[206:209], v[92:95]
	v_mfma_f32_16x16x32_bf16 v[92:95], v[150:153], v[210:213], v[92:95]
	v_mfma_f32_16x16x32_bf16 v[84:87], v[154:157], v[206:209], v[84:87]
	v_mfma_f32_16x16x32_bf16 v[84:87], v[158:161], v[210:213], v[84:87]
	v_mfma_f32_16x16x32_bf16 v[76:79], v[146:149], v[214:217], v[76:79]
	v_mfma_f32_16x16x32_bf16 v[76:79], v[150:153], v[218:221], v[76:79]
	v_mfma_f32_16x16x32_bf16 v[68:71], v[154:157], v[214:217], v[68:71]
	v_mfma_f32_16x16x32_bf16 v[68:71], v[158:161], v[218:221], v[68:71]
	v_mfma_f32_16x16x32_bf16 v[120:123], v[162:165], v[190:193], v[120:123]
	v_mfma_f32_16x16x32_bf16 v[120:123], v[178:181], v[194:197], v[120:123]
	v_mfma_f32_16x16x32_bf16 v[112:115], v[182:185], v[190:193], v[112:115]
	v_mfma_f32_16x16x32_bf16 v[112:115], v[186:189], v[194:197], v[112:115]
	v_mfma_f32_16x16x32_bf16 v[104:107], v[162:165], v[198:201], v[104:107]
	v_mfma_f32_16x16x32_bf16 v[104:107], v[178:181], v[202:205], v[104:107]
	v_mfma_f32_16x16x32_bf16 v[96:99], v[182:185], v[198:201], v[96:99]
	v_mfma_f32_16x16x32_bf16 v[96:99], v[186:189], v[202:205], v[96:99]
	v_mfma_f32_16x16x32_bf16 v[88:91], v[162:165], v[206:209], v[88:91]
	v_mfma_f32_16x16x32_bf16 v[88:91], v[178:181], v[210:213], v[88:91]
	v_mfma_f32_16x16x32_bf16 v[80:83], v[182:185], v[206:209], v[80:83]
	v_mfma_f32_16x16x32_bf16 v[80:83], v[186:189], v[210:213], v[80:83]
	v_mfma_f32_16x16x32_bf16 v[72:75], v[162:165], v[214:217], v[72:75]
	v_mfma_f32_16x16x32_bf16 v[72:75], v[178:181], v[218:221], v[72:75]
	s_setprio 3
	s_barrier
	v_mfma_f32_16x16x32_bf16 v[64:67], v[182:185], v[214:217], v[64:67]
	v_mfma_f32_16x16x32_bf16 v[64:67], v[186:189], v[218:221], v[64:67]
	s_setprio 0
	s_add_i32 s72, s74, s16
	v_lshl_add_u64 v[166:167], v[166:167], 0, s[10:11]
	s_mov_b32 m0, s72
	ds_read_b128 v[190:193], v176 offset:49152
	ds_read_b128 v[194:197], v176 offset:50176
	ds_read_b128 v[198:201], v176 offset:51200
	ds_read_b128 v[202:205], v176 offset:52224
	ds_read_b128 v[206:209], v176 offset:53248
	ds_read_b128 v[210:213], v176 offset:54272
	ds_read_b128 v[214:217], v176 offset:55296
	ds_read_b128 v[218:221], v176 offset:56320
	global_load_lds_dwordx4 v[166:167], off
	s_add_i32 m0, s72, 0x2000
	s_add_u32 s70, s70, 0x40080
	v_lshl_add_u64 v[166:167], v[222:223], 0, s[10:11]
	s_addc_u32 s71, s71, 0
	s_add_i32 s72, s75, s16
	global_load_lds_dwordx4 v[166:167], off
	s_mov_b32 m0, s72
	v_lshl_add_u64 v[166:167], s[70:71], 0, v[132:133]
	global_load_lds_dwordx4 v[166:167], off
	s_add_i32 m0, s72, 0x2000
	v_lshl_add_u64 v[166:167], s[70:71], 0, v[128:129]
	global_load_lds_dwordx4 v[166:167], off
	s_mov_b32 m0, s23
	v_lshl_add_u64 v[166:167], v[224:225], 0, s[10:11]
	global_load_lds_dwordx4 v[166:167], off
	s_mov_b32 m0, s24
	v_lshl_add_u64 v[166:167], v[226:227], 0, s[10:11]
	global_load_lds_dwordx4 v[166:167], off
	s_waitcnt vmcnt(8) lgkmcnt(0)
	s_setprio 1
	s_barrier
	v_mfma_f32_16x16x32_bf16 v[60:63], v[146:149], v[190:193], v[60:63]
	v_mfma_f32_16x16x32_bf16 v[60:63], v[150:153], v[194:197], v[60:63]
	v_mfma_f32_16x16x32_bf16 v[52:55], v[154:157], v[190:193], v[52:55]
	v_mfma_f32_16x16x32_bf16 v[52:55], v[158:161], v[194:197], v[52:55]
	v_mfma_f32_16x16x32_bf16 v[44:47], v[146:149], v[198:201], v[44:47]
	v_mfma_f32_16x16x32_bf16 v[44:47], v[150:153], v[202:205], v[44:47]
	v_mfma_f32_16x16x32_bf16 v[36:39], v[154:157], v[198:201], v[36:39]
	v_mfma_f32_16x16x32_bf16 v[36:39], v[158:161], v[202:205], v[36:39]
	v_mfma_f32_16x16x32_bf16 v[28:31], v[146:149], v[206:209], v[28:31]
	v_mfma_f32_16x16x32_bf16 v[28:31], v[150:153], v[210:213], v[28:31]
	v_mfma_f32_16x16x32_bf16 v[20:23], v[154:157], v[206:209], v[20:23]
	v_mfma_f32_16x16x32_bf16 v[20:23], v[158:161], v[210:213], v[20:23]
	v_mfma_f32_16x16x32_bf16 v[12:15], v[146:149], v[214:217], v[12:15]
	v_mfma_f32_16x16x32_bf16 v[12:15], v[150:153], v[218:221], v[12:15]
	v_mfma_f32_16x16x32_bf16 v[4:7], v[154:157], v[214:217], v[4:7]
	v_mfma_f32_16x16x32_bf16 v[4:7], v[158:161], v[218:221], v[4:7]
	v_mfma_f32_16x16x32_bf16 v[56:59], v[162:165], v[190:193], v[56:59]
	v_mfma_f32_16x16x32_bf16 v[56:59], v[178:181], v[194:197], v[56:59]
	v_mfma_f32_16x16x32_bf16 v[48:51], v[182:185], v[190:193], v[48:51]
	v_mfma_f32_16x16x32_bf16 v[48:51], v[186:189], v[194:197], v[48:51]
	v_mfma_f32_16x16x32_bf16 v[40:43], v[162:165], v[198:201], v[40:43]
	v_mfma_f32_16x16x32_bf16 v[40:43], v[178:181], v[202:205], v[40:43]
	v_mfma_f32_16x16x32_bf16 v[32:35], v[182:185], v[198:201], v[32:35]
	v_mfma_f32_16x16x32_bf16 v[32:35], v[186:189], v[202:205], v[32:35]
	v_mfma_f32_16x16x32_bf16 v[24:27], v[162:165], v[206:209], v[24:27]
	v_mfma_f32_16x16x32_bf16 v[24:27], v[178:181], v[210:213], v[24:27]
	v_mfma_f32_16x16x32_bf16 v[16:19], v[182:185], v[206:209], v[16:19]
	v_mfma_f32_16x16x32_bf16 v[16:19], v[186:189], v[210:213], v[16:19]
	v_mfma_f32_16x16x32_bf16 v[8:11], v[162:165], v[214:217], v[8:11]
	v_mfma_f32_16x16x32_bf16 v[8:11], v[178:181], v[218:221], v[8:11]
	s_setprio 3
	s_barrier
	v_mfma_f32_16x16x32_bf16 v[0:3], v[182:185], v[214:217], v[0:3]
	v_mfma_f32_16x16x32_bf16 v[0:3], v[186:189], v[218:221], v[0:3]
	s_setprio 0
	s_add_i32 s69, s69, 2
	s_add_u32 s58, s58, 0x100
	s_addc_u32 s59, s59, 0
	s_add_u32 s67, s67, 0x100
	s_addc_u32 s68, s68, 0
	s_cmp_gt_u32 s69, 13
	s_cbranch_scc0 .LBB0_2192
	s_branch .Lzskip_10

.LBB0_2341:
	ds_read_b128 v[128:131], v197
	ds_read_b128 v[132:135], v197 offset:1024
	ds_read_b128 v[136:139], v197 offset:2048
	ds_read_b128 v[140:143], v197 offset:3072
	ds_read_b128 v[144:147], v198
	ds_read_b128 v[148:151], v198 offset:1024
	ds_read_b128 v[152:155], v198 offset:2048
	ds_read_b128 v[156:159], v198 offset:3072
	s_add_u32 s18, s16, 0xfff50080
	s_addc_u32 s19, s17, -1
	s_cmp_eq_u32 s45, 40
	s_cselect_b32 s21, s5, s19
	s_cselect_b32 s20, s4, s18
	s_cselect_b32 s19, s15, s44
	s_cselect_b32 s18, s14, s43
	v_lshl_add_u64 v[192:193], s[16:17], 0, v[172:173]
	s_add_i32 m0, s25, 0xc000
	ds_read_b128 v[160:163], v199
	ds_read_b128 v[180:183], v199 offset:1024
	ds_read_b128 v[184:187], v199 offset:2048
	ds_read_b128 v[188:191], v199 offset:3072
	ds_read_b128 v[200:203], v199 offset:4096
	ds_read_b128 v[204:207], v199 offset:5120
	ds_read_b128 v[208:211], v199 offset:6144
	ds_read_b128 v[212:215], v199 offset:7168
	global_load_lds_dwordx4 v[192:193], off
	s_add_i32 m0, s25, 0xe000
	v_lshl_add_u64 v[192:193], s[16:17], 0, v[174:175]
	global_load_lds_dwordx4 v[192:193], off
	s_cmp_eq_u32 s45, -2
	s_waitcnt vmcnt(8) lgkmcnt(0)
	s_setprio 1
	s_cbranch_scc1 .Lzv_11_0
	s_barrier
	v_mfma_f32_16x16x32_bf16 v[124:127], v[128:131], v[160:163], v[124:127]
	v_mfma_f32_16x16x32_bf16 v[124:127], v[132:135], v[180:183], v[124:127]
	v_mfma_f32_16x16x32_bf16 v[120:123], v[136:139], v[160:163], v[120:123]
	v_mfma_f32_16x16x32_bf16 v[120:123], v[140:143], v[180:183], v[120:123]
	v_mfma_f32_16x16x32_bf16 v[108:111], v[128:131], v[184:187], v[108:111]
	v_mfma_f32_16x16x32_bf16 v[108:111], v[132:135], v[188:191], v[108:111]
	v_mfma_f32_16x16x32_bf16 v[104:107], v[136:139], v[184:187], v[104:107]
	v_mfma_f32_16x16x32_bf16 v[104:107], v[140:143], v[188:191], v[104:107]
	v_mfma_f32_16x16x32_bf16 v[96:99], v[128:131], v[200:203], v[96:99]
	v_mfma_f32_16x16x32_bf16 v[96:99], v[132:135], v[204:207], v[96:99]
	v_mfma_f32_16x16x32_bf16 v[88:91], v[136:139], v[200:203], v[88:91]
	v_mfma_f32_16x16x32_bf16 v[88:91], v[140:143], v[204:207], v[88:91]
	v_mfma_f32_16x16x32_bf16 v[80:83], v[128:131], v[208:211], v[80:83]
	v_mfma_f32_16x16x32_bf16 v[80:83], v[132:135], v[212:215], v[80:83]
	v_mfma_f32_16x16x32_bf16 v[72:75], v[136:139], v[208:211], v[72:75]
	v_mfma_f32_16x16x32_bf16 v[72:75], v[140:143], v[212:215], v[72:75]
	v_mfma_f32_16x16x32_bf16 v[116:119], v[144:147], v[160:163], v[116:119]
	v_mfma_f32_16x16x32_bf16 v[116:119], v[148:151], v[180:183], v[116:119]
	v_mfma_f32_16x16x32_bf16 v[112:115], v[152:155], v[160:163], v[112:115]
	v_mfma_f32_16x16x32_bf16 v[112:115], v[156:159], v[180:183], v[112:115]
	v_mfma_f32_16x16x32_bf16 v[100:103], v[144:147], v[184:187], v[100:103]
	v_mfma_f32_16x16x32_bf16 v[100:103], v[148:151], v[188:191], v[100:103]
	v_mfma_f32_16x16x32_bf16 v[92:95], v[152:155], v[184:187], v[92:95]
	v_mfma_f32_16x16x32_bf16 v[92:95], v[156:159], v[188:191], v[92:95]
	v_mfma_f32_16x16x32_bf16 v[84:87], v[144:147], v[200:203], v[84:87]
	v_mfma_f32_16x16x32_bf16 v[84:87], v[148:151], v[204:207], v[84:87]
	v_mfma_f32_16x16x32_bf16 v[76:79], v[152:155], v[200:203], v[76:79]
	v_mfma_f32_16x16x32_bf16 v[76:79], v[156:159], v[204:207], v[76:79]
	v_mfma_f32_16x16x32_bf16 v[68:71], v[144:147], v[208:211], v[68:71]
	v_mfma_f32_16x16x32_bf16 v[68:71], v[148:151], v[212:215], v[68:71]
	s_setprio 3
	s_barrier
	v_mfma_f32_16x16x32_bf16 v[64:67], v[152:155], v[208:211], v[64:67]
	v_mfma_f32_16x16x32_bf16 v[64:67], v[156:159], v[212:215], v[64:67]
	s_setprio 0
.Lzj_11_0:
	s_add_i32 s46, s37, s24
	v_lshl_add_u64 v[192:193], s[18:19], 0, v[166:167]
	s_mov_b32 m0, s46
	ds_read_b128 v[160:163], v199 offset:16384
	ds_read_b128 v[180:183], v199 offset:17408
	ds_read_b128 v[184:187], v199 offset:18432
	ds_read_b128 v[188:191], v199 offset:19456
	ds_read_b128 v[200:203], v199 offset:20480
	ds_read_b128 v[204:207], v199 offset:21504
	ds_read_b128 v[208:211], v199 offset:22528
	ds_read_b128 v[212:215], v199 offset:23552
	global_load_lds_dwordx4 v[192:193], off
	s_add_i32 m0, s46, 0x2000
	s_add_u32 s46, s18, 0xb0000
	v_lshl_add_u64 v[216:217], s[18:19], 0, v[170:171]
	s_addc_u32 s47, s19, 0
	s_add_i32 s48, s38, s24
	global_load_lds_dwordx4 v[216:217], off
	v_lshl_add_u64 v[218:219], s[46:47], 0, v[166:167]
	s_mov_b32 m0, s48
	global_load_lds_dwordx4 v[218:219], off
	s_add_i32 m0, s48, 0x2000
	v_lshl_add_u64 v[218:219], s[46:47], 0, v[170:171]
	global_load_lds_dwordx4 v[218:219], off
	s_mov_b32 m0, s25
	v_lshl_add_u64 v[218:219], s[20:21], 0, v[164:165]
	global_load_lds_dwordx4 v[218:219], off
	s_mov_b32 m0, s26
	v_lshl_add_u64 v[220:221], s[20:21], 0, v[168:169]
	global_load_lds_dwordx4 v[220:221], off
	s_cmp_eq_u32 s45, -2
	s_waitcnt vmcnt(8) lgkmcnt(0)
	s_setprio 1
	s_cbranch_scc1 .Lzv_11_1
	s_barrier
	v_mfma_f32_16x16x32_bf16 v[60:63], v[128:131], v[160:163], v[60:63]
	v_mfma_f32_16x16x32_bf16 v[60:63], v[132:135], v[180:183], v[60:63]
	v_mfma_f32_16x16x32_bf16 v[56:59], v[136:139], v[160:163], v[56:59]
	v_mfma_f32_16x16x32_bf16 v[56:59], v[140:143], v[180:183], v[56:59]
	v_mfma_f32_16x16x32_bf16 v[48:51], v[128:131], v[184:187], v[48:51]
	v_mfma_f32_16x16x32_bf16 v[48:51], v[132:135], v[188:191], v[48:51]
	v_mfma_f32_16x16x32_bf16 v[40:43], v[136:139], v[184:187], v[40:43]
	v_mfma_f32_16x16x32_bf16 v[40:43], v[140:143], v[188:191], v[40:43]
	v_mfma_f32_16x16x32_bf16 v[32:35], v[128:131], v[200:203], v[32:35]
	v_mfma_f32_16x16x32_bf16 v[32:35], v[132:135], v[204:207], v[32:35]
	v_mfma_f32_16x16x32_bf16 v[24:27], v[136:139], v[200:203], v[24:27]
	v_mfma_f32_16x16x32_bf16 v[24:27], v[140:143], v[204:207], v[24:27]
	v_mfma_f32_16x16x32_bf16 v[16:19], v[128:131], v[208:211], v[16:19]
	v_mfma_f32_16x16x32_bf16 v[16:19], v[132:135], v[212:215], v[16:19]
	v_mfma_f32_16x16x32_bf16 v[8:11], v[136:139], v[208:211], v[8:11]
	v_mfma_f32_16x16x32_bf16 v[8:11], v[140:143], v[212:215], v[8:11]
	v_mfma_f32_16x16x32_bf16 v[52:55], v[144:147], v[160:163], v[52:55]
	v_mfma_f32_16x16x32_bf16 v[52:55], v[148:151], v[180:183], v[52:55]
	v_mfma_f32_16x16x32_bf16 v[44:47], v[152:155], v[160:163], v[44:47]
	v_mfma_f32_16x16x32_bf16 v[44:47], v[156:159], v[180:183], v[44:47]
	v_mfma_f32_16x16x32_bf16 v[36:39], v[144:147], v[184:187], v[36:39]
	v_mfma_f32_16x16x32_bf16 v[36:39], v[148:151], v[188:191], v[36:39]
	v_mfma_f32_16x16x32_bf16 v[28:31], v[152:155], v[184:187], v[28:31]
	v_mfma_f32_16x16x32_bf16 v[28:31], v[156:159], v[188:191], v[28:31]
	v_mfma_f32_16x16x32_bf16 v[20:23], v[144:147], v[200:203], v[20:23]
	v_mfma_f32_16x16x32_bf16 v[20:23], v[148:151], v[204:207], v[20:23]
	v_mfma_f32_16x16x32_bf16 v[12:15], v[152:155], v[200:203], v[12:15]
	v_mfma_f32_16x16x32_bf16 v[12:15], v[156:159], v[204:207], v[12:15]
	v_mfma_f32_16x16x32_bf16 v[4:7], v[144:147], v[208:211], v[4:7]
	v_mfma_f32_16x16x32_bf16 v[4:7], v[148:151], v[212:215], v[4:7]
	s_setprio 3
	s_barrier
	v_mfma_f32_16x16x32_bf16 v[0:3], v[152:155], v[208:211], v[0:3]
	v_mfma_f32_16x16x32_bf16 v[0:3], v[156:159], v[212:215], v[0:3]
	s_setprio 0
.Lzj_11_1:
	s_add_i32 s46, 0, 0x18000
	s_add_i32 s47, 0, 0x1c000
	v_add_u32_e32 v140, s46, v195
	v_add_u32_e32 v156, s47, v195
	ds_read_b128 v[128:131], v140
	ds_read_b128 v[132:135], v140 offset:1024
	ds_read_b128 v[136:139], v140 offset:2048
	ds_read_b128 v[140:143], v140 offset:3072
	ds_read_b128 v[144:147], v156
	ds_read_b128 v[148:151], v156 offset:1024
	ds_read_b128 v[152:155], v156 offset:2048
	ds_read_b128 v[156:159], v156 offset:3072
	s_add_u32 s20, s20, 0xb0000
	s_addc_u32 s21, s21, 0
	s_mov_b32 m0, s27
	v_lshl_add_u64 v[222:223], s[20:21], 0, v[164:165]
	ds_read_b128 v[160:163], v199 offset:32768
	ds_read_b128 v[180:183], v199 offset:33792
	ds_read_b128 v[184:187], v199 offset:34816
	ds_read_b128 v[188:191], v199 offset:35840
	ds_read_b128 v[200:203], v199 offset:36864
	ds_read_b128 v[204:207], v199 offset:37888
	ds_read_b128 v[208:211], v199 offset:38912
	ds_read_b128 v[212:215], v199 offset:39936
	global_load_lds_dwordx4 v[222:223], off
	s_mov_b32 m0, s28
	v_lshl_add_u64 v[222:223], s[20:21], 0, v[168:169]
	global_load_lds_dwordx4 v[222:223], off
	s_waitcnt vmcnt(8) lgkmcnt(0)
	s_setprio 1
	s_barrier
	v_mfma_f32_16x16x32_bf16 v[124:127], v[128:131], v[160:163], v[124:127]
	v_mfma_f32_16x16x32_bf16 v[124:127], v[132:135], v[180:183], v[124:127]
	v_mfma_f32_16x16x32_bf16 v[120:123], v[136:139], v[160:163], v[120:123]
	v_mfma_f32_16x16x32_bf16 v[120:123], v[140:143], v[180:183], v[120:123]
	v_mfma_f32_16x16x32_bf16 v[108:111], v[128:131], v[184:187], v[108:111]
	v_mfma_f32_16x16x32_bf16 v[108:111], v[132:135], v[188:191], v[108:111]
	v_mfma_f32_16x16x32_bf16 v[104:107], v[136:139], v[184:187], v[104:107]
	v_mfma_f32_16x16x32_bf16 v[104:107], v[140:143], v[188:191], v[104:107]
	v_mfma_f32_16x16x32_bf16 v[96:99], v[128:131], v[200:203], v[96:99]
	v_mfma_f32_16x16x32_bf16 v[96:99], v[132:135], v[204:207], v[96:99]
	v_mfma_f32_16x16x32_bf16 v[88:91], v[136:139], v[200:203], v[88:91]
	v_mfma_f32_16x16x32_bf16 v[88:91], v[140:143], v[204:207], v[88:91]
	v_mfma_f32_16x16x32_bf16 v[80:83], v[128:131], v[208:211], v[80:83]
	v_mfma_f32_16x16x32_bf16 v[80:83], v[132:135], v[212:215], v[80:83]
	v_mfma_f32_16x16x32_bf16 v[72:75], v[136:139], v[208:211], v[72:75]
	v_mfma_f32_16x16x32_bf16 v[72:75], v[140:143], v[212:215], v[72:75]
	v_mfma_f32_16x16x32_bf16 v[116:119], v[144:147], v[160:163], v[116:119]
	v_mfma_f32_16x16x32_bf16 v[116:119], v[148:151], v[180:183], v[116:119]
	v_mfma_f32_16x16x32_bf16 v[112:115], v[152:155], v[160:163], v[112:115]
	v_mfma_f32_16x16x32_bf16 v[112:115], v[156:159], v[180:183], v[112:115]
	v_mfma_f32_16x16x32_bf16 v[100:103], v[144:147], v[184:187], v[100:103]
	v_mfma_f32_16x16x32_bf16 v[100:103], v[148:151], v[188:191], v[100:103]
	v_mfma_f32_16x16x32_bf16 v[92:95], v[152:155], v[184:187], v[92:95]
	v_mfma_f32_16x16x32_bf16 v[92:95], v[156:159], v[188:191], v[92:95]
	v_mfma_f32_16x16x32_bf16 v[84:87], v[144:147], v[200:203], v[84:87]
	v_mfma_f32_16x16x32_bf16 v[84:87], v[148:151], v[204:207], v[84:87]
	v_mfma_f32_16x16x32_bf16 v[76:79], v[152:155], v[200:203], v[76:79]
	v_mfma_f32_16x16x32_bf16 v[76:79], v[156:159], v[204:207], v[76:79]
	v_mfma_f32_16x16x32_bf16 v[68:71], v[144:147], v[208:211], v[68:71]
	v_mfma_f32_16x16x32_bf16 v[68:71], v[148:151], v[212:215], v[68:71]
	s_setprio 3
	s_barrier
	v_mfma_f32_16x16x32_bf16 v[64:67], v[152:155], v[208:211], v[64:67]
	v_mfma_f32_16x16x32_bf16 v[64:67], v[156:159], v[212:215], v[64:67]
	s_setprio 0
	s_add_i32 s20, s46, s24
	v_lshl_add_u64 v[192:193], v[192:193], 0, s[8:9]
	s_mov_b32 m0, s20
	ds_read_b128 v[160:163], v199 offset:49152
	ds_read_b128 v[180:183], v199 offset:50176
	ds_read_b128 v[184:187], v199 offset:51200
	ds_read_b128 v[188:191], v199 offset:52224
	ds_read_b128 v[200:203], v199 offset:53248
	ds_read_b128 v[204:207], v199 offset:54272
	ds_read_b128 v[208:211], v199 offset:55296
	ds_read_b128 v[212:215], v199 offset:56320
	global_load_lds_dwordx4 v[192:193], off
	s_add_i32 m0, s20, 0x2000
	s_add_u32 s18, s18, 0xb0080
	v_lshl_add_u64 v[192:193], v[216:217], 0, s[8:9]
	s_addc_u32 s19, s19, 0
	s_add_i32 s20, s47, s24
	global_load_lds_dwordx4 v[192:193], off
	s_mov_b32 m0, s20
	v_lshl_add_u64 v[192:193], s[18:19], 0, v[166:167]
	global_load_lds_dwordx4 v[192:193], off
	s_add_i32 m0, s20, 0x2000
	v_lshl_add_u64 v[192:193], s[18:19], 0, v[170:171]
	global_load_lds_dwordx4 v[192:193], off
	s_mov_b32 m0, s33
	v_lshl_add_u64 v[192:193], v[218:219], 0, s[8:9]
	global_load_lds_dwordx4 v[192:193], off
	s_mov_b32 m0, s35
	v_lshl_add_u64 v[192:193], v[220:221], 0, s[8:9]
	global_load_lds_dwordx4 v[192:193], off
	s_waitcnt vmcnt(8) lgkmcnt(0)
	s_setprio 1
	s_barrier
	v_mfma_f32_16x16x32_bf16 v[60:63], v[128:131], v[160:163], v[60:63]
	v_mfma_f32_16x16x32_bf16 v[60:63], v[132:135], v[180:183], v[60:63]
	v_mfma_f32_16x16x32_bf16 v[56:59], v[136:139], v[160:163], v[56:59]
	v_mfma_f32_16x16x32_bf16 v[56:59], v[140:143], v[180:183], v[56:59]
	v_mfma_f32_16x16x32_bf16 v[48:51], v[128:131], v[184:187], v[48:51]
	v_mfma_f32_16x16x32_bf16 v[48:51], v[132:135], v[188:191], v[48:51]
	v_mfma_f32_16x16x32_bf16 v[40:43], v[136:139], v[184:187], v[40:43]
	v_mfma_f32_16x16x32_bf16 v[40:43], v[140:143], v[188:191], v[40:43]
	v_mfma_f32_16x16x32_bf16 v[32:35], v[128:131], v[200:203], v[32:35]
	v_mfma_f32_16x16x32_bf16 v[32:35], v[132:135], v[204:207], v[32:35]
	v_mfma_f32_16x16x32_bf16 v[24:27], v[136:139], v[200:203], v[24:27]
	v_mfma_f32_16x16x32_bf16 v[24:27], v[140:143], v[204:207], v[24:27]
	v_mfma_f32_16x16x32_bf16 v[16:19], v[128:131], v[208:211], v[16:19]
	v_mfma_f32_16x16x32_bf16 v[16:19], v[132:135], v[212:215], v[16:19]
	v_mfma_f32_16x16x32_bf16 v[8:11], v[136:139], v[208:211], v[8:11]
	v_mfma_f32_16x16x32_bf16 v[8:11], v[140:143], v[212:215], v[8:11]
	v_mfma_f32_16x16x32_bf16 v[52:55], v[144:147], v[160:163], v[52:55]
	v_mfma_f32_16x16x32_bf16 v[52:55], v[148:151], v[180:183], v[52:55]
	v_mfma_f32_16x16x32_bf16 v[44:47], v[152:155], v[160:163], v[44:47]
	v_mfma_f32_16x16x32_bf16 v[44:47], v[156:159], v[180:183], v[44:47]
	v_mfma_f32_16x16x32_bf16 v[36:39], v[144:147], v[184:187], v[36:39]
	v_mfma_f32_16x16x32_bf16 v[36:39], v[148:151], v[188:191], v[36:39]
	v_mfma_f32_16x16x32_bf16 v[28:31], v[152:155], v[184:187], v[28:31]
	v_mfma_f32_16x16x32_bf16 v[28:31], v[156:159], v[188:191], v[28:31]
	v_mfma_f32_16x16x32_bf16 v[20:23], v[144:147], v[200:203], v[20:23]
	v_mfma_f32_16x16x32_bf16 v[20:23], v[148:151], v[204:207], v[20:23]
	v_mfma_f32_16x16x32_bf16 v[12:15], v[152:155], v[200:203], v[12:15]
	v_mfma_f32_16x16x32_bf16 v[12:15], v[156:159], v[204:207], v[12:15]
	v_mfma_f32_16x16x32_bf16 v[4:7], v[144:147], v[208:211], v[4:7]
	v_mfma_f32_16x16x32_bf16 v[4:7], v[148:151], v[212:215], v[4:7]
	s_setprio 3
	s_barrier
	v_mfma_f32_16x16x32_bf16 v[0:3], v[152:155], v[208:211], v[0:3]
	v_mfma_f32_16x16x32_bf16 v[0:3], v[156:159], v[212:215], v[0:3]
	s_setprio 0
	s_add_i32 s45, s45, 2
	s_add_u32 s16, s16, 0x100
	s_addc_u32 s17, s17, 0
	s_add_u32 s43, s43, 0x100
	s_addc_u32 s44, s44, 0
	s_cmp_gt_u32 s45, 41
	s_cbranch_scc0 .LBB0_2341
	s_branch .Lzskip_11
.Lzv_11_0:
	s_barrier
	v_mfma_f32_16x16x32_bf16 v[124:127], v[128:131], v[160:163], 0
	v_mfma_f32_16x16x32_bf16 v[124:127], v[132:135], v[180:183], v[124:127]
	v_mfma_f32_16x16x32_bf16 v[120:123], v[136:139], v[160:163], 0
	v_mfma_f32_16x16x32_bf16 v[120:123], v[140:143], v[180:183], v[120:123]
	v_mfma_f32_16x16x32_bf16 v[108:111], v[128:131], v[184:187], 0
	v_mfma_f32_16x16x32_bf16 v[108:111], v[132:135], v[188:191], v[108:111]
	v_mfma_f32_16x16x32_bf16 v[104:107], v[136:139], v[184:187], 0
	v_mfma_f32_16x16x32_bf16 v[104:107], v[140:143], v[188:191], v[104:107]
	v_mfma_f32_16x16x32_bf16 v[96:99], v[128:131], v[200:203], 0
	v_mfma_f32_16x16x32_bf16 v[96:99], v[132:135], v[204:207], v[96:99]
	v_mfma_f32_16x16x32_bf16 v[88:91], v[136:139], v[200:203], 0
	v_mfma_f32_16x16x32_bf16 v[88:91], v[140:143], v[204:207], v[88:91]
	v_mfma_f32_16x16x32_bf16 v[80:83], v[128:131], v[208:211], 0
	v_mfma_f32_16x16x32_bf16 v[80:83], v[132:135], v[212:215], v[80:83]
	v_mfma_f32_16x16x32_bf16 v[72:75], v[136:139], v[208:211], 0
	v_mfma_f32_16x16x32_bf16 v[72:75], v[140:143], v[212:215], v[72:75]
	v_mfma_f32_16x16x32_bf16 v[116:119], v[144:147], v[160:163], 0
	v_mfma_f32_16x16x32_bf16 v[116:119], v[148:151], v[180:183], v[116:119]
	v_mfma_f32_16x16x32_bf16 v[112:115], v[152:155], v[160:163], 0
	v_mfma_f32_16x16x32_bf16 v[112:115], v[156:159], v[180:183], v[112:115]
	v_mfma_f32_16x16x32_bf16 v[100:103], v[144:147], v[184:187], 0
	v_mfma_f32_16x16x32_bf16 v[100:103], v[148:151], v[188:191], v[100:103]
	v_mfma_f32_16x16x32_bf16 v[92:95], v[152:155], v[184:187], 0
	v_mfma_f32_16x16x32_bf16 v[92:95], v[156:159], v[188:191], v[92:95]
	v_mfma_f32_16x16x32_bf16 v[84:87], v[144:147], v[200:203], 0
	v_mfma_f32_16x16x32_bf16 v[84:87], v[148:151], v[204:207], v[84:87]
	v_mfma_f32_16x16x32_bf16 v[76:79], v[152:155], v[200:203], 0
	v_mfma_f32_16x16x32_bf16 v[76:79], v[156:159], v[204:207], v[76:79]
	v_mfma_f32_16x16x32_bf16 v[68:71], v[144:147], v[208:211], 0
	v_mfma_f32_16x16x32_bf16 v[68:71], v[148:151], v[212:215], v[68:71]
	s_setprio 3
	s_barrier
	v_mfma_f32_16x16x32_bf16 v[64:67], v[152:155], v[208:211], 0
	v_mfma_f32_16x16x32_bf16 v[64:67], v[156:159], v[212:215], v[64:67]
	s_setprio 0
	s_branch .Lzj_11_0
.Lzv_11_1:
	s_barrier
	v_mfma_f32_16x16x32_bf16 v[60:63], v[128:131], v[160:163], 0
	v_mfma_f32_16x16x32_bf16 v[60:63], v[132:135], v[180:183], v[60:63]
	v_mfma_f32_16x16x32_bf16 v[56:59], v[136:139], v[160:163], 0
	v_mfma_f32_16x16x32_bf16 v[56:59], v[140:143], v[180:183], v[56:59]
	v_mfma_f32_16x16x32_bf16 v[48:51], v[128:131], v[184:187], 0
	v_mfma_f32_16x16x32_bf16 v[48:51], v[132:135], v[188:191], v[48:51]
	v_mfma_f32_16x16x32_bf16 v[40:43], v[136:139], v[184:187], 0
	v_mfma_f32_16x16x32_bf16 v[40:43], v[140:143], v[188:191], v[40:43]
	v_mfma_f32_16x16x32_bf16 v[32:35], v[128:131], v[200:203], 0
	v_mfma_f32_16x16x32_bf16 v[32:35], v[132:135], v[204:207], v[32:35]
	v_mfma_f32_16x16x32_bf16 v[24:27], v[136:139], v[200:203], 0
	v_mfma_f32_16x16x32_bf16 v[24:27], v[140:143], v[204:207], v[24:27]
	v_mfma_f32_16x16x32_bf16 v[16:19], v[128:131], v[208:211], 0
	v_mfma_f32_16x16x32_bf16 v[16:19], v[132:135], v[212:215], v[16:19]
	v_mfma_f32_16x16x32_bf16 v[8:11], v[136:139], v[208:211], 0
	v_mfma_f32_16x16x32_bf16 v[8:11], v[140:143], v[212:215], v[8:11]
	v_mfma_f32_16x16x32_bf16 v[52:55], v[144:147], v[160:163], 0
	v_mfma_f32_16x16x32_bf16 v[52:55], v[148:151], v[180:183], v[52:55]
	v_mfma_f32_16x16x32_bf16 v[44:47], v[152:155], v[160:163], 0
	v_mfma_f32_16x16x32_bf16 v[44:47], v[156:159], v[180:183], v[44:47]
	v_mfma_f32_16x16x32_bf16 v[36:39], v[144:147], v[184:187], 0
	v_mfma_f32_16x16x32_bf16 v[36:39], v[148:151], v[188:191], v[36:39]
	v_mfma_f32_16x16x32_bf16 v[28:31], v[152:155], v[184:187], 0
	v_mfma_f32_16x16x32_bf16 v[28:31], v[156:159], v[188:191], v[28:31]
	v_mfma_f32_16x16x32_bf16 v[20:23], v[144:147], v[200:203], 0
	v_mfma_f32_16x16x32_bf16 v[20:23], v[148:151], v[204:207], v[20:23]
	v_mfma_f32_16x16x32_bf16 v[12:15], v[152:155], v[200:203], 0
	v_mfma_f32_16x16x32_bf16 v[12:15], v[156:159], v[204:207], v[12:15]
	v_mfma_f32_16x16x32_bf16 v[4:7], v[144:147], v[208:211], 0
	v_mfma_f32_16x16x32_bf16 v[4:7], v[148:151], v[212:215], v[4:7]
	s_setprio 3
	s_barrier
	v_mfma_f32_16x16x32_bf16 v[0:3], v[152:155], v[208:211], 0
	v_mfma_f32_16x16x32_bf16 v[0:3], v[156:159], v[212:215], v[0:3]
	s_setprio 0
	s_branch .Lzj_11_1
